# residual epilogues: x_old load window grows as accumulator quads are stored (up to ~24 loads in flight instead of 11)
# baseline (speedup 1.0000x reference)
.LBB0_274:
	v_lshrrev_b32_e32 v132, 6, v206
	v_and_b32_e32 v143, 63, v206
	v_lshrrev_b32_e32 v142, 2, v132
	v_and_b32_e32 v132, 3, v132
	v_lshlrev_b32_e32 v142, 6, v142
	v_lshrrev_b32_e32 v146, 4, v143
	v_and_b32_e32 v211, 15, v143
	v_xor_b32_e32 v144, 16, v143
	v_xor_b32_e32 v145, 32, v143
	v_lshlrev_b32_e32 v144, 2, v144
	v_lshlrev_b32_e32 v145, 2, v145
	s_lshl_b32 vcc_lo, s24, 8
	v_add_u32_e32 v142, vcc_lo, v142
	s_lshl_b32 vcc_lo, s57, 2
	v_add_u32_e32 v204, vcc_lo, v132
	v_add_u32_e32 v147, v142, v211
	v_lshlrev_b32_e32 v147, 6, v147
	v_lshl_add_u32 v204, v204, 2, v147
	v_lshlrev_b32_e32 v143, 5, v132
	v_lshrrev_b32_e32 v147, 3, v211
	v_lshl_add_u32 v147, v147, 2, v146
	v_lshl_add_u32 v143, v147, 2, v143
	s_lshl_b32 vcc_lo, s57, 8
	v_add_u32_e32 v143, vcc_lo, v143
	v_and_b32_e32 v147, 7, v211
	v_add_u32_e32 v142, v142, v147
	v_lshlrev_b32_e32 v148, 12, v142
	v_lshl_add_u32 v148, v143, 2, v148
	v_add_u32_e32 v149, 0x8000, v148
	v_lshlrev_b32_e32 v158, 11, v142
	v_lshl_add_u32 v158, v143, 1, v158
	v_add_u32_e32 v159, 0x4000, v158
	s_mov_b32 s86, s90
	s_mov_b32 s87, s91
	s_mov_b32 s88, s94
	s_mov_b32 s89, s95
	s_add_u32 s92, s96, 0x9e00000
	s_addc_u32 s93, s97, 0
	s_add_u32 s100, s96, 0x4600000
	s_addc_u32 s101, s97, 0
	global_load_dwordx4 v[164:167], v148, s[86:87]
	global_load_dwordx4 v[168:171], v149, s[86:87]
	global_load_dwordx4 v[172:175], v148, s[86:87] offset:512
	global_load_dwordx4 v[176:179], v149, s[86:87] offset:512
	s_add_u32 s86, s86, 0x10000
	s_addc_u32 s87, s87, 0
	global_load_dwordx4 v[180:183], v148, s[86:87]
	global_load_dwordx4 v[184:187], v149, s[86:87]
	global_load_dwordx4 v[188:191], v148, s[86:87] offset:512
	global_load_dwordx4 v[192:195], v149, s[86:87] offset:512
	s_add_u32 s86, s86, 0x10000
	s_addc_u32 s87, s87, 0
	global_load_dwordx4 v[196:199], v148, s[86:87]
	global_load_dwordx4 v[200:203], v149, s[86:87]
	global_load_dwordx4 v[212:215], v148, s[86:87] offset:512
	v_mov_b32_e32 v160, v120
	v_mov_b32_e32 v161, v121
	v_mov_b32_e32 v162, v122
	v_mov_b32_e32 v163, v123
	v_mov_b32_dpp v120, v124 row_ror:8 row_mask:0xf bank_mask:0x3
	v_mov_b32_dpp v121, v125 row_ror:8 row_mask:0xf bank_mask:0x3
	v_mov_b32_dpp v122, v126 row_ror:8 row_mask:0xf bank_mask:0x3
	v_mov_b32_dpp v123, v127 row_ror:8 row_mask:0xf bank_mask:0x3
	v_mov_b32_dpp v124, v160 row_ror:8 row_mask:0xf bank_mask:0xc
	v_mov_b32_dpp v125, v161 row_ror:8 row_mask:0xf bank_mask:0xc
	v_mov_b32_dpp v126, v162 row_ror:8 row_mask:0xf bank_mask:0xc
	v_mov_b32_dpp v127, v163 row_ror:8 row_mask:0xf bank_mask:0xc
	s_waitcnt vmcnt(10)
	v_fma_f32 v124, v124, 0.5, v164
	v_fma_f32 v125, v125, 0.5, v165
	v_fma_f32 v126, v126, 0.5, v166
	v_fma_f32 v127, v127, 0.5, v167
	global_store_dwordx4 v148, v[124:127], s[88:89]
	v_cvt_pk_bf16_f32 v164, v124, v125
	v_cvt_pk_bf16_f32 v165, v126, v127
	global_store_dwordx2 v158, v[164:165], s[92:93]
	v_mul_f32_e32 v205, v124, v124
	v_fmac_f32_e32 v205, v125, v125
	v_fmac_f32_e32 v205, v126, v126
	v_fmac_f32_e32 v205, v127, v127
	global_load_dwordx4 v[164:167], v149, s[86:87] offset:512
	s_add_u32 s86, s86, 0x10000
	s_addc_u32 s87, s87, 0
	global_load_dwordx4 v[124:127], v148, s[86:87]
	s_waitcnt vmcnt(13)
	v_fma_f32 v120, v120, 0.5, v168
	v_fma_f32 v121, v121, 0.5, v169
	v_fma_f32 v122, v122, 0.5, v170
	v_fma_f32 v123, v123, 0.5, v171
	global_store_dwordx4 v149, v[120:123], s[88:89]
	v_cvt_pk_bf16_f32 v168, v120, v121
	v_cvt_pk_bf16_f32 v169, v122, v123
	global_store_dwordx2 v159, v[168:169], s[92:93]
	v_mul_f32_e32 v210, v120, v120
	v_fmac_f32_e32 v210, v121, v121
	v_fmac_f32_e32 v210, v122, v122
	v_fmac_f32_e32 v210, v123, v123
	global_load_dwordx4 v[168:171], v149, s[86:87]
	global_load_dwordx4 v[120:123], v148, s[86:87] offset:512
	v_mov_b32_e32 v160, v112
	v_mov_b32_e32 v161, v113
	v_mov_b32_e32 v162, v114
	v_mov_b32_e32 v163, v115
	v_mov_b32_dpp v112, v116 row_ror:8 row_mask:0xf bank_mask:0x3
	v_mov_b32_dpp v113, v117 row_ror:8 row_mask:0xf bank_mask:0x3
	v_mov_b32_dpp v114, v118 row_ror:8 row_mask:0xf bank_mask:0x3
	v_mov_b32_dpp v115, v119 row_ror:8 row_mask:0xf bank_mask:0x3
	v_mov_b32_dpp v116, v160 row_ror:8 row_mask:0xf bank_mask:0xc
	v_mov_b32_dpp v117, v161 row_ror:8 row_mask:0xf bank_mask:0xc
	v_mov_b32_dpp v118, v162 row_ror:8 row_mask:0xf bank_mask:0xc
	v_mov_b32_dpp v119, v163 row_ror:8 row_mask:0xf bank_mask:0xc
	s_waitcnt vmcnt(16)
	v_fma_f32 v116, v116, 0.5, v172
	v_fma_f32 v117, v117, 0.5, v173
	v_fma_f32 v118, v118, 0.5, v174
	v_fma_f32 v119, v119, 0.5, v175
	global_store_dwordx4 v148, v[116:119], s[88:89] offset:512
	v_cvt_pk_bf16_f32 v172, v116, v117
	v_cvt_pk_bf16_f32 v173, v118, v119
	global_store_dwordx2 v158, v[172:173], s[92:93] offset:256
	v_fmac_f32_e32 v205, v116, v116
	v_fmac_f32_e32 v205, v117, v117
	v_fmac_f32_e32 v205, v118, v118
	v_fmac_f32_e32 v205, v119, v119
	global_load_dwordx4 v[172:175], v149, s[86:87] offset:512
	s_add_u32 s86, s86, 0x50000
	s_addc_u32 s87, s87, 0
	global_load_dwordx4 v[116:119], v148, s[86:87]
	s_waitcnt vmcnt(19)
	v_fma_f32 v112, v112, 0.5, v176
	v_fma_f32 v113, v113, 0.5, v177
	v_fma_f32 v114, v114, 0.5, v178
	v_fma_f32 v115, v115, 0.5, v179
	global_store_dwordx4 v149, v[112:115], s[88:89] offset:512
	v_cvt_pk_bf16_f32 v176, v112, v113
	v_cvt_pk_bf16_f32 v177, v114, v115
	global_store_dwordx2 v159, v[176:177], s[92:93] offset:256
	v_fmac_f32_e32 v210, v112, v112
	v_fmac_f32_e32 v210, v113, v113
	v_fmac_f32_e32 v210, v114, v114
	v_fmac_f32_e32 v210, v115, v115
	global_load_dwordx4 v[176:179], v149, s[86:87]
	global_load_dwordx4 v[112:115], v148, s[86:87] offset:512
	s_nop 1
	v_add_f32_dpp v205, v205, v205 row_ror:8 row_mask:0xf bank_mask:0xf
	v_add_f32_dpp v210, v210, v210 row_ror:8 row_mask:0xf bank_mask:0xf
	s_nop 0
	ds_bpermute_b32 v147, v144, v205
	ds_bpermute_b32 v132, v144, v210
	s_waitcnt lgkmcnt(0)
	v_add_f32_e32 v205, v205, v147
	v_add_f32_e32 v210, v210, v132
	s_nop 0
	ds_bpermute_b32 v147, v145, v205
	ds_bpermute_b32 v132, v145, v210
	s_waitcnt lgkmcnt(0)
	v_add_f32_e32 v205, v205, v147
	v_add_f32_e32 v210, v210, v132
	v_cmp_gt_u32_e32 vcc, 8, v211
	s_nop 1
	v_cndmask_b32_e32 v205, v210, v205, vcc
	v_cmp_eq_u32_e32 vcc, 0, v146
	s_and_saveexec_b64 s[98:99], vcc
	global_store_dword v204, v205, s[100:101]
	s_mov_b64 exec, s[98:99]
	s_add_u32 s88, s88, 0x10000
	s_addc_u32 s89, s89, 0
	s_add_u32 s92, s92, 0x8000
	s_addc_u32 s93, s93, 0
	s_add_u32 s100, s100, 0x400
	s_addc_u32 s101, s101, 0
	v_mov_b32_e32 v160, v104
	v_mov_b32_e32 v161, v105
	v_mov_b32_e32 v162, v106
	v_mov_b32_e32 v163, v107
	v_mov_b32_dpp v104, v108 row_ror:8 row_mask:0xf bank_mask:0x3
	v_mov_b32_dpp v105, v109 row_ror:8 row_mask:0xf bank_mask:0x3
	v_mov_b32_dpp v106, v110 row_ror:8 row_mask:0xf bank_mask:0x3
	v_mov_b32_dpp v107, v111 row_ror:8 row_mask:0xf bank_mask:0x3
	v_mov_b32_dpp v108, v160 row_ror:8 row_mask:0xf bank_mask:0xc
	v_mov_b32_dpp v109, v161 row_ror:8 row_mask:0xf bank_mask:0xc
	v_mov_b32_dpp v110, v162 row_ror:8 row_mask:0xf bank_mask:0xc
	v_mov_b32_dpp v111, v163 row_ror:8 row_mask:0xf bank_mask:0xc
	s_waitcnt vmcnt(23)
	v_fma_f32 v108, v108, 0.5, v180
	v_fma_f32 v109, v109, 0.5, v181
	v_fma_f32 v110, v110, 0.5, v182
	v_fma_f32 v111, v111, 0.5, v183
	global_store_dwordx4 v148, v[108:111], s[88:89]
	v_cvt_pk_bf16_f32 v180, v108, v109
	v_cvt_pk_bf16_f32 v181, v110, v111
	global_store_dwordx2 v158, v[180:181], s[92:93]
	v_mul_f32_e32 v205, v108, v108
	v_fmac_f32_e32 v205, v109, v109
	v_fmac_f32_e32 v205, v110, v110
	v_fmac_f32_e32 v205, v111, v111
	global_load_dwordx4 v[180:183], v149, s[86:87] offset:512
	s_add_u32 s86, s86, 0x10000
	s_addc_u32 s87, s87, 0
	global_load_dwordx4 v[108:111], v148, s[86:87]
	s_waitcnt vmcnt(26)
	v_fma_f32 v104, v104, 0.5, v184
	v_fma_f32 v105, v105, 0.5, v185
	v_fma_f32 v106, v106, 0.5, v186
	v_fma_f32 v107, v107, 0.5, v187
	global_store_dwordx4 v149, v[104:107], s[88:89]
	v_cvt_pk_bf16_f32 v184, v104, v105
	v_cvt_pk_bf16_f32 v185, v106, v107
	global_store_dwordx2 v159, v[184:185], s[92:93]
	v_mul_f32_e32 v210, v104, v104
	v_fmac_f32_e32 v210, v105, v105
	v_fmac_f32_e32 v210, v106, v106
	v_fmac_f32_e32 v210, v107, v107
	global_load_dwordx4 v[184:187], v149, s[86:87]
	global_load_dwordx4 v[104:107], v148, s[86:87] offset:512
	v_mov_b32_e32 v160, v96
	v_mov_b32_e32 v161, v97
	v_mov_b32_e32 v162, v98
	v_mov_b32_e32 v163, v99
	v_mov_b32_dpp v96, v100 row_ror:8 row_mask:0xf bank_mask:0x3
	v_mov_b32_dpp v97, v101 row_ror:8 row_mask:0xf bank_mask:0x3
	v_mov_b32_dpp v98, v102 row_ror:8 row_mask:0xf bank_mask:0x3
	v_mov_b32_dpp v99, v103 row_ror:8 row_mask:0xf bank_mask:0x3
	v_mov_b32_dpp v100, v160 row_ror:8 row_mask:0xf bank_mask:0xc
	v_mov_b32_dpp v101, v161 row_ror:8 row_mask:0xf bank_mask:0xc
	v_mov_b32_dpp v102, v162 row_ror:8 row_mask:0xf bank_mask:0xc
	v_mov_b32_dpp v103, v163 row_ror:8 row_mask:0xf bank_mask:0xc
	s_waitcnt vmcnt(29)
	v_fma_f32 v100, v100, 0.5, v188
	v_fma_f32 v101, v101, 0.5, v189
	v_fma_f32 v102, v102, 0.5, v190
	v_fma_f32 v103, v103, 0.5, v191
	global_store_dwordx4 v148, v[100:103], s[88:89] offset:512
	v_cvt_pk_bf16_f32 v188, v100, v101
	v_cvt_pk_bf16_f32 v189, v102, v103
	global_store_dwordx2 v158, v[188:189], s[92:93] offset:256
	v_fmac_f32_e32 v205, v100, v100
	v_fmac_f32_e32 v205, v101, v101
	v_fmac_f32_e32 v205, v102, v102
	v_fmac_f32_e32 v205, v103, v103
	global_load_dwordx4 v[188:191], v149, s[86:87] offset:512
	s_add_u32 s86, s86, 0x10000
	s_addc_u32 s87, s87, 0
	global_load_dwordx4 v[100:103], v148, s[86:87]
	s_waitcnt vmcnt(32)
	v_fma_f32 v96, v96, 0.5, v192
	v_fma_f32 v97, v97, 0.5, v193
	v_fma_f32 v98, v98, 0.5, v194
	v_fma_f32 v99, v99, 0.5, v195
	global_store_dwordx4 v149, v[96:99], s[88:89] offset:512
	v_cvt_pk_bf16_f32 v192, v96, v97
	v_cvt_pk_bf16_f32 v193, v98, v99
	global_store_dwordx2 v159, v[192:193], s[92:93] offset:256
	v_fmac_f32_e32 v210, v96, v96
	v_fmac_f32_e32 v210, v97, v97
	v_fmac_f32_e32 v210, v98, v98
	v_fmac_f32_e32 v210, v99, v99
	global_load_dwordx4 v[192:195], v149, s[86:87]
	global_load_dwordx4 v[96:99], v148, s[86:87] offset:512
	s_nop 1
	v_add_f32_dpp v205, v205, v205 row_ror:8 row_mask:0xf bank_mask:0xf
	v_add_f32_dpp v210, v210, v210 row_ror:8 row_mask:0xf bank_mask:0xf
	s_nop 0
	ds_bpermute_b32 v147, v144, v205
	ds_bpermute_b32 v132, v144, v210
	s_waitcnt lgkmcnt(0)
	v_add_f32_e32 v205, v205, v147
	v_add_f32_e32 v210, v210, v132
	s_nop 0
	ds_bpermute_b32 v147, v145, v205
	ds_bpermute_b32 v132, v145, v210
	s_waitcnt lgkmcnt(0)
	v_add_f32_e32 v205, v205, v147
	v_add_f32_e32 v210, v210, v132
	v_cmp_gt_u32_e32 vcc, 8, v211
	s_nop 1
	v_cndmask_b32_e32 v205, v210, v205, vcc
	v_cmp_eq_u32_e32 vcc, 0, v146
	s_and_saveexec_b64 s[98:99], vcc
	global_store_dword v204, v205, s[100:101]
	s_mov_b64 exec, s[98:99]
	s_add_u32 s88, s88, 0x10000
	s_addc_u32 s89, s89, 0
	s_add_u32 s92, s92, 0x8000
	s_addc_u32 s93, s93, 0
	s_add_u32 s100, s100, 0x400
	s_addc_u32 s101, s101, 0
	v_mov_b32_e32 v160, v88
	v_mov_b32_e32 v161, v89
	v_mov_b32_e32 v162, v90
	v_mov_b32_e32 v163, v91
	v_mov_b32_dpp v88, v92 row_ror:8 row_mask:0xf bank_mask:0x3
	v_mov_b32_dpp v89, v93 row_ror:8 row_mask:0xf bank_mask:0x3
	v_mov_b32_dpp v90, v94 row_ror:8 row_mask:0xf bank_mask:0x3
	v_mov_b32_dpp v91, v95 row_ror:8 row_mask:0xf bank_mask:0x3
	v_mov_b32_dpp v92, v160 row_ror:8 row_mask:0xf bank_mask:0xc
	v_mov_b32_dpp v93, v161 row_ror:8 row_mask:0xf bank_mask:0xc
	v_mov_b32_dpp v94, v162 row_ror:8 row_mask:0xf bank_mask:0xc
	v_mov_b32_dpp v95, v163 row_ror:8 row_mask:0xf bank_mask:0xc
	s_waitcnt vmcnt(36)
	v_fma_f32 v92, v92, 0.5, v196
	v_fma_f32 v93, v93, 0.5, v197
	v_fma_f32 v94, v94, 0.5, v198
	v_fma_f32 v95, v95, 0.5, v199
	global_store_dwordx4 v148, v[92:95], s[88:89]
	v_cvt_pk_bf16_f32 v196, v92, v93
	v_cvt_pk_bf16_f32 v197, v94, v95
	global_store_dwordx2 v158, v[196:197], s[92:93]
	v_mul_f32_e32 v205, v92, v92
	v_fmac_f32_e32 v205, v93, v93
	v_fmac_f32_e32 v205, v94, v94
	v_fmac_f32_e32 v205, v95, v95
	global_load_dwordx4 v[196:199], v149, s[86:87] offset:512
	s_add_u32 s86, s86, 0x10000
	s_addc_u32 s87, s87, 0
	global_load_dwordx4 v[92:95], v148, s[86:87]
	s_waitcnt vmcnt(39)
	v_fma_f32 v88, v88, 0.5, v200
	v_fma_f32 v89, v89, 0.5, v201
	v_fma_f32 v90, v90, 0.5, v202
	v_fma_f32 v91, v91, 0.5, v203
	global_store_dwordx4 v149, v[88:91], s[88:89]
	v_cvt_pk_bf16_f32 v200, v88, v89
	v_cvt_pk_bf16_f32 v201, v90, v91
	global_store_dwordx2 v159, v[200:201], s[92:93]
	v_mul_f32_e32 v210, v88, v88
	v_fmac_f32_e32 v210, v89, v89
	v_fmac_f32_e32 v210, v90, v90
	v_fmac_f32_e32 v210, v91, v91
	global_load_dwordx4 v[200:203], v149, s[86:87]
	global_load_dwordx4 v[88:91], v148, s[86:87] offset:512
	v_mov_b32_e32 v160, v80
	v_mov_b32_e32 v161, v81
	v_mov_b32_e32 v162, v82
	v_mov_b32_e32 v163, v83
	v_mov_b32_dpp v80, v84 row_ror:8 row_mask:0xf bank_mask:0x3
	v_mov_b32_dpp v81, v85 row_ror:8 row_mask:0xf bank_mask:0x3
	v_mov_b32_dpp v82, v86 row_ror:8 row_mask:0xf bank_mask:0x3
	v_mov_b32_dpp v83, v87 row_ror:8 row_mask:0xf bank_mask:0x3
	v_mov_b32_dpp v84, v160 row_ror:8 row_mask:0xf bank_mask:0xc
	v_mov_b32_dpp v85, v161 row_ror:8 row_mask:0xf bank_mask:0xc
	v_mov_b32_dpp v86, v162 row_ror:8 row_mask:0xf bank_mask:0xc
	v_mov_b32_dpp v87, v163 row_ror:8 row_mask:0xf bank_mask:0xc
	s_waitcnt vmcnt(42)
	v_fma_f32 v84, v84, 0.5, v212
	v_fma_f32 v85, v85, 0.5, v213
	v_fma_f32 v86, v86, 0.5, v214
	v_fma_f32 v87, v87, 0.5, v215
	global_store_dwordx4 v148, v[84:87], s[88:89] offset:512
	v_cvt_pk_bf16_f32 v212, v84, v85
	v_cvt_pk_bf16_f32 v213, v86, v87
	global_store_dwordx2 v158, v[212:213], s[92:93] offset:256
	v_fmac_f32_e32 v205, v84, v84
	v_fmac_f32_e32 v205, v85, v85
	v_fmac_f32_e32 v205, v86, v86
	v_fmac_f32_e32 v205, v87, v87
	global_load_dwordx4 v[212:215], v149, s[86:87] offset:512
	s_waitcnt vmcnt(42)
	v_fma_f32 v80, v80, 0.5, v164
	v_fma_f32 v81, v81, 0.5, v165
	v_fma_f32 v82, v82, 0.5, v166
	v_fma_f32 v83, v83, 0.5, v167
	global_store_dwordx4 v149, v[80:83], s[88:89] offset:512
	v_cvt_pk_bf16_f32 v164, v80, v81
	v_cvt_pk_bf16_f32 v165, v82, v83
	global_store_dwordx2 v159, v[164:165], s[92:93] offset:256
	v_fmac_f32_e32 v210, v80, v80
	v_fmac_f32_e32 v210, v81, v81
	v_fmac_f32_e32 v210, v82, v82
	v_fmac_f32_e32 v210, v83, v83
	s_nop 1
	v_add_f32_dpp v205, v205, v205 row_ror:8 row_mask:0xf bank_mask:0xf
	v_add_f32_dpp v210, v210, v210 row_ror:8 row_mask:0xf bank_mask:0xf
	s_nop 0
	ds_bpermute_b32 v147, v144, v205
	ds_bpermute_b32 v132, v144, v210
	s_waitcnt lgkmcnt(0)
	v_add_f32_e32 v205, v205, v147
	v_add_f32_e32 v210, v210, v132
	s_nop 0
	ds_bpermute_b32 v147, v145, v205
	ds_bpermute_b32 v132, v145, v210
	s_waitcnt lgkmcnt(0)
	v_add_f32_e32 v205, v205, v147
	v_add_f32_e32 v210, v210, v132
	v_cmp_gt_u32_e32 vcc, 8, v211
	s_nop 1
	v_cndmask_b32_e32 v205, v210, v205, vcc
	v_cmp_eq_u32_e32 vcc, 0, v146
	s_and_saveexec_b64 s[98:99], vcc
	global_store_dword v204, v205, s[100:101]
	s_mov_b64 exec, s[98:99]
	s_add_u32 s88, s88, 0x10000
	s_addc_u32 s89, s89, 0
	s_add_u32 s92, s92, 0x8000
	s_addc_u32 s93, s93, 0
	s_add_u32 s100, s100, 0x400
	s_addc_u32 s101, s101, 0
	v_mov_b32_e32 v160, v72
	v_mov_b32_e32 v161, v73
	v_mov_b32_e32 v162, v74
	v_mov_b32_e32 v163, v75
	v_mov_b32_dpp v72, v76 row_ror:8 row_mask:0xf bank_mask:0x3
	v_mov_b32_dpp v73, v77 row_ror:8 row_mask:0xf bank_mask:0x3
	v_mov_b32_dpp v74, v78 row_ror:8 row_mask:0xf bank_mask:0x3
	v_mov_b32_dpp v75, v79 row_ror:8 row_mask:0xf bank_mask:0x3
	v_mov_b32_dpp v76, v160 row_ror:8 row_mask:0xf bank_mask:0xc
	v_mov_b32_dpp v77, v161 row_ror:8 row_mask:0xf bank_mask:0xc
	v_mov_b32_dpp v78, v162 row_ror:8 row_mask:0xf bank_mask:0xc
	v_mov_b32_dpp v79, v163 row_ror:8 row_mask:0xf bank_mask:0xc
	s_waitcnt vmcnt(44)
	v_fma_f32 v76, v76, 0.5, v124
	v_fma_f32 v77, v77, 0.5, v125
	v_fma_f32 v78, v78, 0.5, v126
	v_fma_f32 v79, v79, 0.5, v127
	global_store_dwordx4 v148, v[76:79], s[88:89]
	v_cvt_pk_bf16_f32 v124, v76, v77
	v_cvt_pk_bf16_f32 v125, v78, v79
	global_store_dwordx2 v158, v[124:125], s[92:93]
	v_mul_f32_e32 v205, v76, v76
	v_fmac_f32_e32 v205, v77, v77
	v_fmac_f32_e32 v205, v78, v78
	v_fmac_f32_e32 v205, v79, v79
	s_waitcnt vmcnt(43)
	v_fma_f32 v72, v72, 0.5, v168
	v_fma_f32 v73, v73, 0.5, v169
	v_fma_f32 v74, v74, 0.5, v170
	v_fma_f32 v75, v75, 0.5, v171
	global_store_dwordx4 v149, v[72:75], s[88:89]
	v_cvt_pk_bf16_f32 v168, v72, v73
	v_cvt_pk_bf16_f32 v169, v74, v75
	global_store_dwordx2 v159, v[168:169], s[92:93]
	v_mul_f32_e32 v210, v72, v72
	v_fmac_f32_e32 v210, v73, v73
	v_fmac_f32_e32 v210, v74, v74
	v_fmac_f32_e32 v210, v75, v75
	v_mov_b32_e32 v160, v64
	v_mov_b32_e32 v161, v65
	v_mov_b32_e32 v162, v66
	v_mov_b32_e32 v163, v67
	v_mov_b32_dpp v64, v68 row_ror:8 row_mask:0xf bank_mask:0x3
	v_mov_b32_dpp v65, v69 row_ror:8 row_mask:0xf bank_mask:0x3
	v_mov_b32_dpp v66, v70 row_ror:8 row_mask:0xf bank_mask:0x3
	v_mov_b32_dpp v67, v71 row_ror:8 row_mask:0xf bank_mask:0x3
	v_mov_b32_dpp v68, v160 row_ror:8 row_mask:0xf bank_mask:0xc
	v_mov_b32_dpp v69, v161 row_ror:8 row_mask:0xf bank_mask:0xc
	v_mov_b32_dpp v70, v162 row_ror:8 row_mask:0xf bank_mask:0xc
	v_mov_b32_dpp v71, v163 row_ror:8 row_mask:0xf bank_mask:0xc
	s_waitcnt vmcnt(44)
	v_fma_f32 v68, v68, 0.5, v120
	v_fma_f32 v69, v69, 0.5, v121
	v_fma_f32 v70, v70, 0.5, v122
	v_fma_f32 v71, v71, 0.5, v123
	global_store_dwordx4 v148, v[68:71], s[88:89] offset:512
	v_cvt_pk_bf16_f32 v120, v68, v69
	v_cvt_pk_bf16_f32 v121, v70, v71
	global_store_dwordx2 v158, v[120:121], s[92:93] offset:256
	v_fmac_f32_e32 v205, v68, v68
	v_fmac_f32_e32 v205, v69, v69
	v_fmac_f32_e32 v205, v70, v70
	v_fmac_f32_e32 v205, v71, v71
	s_waitcnt vmcnt(43)
	v_fma_f32 v64, v64, 0.5, v172
	v_fma_f32 v65, v65, 0.5, v173
	v_fma_f32 v66, v66, 0.5, v174
	v_fma_f32 v67, v67, 0.5, v175
	global_store_dwordx4 v149, v[64:67], s[88:89] offset:512
	v_cvt_pk_bf16_f32 v172, v64, v65
	v_cvt_pk_bf16_f32 v173, v66, v67
	global_store_dwordx2 v159, v[172:173], s[92:93] offset:256
	v_fmac_f32_e32 v210, v64, v64
	v_fmac_f32_e32 v210, v65, v65
	v_fmac_f32_e32 v210, v66, v66
	v_fmac_f32_e32 v210, v67, v67
	s_nop 1
	v_add_f32_dpp v205, v205, v205 row_ror:8 row_mask:0xf bank_mask:0xf
	v_add_f32_dpp v210, v210, v210 row_ror:8 row_mask:0xf bank_mask:0xf
	s_nop 0
	ds_bpermute_b32 v147, v144, v205
	ds_bpermute_b32 v132, v144, v210
	s_waitcnt lgkmcnt(0)
	v_add_f32_e32 v205, v205, v147
	v_add_f32_e32 v210, v210, v132
	s_nop 0
	ds_bpermute_b32 v147, v145, v205
	ds_bpermute_b32 v132, v145, v210
	s_waitcnt lgkmcnt(0)
	v_add_f32_e32 v205, v205, v147
	v_add_f32_e32 v210, v210, v132
	v_cmp_gt_u32_e32 vcc, 8, v211
	s_nop 1
	v_cndmask_b32_e32 v205, v210, v205, vcc
	v_cmp_eq_u32_e32 vcc, 0, v146
	s_and_saveexec_b64 s[98:99], vcc
	global_store_dword v204, v205, s[100:101]
	s_mov_b64 exec, s[98:99]
	s_add_u32 s88, s88, 0x50000
	s_addc_u32 s89, s89, 0
	s_add_u32 s92, s92, 0x28000
	s_addc_u32 s93, s93, 0
	s_add_u32 s100, s100, 0x1400
	s_addc_u32 s101, s101, 0
	v_mov_b32_e32 v160, v56
	v_mov_b32_e32 v161, v57
	v_mov_b32_e32 v162, v58
	v_mov_b32_e32 v163, v59
	v_mov_b32_dpp v56, v60 row_ror:8 row_mask:0xf bank_mask:0x3
	v_mov_b32_dpp v57, v61 row_ror:8 row_mask:0xf bank_mask:0x3
	v_mov_b32_dpp v58, v62 row_ror:8 row_mask:0xf bank_mask:0x3
	v_mov_b32_dpp v59, v63 row_ror:8 row_mask:0xf bank_mask:0x3
	v_mov_b32_dpp v60, v160 row_ror:8 row_mask:0xf bank_mask:0xc
	v_mov_b32_dpp v61, v161 row_ror:8 row_mask:0xf bank_mask:0xc
	v_mov_b32_dpp v62, v162 row_ror:8 row_mask:0xf bank_mask:0xc
	v_mov_b32_dpp v63, v163 row_ror:8 row_mask:0xf bank_mask:0xc
	s_waitcnt vmcnt(45)
	v_fma_f32 v60, v60, 0.5, v116
	v_fma_f32 v61, v61, 0.5, v117
	v_fma_f32 v62, v62, 0.5, v118
	v_fma_f32 v63, v63, 0.5, v119
	global_store_dwordx4 v148, v[60:63], s[88:89]
	v_cvt_pk_bf16_f32 v116, v60, v61
	v_cvt_pk_bf16_f32 v117, v62, v63
	global_store_dwordx2 v158, v[116:117], s[92:93]
	v_mul_f32_e32 v205, v60, v60
	v_fmac_f32_e32 v205, v61, v61
	v_fmac_f32_e32 v205, v62, v62
	v_fmac_f32_e32 v205, v63, v63
	s_waitcnt vmcnt(44)
	v_fma_f32 v56, v56, 0.5, v176
	v_fma_f32 v57, v57, 0.5, v177
	v_fma_f32 v58, v58, 0.5, v178
	v_fma_f32 v59, v59, 0.5, v179
	global_store_dwordx4 v149, v[56:59], s[88:89]
	v_cvt_pk_bf16_f32 v176, v56, v57
	v_cvt_pk_bf16_f32 v177, v58, v59
	global_store_dwordx2 v159, v[176:177], s[92:93]
	v_mul_f32_e32 v210, v56, v56
	v_fmac_f32_e32 v210, v57, v57
	v_fmac_f32_e32 v210, v58, v58
	v_fmac_f32_e32 v210, v59, v59
	v_mov_b32_e32 v160, v48
	v_mov_b32_e32 v161, v49
	v_mov_b32_e32 v162, v50
	v_mov_b32_e32 v163, v51
	v_mov_b32_dpp v48, v52 row_ror:8 row_mask:0xf bank_mask:0x3
	v_mov_b32_dpp v49, v53 row_ror:8 row_mask:0xf bank_mask:0x3
	v_mov_b32_dpp v50, v54 row_ror:8 row_mask:0xf bank_mask:0x3
	v_mov_b32_dpp v51, v55 row_ror:8 row_mask:0xf bank_mask:0x3
	v_mov_b32_dpp v52, v160 row_ror:8 row_mask:0xf bank_mask:0xc
	v_mov_b32_dpp v53, v161 row_ror:8 row_mask:0xf bank_mask:0xc
	v_mov_b32_dpp v54, v162 row_ror:8 row_mask:0xf bank_mask:0xc
	v_mov_b32_dpp v55, v163 row_ror:8 row_mask:0xf bank_mask:0xc
	s_waitcnt vmcnt(45)
	v_fma_f32 v52, v52, 0.5, v112
	v_fma_f32 v53, v53, 0.5, v113
	v_fma_f32 v54, v54, 0.5, v114
	v_fma_f32 v55, v55, 0.5, v115
	global_store_dwordx4 v148, v[52:55], s[88:89] offset:512
	v_cvt_pk_bf16_f32 v112, v52, v53
	v_cvt_pk_bf16_f32 v113, v54, v55
	global_store_dwordx2 v158, v[112:113], s[92:93] offset:256
	v_fmac_f32_e32 v205, v52, v52
	v_fmac_f32_e32 v205, v53, v53
	v_fmac_f32_e32 v205, v54, v54
	v_fmac_f32_e32 v205, v55, v55
	s_waitcnt vmcnt(43)
	v_fma_f32 v48, v48, 0.5, v180
	v_fma_f32 v49, v49, 0.5, v181
	v_fma_f32 v50, v50, 0.5, v182
	v_fma_f32 v51, v51, 0.5, v183
	global_store_dwordx4 v149, v[48:51], s[88:89] offset:512
	v_cvt_pk_bf16_f32 v180, v48, v49
	v_cvt_pk_bf16_f32 v181, v50, v51
	global_store_dwordx2 v159, v[180:181], s[92:93] offset:256
	v_fmac_f32_e32 v210, v48, v48
	v_fmac_f32_e32 v210, v49, v49
	v_fmac_f32_e32 v210, v50, v50
	v_fmac_f32_e32 v210, v51, v51
	s_nop 1
	v_add_f32_dpp v205, v205, v205 row_ror:8 row_mask:0xf bank_mask:0xf
	v_add_f32_dpp v210, v210, v210 row_ror:8 row_mask:0xf bank_mask:0xf
	s_nop 0
	ds_bpermute_b32 v147, v144, v205
	ds_bpermute_b32 v132, v144, v210
	s_waitcnt lgkmcnt(0)
	v_add_f32_e32 v205, v205, v147
	v_add_f32_e32 v210, v210, v132
	s_nop 0
	ds_bpermute_b32 v147, v145, v205
	ds_bpermute_b32 v132, v145, v210
	s_waitcnt lgkmcnt(0)
	v_add_f32_e32 v205, v205, v147
	v_add_f32_e32 v210, v210, v132
	v_cmp_gt_u32_e32 vcc, 8, v211
	s_nop 1
	v_cndmask_b32_e32 v205, v210, v205, vcc
	v_cmp_eq_u32_e32 vcc, 0, v146
	s_and_saveexec_b64 s[98:99], vcc
	global_store_dword v204, v205, s[100:101]
	s_mov_b64 exec, s[98:99]
	s_add_u32 s88, s88, 0x10000
	s_addc_u32 s89, s89, 0
	s_add_u32 s92, s92, 0x8000
	s_addc_u32 s93, s93, 0
	s_add_u32 s100, s100, 0x400
	s_addc_u32 s101, s101, 0
	v_mov_b32_e32 v160, v40
	v_mov_b32_e32 v161, v41
	v_mov_b32_e32 v162, v42
	v_mov_b32_e32 v163, v43
	v_mov_b32_dpp v40, v44 row_ror:8 row_mask:0xf bank_mask:0x3
	v_mov_b32_dpp v41, v45 row_ror:8 row_mask:0xf bank_mask:0x3
	v_mov_b32_dpp v42, v46 row_ror:8 row_mask:0xf bank_mask:0x3
	v_mov_b32_dpp v43, v47 row_ror:8 row_mask:0xf bank_mask:0x3
	v_mov_b32_dpp v44, v160 row_ror:8 row_mask:0xf bank_mask:0xc
	v_mov_b32_dpp v45, v161 row_ror:8 row_mask:0xf bank_mask:0xc
	v_mov_b32_dpp v46, v162 row_ror:8 row_mask:0xf bank_mask:0xc
	v_mov_b32_dpp v47, v163 row_ror:8 row_mask:0xf bank_mask:0xc
	s_waitcnt vmcnt(45)
	v_fma_f32 v44, v44, 0.5, v108
	v_fma_f32 v45, v45, 0.5, v109
	v_fma_f32 v46, v46, 0.5, v110
	v_fma_f32 v47, v47, 0.5, v111
	global_store_dwordx4 v148, v[44:47], s[88:89]
	v_cvt_pk_bf16_f32 v108, v44, v45
	v_cvt_pk_bf16_f32 v109, v46, v47
	global_store_dwordx2 v158, v[108:109], s[92:93]
	v_mul_f32_e32 v205, v44, v44
	v_fmac_f32_e32 v205, v45, v45
	v_fmac_f32_e32 v205, v46, v46
	v_fmac_f32_e32 v205, v47, v47
	s_waitcnt vmcnt(44)
	v_fma_f32 v40, v40, 0.5, v184
	v_fma_f32 v41, v41, 0.5, v185
	v_fma_f32 v42, v42, 0.5, v186
	v_fma_f32 v43, v43, 0.5, v187
	global_store_dwordx4 v149, v[40:43], s[88:89]
	v_cvt_pk_bf16_f32 v184, v40, v41
	v_cvt_pk_bf16_f32 v185, v42, v43
	global_store_dwordx2 v159, v[184:185], s[92:93]
	v_mul_f32_e32 v210, v40, v40
	v_fmac_f32_e32 v210, v41, v41
	v_fmac_f32_e32 v210, v42, v42
	v_fmac_f32_e32 v210, v43, v43
	v_mov_b32_e32 v160, v32
	v_mov_b32_e32 v161, v33
	v_mov_b32_e32 v162, v34
	v_mov_b32_e32 v163, v35
	v_mov_b32_dpp v32, v36 row_ror:8 row_mask:0xf bank_mask:0x3
	v_mov_b32_dpp v33, v37 row_ror:8 row_mask:0xf bank_mask:0x3
	v_mov_b32_dpp v34, v38 row_ror:8 row_mask:0xf bank_mask:0x3
	v_mov_b32_dpp v35, v39 row_ror:8 row_mask:0xf bank_mask:0x3
	v_mov_b32_dpp v36, v160 row_ror:8 row_mask:0xf bank_mask:0xc
	v_mov_b32_dpp v37, v161 row_ror:8 row_mask:0xf bank_mask:0xc
	v_mov_b32_dpp v38, v162 row_ror:8 row_mask:0xf bank_mask:0xc
	v_mov_b32_dpp v39, v163 row_ror:8 row_mask:0xf bank_mask:0xc
	s_waitcnt vmcnt(45)
	v_fma_f32 v36, v36, 0.5, v104
	v_fma_f32 v37, v37, 0.5, v105
	v_fma_f32 v38, v38, 0.5, v106
	v_fma_f32 v39, v39, 0.5, v107
	global_store_dwordx4 v148, v[36:39], s[88:89] offset:512
	v_cvt_pk_bf16_f32 v104, v36, v37
	v_cvt_pk_bf16_f32 v105, v38, v39
	global_store_dwordx2 v158, v[104:105], s[92:93] offset:256
	v_fmac_f32_e32 v205, v36, v36
	v_fmac_f32_e32 v205, v37, v37
	v_fmac_f32_e32 v205, v38, v38
	v_fmac_f32_e32 v205, v39, v39
	s_waitcnt vmcnt(44)
	v_fma_f32 v32, v32, 0.5, v188
	v_fma_f32 v33, v33, 0.5, v189
	v_fma_f32 v34, v34, 0.5, v190
	v_fma_f32 v35, v35, 0.5, v191
	global_store_dwordx4 v149, v[32:35], s[88:89] offset:512
	v_cvt_pk_bf16_f32 v188, v32, v33
	v_cvt_pk_bf16_f32 v189, v34, v35
	global_store_dwordx2 v159, v[188:189], s[92:93] offset:256
	v_fmac_f32_e32 v210, v32, v32
	v_fmac_f32_e32 v210, v33, v33
	v_fmac_f32_e32 v210, v34, v34
	v_fmac_f32_e32 v210, v35, v35
	s_nop 1
	v_add_f32_dpp v205, v205, v205 row_ror:8 row_mask:0xf bank_mask:0xf
	v_add_f32_dpp v210, v210, v210 row_ror:8 row_mask:0xf bank_mask:0xf
	s_nop 0
	ds_bpermute_b32 v147, v144, v205
	ds_bpermute_b32 v132, v144, v210
	s_waitcnt lgkmcnt(0)
	v_add_f32_e32 v205, v205, v147
	v_add_f32_e32 v210, v210, v132
	s_nop 0
	ds_bpermute_b32 v147, v145, v205
	ds_bpermute_b32 v132, v145, v210
	s_waitcnt lgkmcnt(0)
	v_add_f32_e32 v205, v205, v147
	v_add_f32_e32 v210, v210, v132
	v_cmp_gt_u32_e32 vcc, 8, v211
	s_nop 1
	v_cndmask_b32_e32 v205, v210, v205, vcc
	v_cmp_eq_u32_e32 vcc, 0, v146
	s_and_saveexec_b64 s[98:99], vcc
	global_store_dword v204, v205, s[100:101]
	s_mov_b64 exec, s[98:99]
	s_add_u32 s88, s88, 0x10000
	s_addc_u32 s89, s89, 0
	s_add_u32 s92, s92, 0x8000
	s_addc_u32 s93, s93, 0
	s_add_u32 s100, s100, 0x400
	s_addc_u32 s101, s101, 0
	v_mov_b32_e32 v160, v24
	v_mov_b32_e32 v161, v25
	v_mov_b32_e32 v162, v26
	v_mov_b32_e32 v163, v27
	v_mov_b32_dpp v24, v28 row_ror:8 row_mask:0xf bank_mask:0x3
	v_mov_b32_dpp v25, v29 row_ror:8 row_mask:0xf bank_mask:0x3
	v_mov_b32_dpp v26, v30 row_ror:8 row_mask:0xf bank_mask:0x3
	v_mov_b32_dpp v27, v31 row_ror:8 row_mask:0xf bank_mask:0x3
	v_mov_b32_dpp v28, v160 row_ror:8 row_mask:0xf bank_mask:0xc
	v_mov_b32_dpp v29, v161 row_ror:8 row_mask:0xf bank_mask:0xc
	v_mov_b32_dpp v30, v162 row_ror:8 row_mask:0xf bank_mask:0xc
	v_mov_b32_dpp v31, v163 row_ror:8 row_mask:0xf bank_mask:0xc
	s_waitcnt vmcnt(46)
	v_fma_f32 v28, v28, 0.5, v100
	v_fma_f32 v29, v29, 0.5, v101
	v_fma_f32 v30, v30, 0.5, v102
	v_fma_f32 v31, v31, 0.5, v103
	global_store_dwordx4 v148, v[28:31], s[88:89]
	v_cvt_pk_bf16_f32 v100, v28, v29
	v_cvt_pk_bf16_f32 v101, v30, v31
	global_store_dwordx2 v158, v[100:101], s[92:93]
	v_mul_f32_e32 v205, v28, v28
	v_fmac_f32_e32 v205, v29, v29
	v_fmac_f32_e32 v205, v30, v30
	v_fmac_f32_e32 v205, v31, v31
	s_waitcnt vmcnt(45)
	v_fma_f32 v24, v24, 0.5, v192
	v_fma_f32 v25, v25, 0.5, v193
	v_fma_f32 v26, v26, 0.5, v194
	v_fma_f32 v27, v27, 0.5, v195
	global_store_dwordx4 v149, v[24:27], s[88:89]
	v_cvt_pk_bf16_f32 v192, v24, v25
	v_cvt_pk_bf16_f32 v193, v26, v27
	global_store_dwordx2 v159, v[192:193], s[92:93]
	v_mul_f32_e32 v210, v24, v24
	v_fmac_f32_e32 v210, v25, v25
	v_fmac_f32_e32 v210, v26, v26
	v_fmac_f32_e32 v210, v27, v27
	v_mov_b32_e32 v160, v16
	v_mov_b32_e32 v161, v17
	v_mov_b32_e32 v162, v18
	v_mov_b32_e32 v163, v19
	v_mov_b32_dpp v16, v20 row_ror:8 row_mask:0xf bank_mask:0x3
	v_mov_b32_dpp v17, v21 row_ror:8 row_mask:0xf bank_mask:0x3
	v_mov_b32_dpp v18, v22 row_ror:8 row_mask:0xf bank_mask:0x3
	v_mov_b32_dpp v19, v23 row_ror:8 row_mask:0xf bank_mask:0x3
	v_mov_b32_dpp v20, v160 row_ror:8 row_mask:0xf bank_mask:0xc
	v_mov_b32_dpp v21, v161 row_ror:8 row_mask:0xf bank_mask:0xc
	v_mov_b32_dpp v22, v162 row_ror:8 row_mask:0xf bank_mask:0xc
	v_mov_b32_dpp v23, v163 row_ror:8 row_mask:0xf bank_mask:0xc
	s_waitcnt vmcnt(46)
	v_fma_f32 v20, v20, 0.5, v96
	v_fma_f32 v21, v21, 0.5, v97
	v_fma_f32 v22, v22, 0.5, v98
	v_fma_f32 v23, v23, 0.5, v99
	global_store_dwordx4 v148, v[20:23], s[88:89] offset:512
	v_cvt_pk_bf16_f32 v96, v20, v21
	v_cvt_pk_bf16_f32 v97, v22, v23
	global_store_dwordx2 v158, v[96:97], s[92:93] offset:256
	v_fmac_f32_e32 v205, v20, v20
	v_fmac_f32_e32 v205, v21, v21
	v_fmac_f32_e32 v205, v22, v22
	v_fmac_f32_e32 v205, v23, v23
	s_waitcnt vmcnt(44)
	v_fma_f32 v16, v16, 0.5, v196
	v_fma_f32 v17, v17, 0.5, v197
	v_fma_f32 v18, v18, 0.5, v198
	v_fma_f32 v19, v19, 0.5, v199
	global_store_dwordx4 v149, v[16:19], s[88:89] offset:512
	v_cvt_pk_bf16_f32 v196, v16, v17
	v_cvt_pk_bf16_f32 v197, v18, v19
	global_store_dwordx2 v159, v[196:197], s[92:93] offset:256
	v_fmac_f32_e32 v210, v16, v16
	v_fmac_f32_e32 v210, v17, v17
	v_fmac_f32_e32 v210, v18, v18
	v_fmac_f32_e32 v210, v19, v19
	s_nop 1
	v_add_f32_dpp v205, v205, v205 row_ror:8 row_mask:0xf bank_mask:0xf
	v_add_f32_dpp v210, v210, v210 row_ror:8 row_mask:0xf bank_mask:0xf
	s_nop 0
	ds_bpermute_b32 v147, v144, v205
	ds_bpermute_b32 v132, v144, v210
	s_waitcnt lgkmcnt(0)
	v_add_f32_e32 v205, v205, v147
	v_add_f32_e32 v210, v210, v132
	s_nop 0
	ds_bpermute_b32 v147, v145, v205
	ds_bpermute_b32 v132, v145, v210
	s_waitcnt lgkmcnt(0)
	v_add_f32_e32 v205, v205, v147
	v_add_f32_e32 v210, v210, v132
	v_cmp_gt_u32_e32 vcc, 8, v211
	s_nop 1
	v_cndmask_b32_e32 v205, v210, v205, vcc
	v_cmp_eq_u32_e32 vcc, 0, v146
	s_and_saveexec_b64 s[98:99], vcc
	global_store_dword v204, v205, s[100:101]
	s_mov_b64 exec, s[98:99]
	s_add_u32 s88, s88, 0x10000
	s_addc_u32 s89, s89, 0
	s_add_u32 s92, s92, 0x8000
	s_addc_u32 s93, s93, 0
	s_add_u32 s100, s100, 0x400
	s_addc_u32 s101, s101, 0
	v_mov_b32_e32 v160, v8
	v_mov_b32_e32 v161, v9
	v_mov_b32_e32 v162, v10
	v_mov_b32_e32 v163, v11
	v_mov_b32_dpp v8, v12 row_ror:8 row_mask:0xf bank_mask:0x3
	v_mov_b32_dpp v9, v13 row_ror:8 row_mask:0xf bank_mask:0x3
	v_mov_b32_dpp v10, v14 row_ror:8 row_mask:0xf bank_mask:0x3
	v_mov_b32_dpp v11, v15 row_ror:8 row_mask:0xf bank_mask:0x3
	v_mov_b32_dpp v12, v160 row_ror:8 row_mask:0xf bank_mask:0xc
	v_mov_b32_dpp v13, v161 row_ror:8 row_mask:0xf bank_mask:0xc
	v_mov_b32_dpp v14, v162 row_ror:8 row_mask:0xf bank_mask:0xc
	v_mov_b32_dpp v15, v163 row_ror:8 row_mask:0xf bank_mask:0xc
	s_waitcnt vmcnt(46)
	v_fma_f32 v12, v12, 0.5, v92
	v_fma_f32 v13, v13, 0.5, v93
	v_fma_f32 v14, v14, 0.5, v94
	v_fma_f32 v15, v15, 0.5, v95
	global_store_dwordx4 v148, v[12:15], s[88:89]
	v_cvt_pk_bf16_f32 v92, v12, v13
	v_cvt_pk_bf16_f32 v93, v14, v15
	global_store_dwordx2 v158, v[92:93], s[92:93]
	v_mul_f32_e32 v205, v12, v12
	v_fmac_f32_e32 v205, v13, v13
	v_fmac_f32_e32 v205, v14, v14
	v_fmac_f32_e32 v205, v15, v15
	s_waitcnt vmcnt(45)
	v_fma_f32 v8, v8, 0.5, v200
	v_fma_f32 v9, v9, 0.5, v201
	v_fma_f32 v10, v10, 0.5, v202
	v_fma_f32 v11, v11, 0.5, v203
	global_store_dwordx4 v149, v[8:11], s[88:89]
	v_cvt_pk_bf16_f32 v200, v8, v9
	v_cvt_pk_bf16_f32 v201, v10, v11
	global_store_dwordx2 v159, v[200:201], s[92:93]
	v_mul_f32_e32 v210, v8, v8
	v_fmac_f32_e32 v210, v9, v9
	v_fmac_f32_e32 v210, v10, v10
	v_fmac_f32_e32 v210, v11, v11
	v_mov_b32_e32 v160, v0
	v_mov_b32_e32 v161, v1
	v_mov_b32_e32 v162, v2
	v_mov_b32_e32 v163, v3
	v_mov_b32_dpp v0, v4 row_ror:8 row_mask:0xf bank_mask:0x3
	v_mov_b32_dpp v1, v5 row_ror:8 row_mask:0xf bank_mask:0x3
	v_mov_b32_dpp v2, v6 row_ror:8 row_mask:0xf bank_mask:0x3
	v_mov_b32_dpp v3, v7 row_ror:8 row_mask:0xf bank_mask:0x3
	v_mov_b32_dpp v4, v160 row_ror:8 row_mask:0xf bank_mask:0xc
	v_mov_b32_dpp v5, v161 row_ror:8 row_mask:0xf bank_mask:0xc
	v_mov_b32_dpp v6, v162 row_ror:8 row_mask:0xf bank_mask:0xc
	v_mov_b32_dpp v7, v163 row_ror:8 row_mask:0xf bank_mask:0xc
	s_waitcnt vmcnt(46)
	v_fma_f32 v4, v4, 0.5, v88
	v_fma_f32 v5, v5, 0.5, v89
	v_fma_f32 v6, v6, 0.5, v90
	v_fma_f32 v7, v7, 0.5, v91
	global_store_dwordx4 v148, v[4:7], s[88:89] offset:512
	v_cvt_pk_bf16_f32 v88, v4, v5
	v_cvt_pk_bf16_f32 v89, v6, v7
	global_store_dwordx2 v158, v[88:89], s[92:93] offset:256
	v_fmac_f32_e32 v205, v4, v4
	v_fmac_f32_e32 v205, v5, v5
	v_fmac_f32_e32 v205, v6, v6
	v_fmac_f32_e32 v205, v7, v7
	s_waitcnt vmcnt(45)
	v_fma_f32 v0, v0, 0.5, v212
	v_fma_f32 v1, v1, 0.5, v213
	v_fma_f32 v2, v2, 0.5, v214
	v_fma_f32 v3, v3, 0.5, v215
	global_store_dwordx4 v149, v[0:3], s[88:89] offset:512
	v_cvt_pk_bf16_f32 v212, v0, v1
	v_cvt_pk_bf16_f32 v213, v2, v3
	global_store_dwordx2 v159, v[212:213], s[92:93] offset:256
	v_fmac_f32_e32 v210, v0, v0
	v_fmac_f32_e32 v210, v1, v1
	v_fmac_f32_e32 v210, v2, v2
	v_fmac_f32_e32 v210, v3, v3
	s_nop 1
	v_add_f32_dpp v205, v205, v205 row_ror:8 row_mask:0xf bank_mask:0xf
	v_add_f32_dpp v210, v210, v210 row_ror:8 row_mask:0xf bank_mask:0xf
	s_nop 0
	ds_bpermute_b32 v147, v144, v205
	ds_bpermute_b32 v132, v144, v210
	s_waitcnt lgkmcnt(0)
	v_add_f32_e32 v205, v205, v147
	v_add_f32_e32 v210, v210, v132
	s_nop 0
	ds_bpermute_b32 v147, v145, v205
	ds_bpermute_b32 v132, v145, v210
	s_waitcnt lgkmcnt(0)
	v_add_f32_e32 v205, v205, v147
	v_add_f32_e32 v210, v210, v132
	v_cmp_gt_u32_e32 vcc, 8, v211
	s_nop 1
	v_cndmask_b32_e32 v205, v210, v205, vcc
	v_cmp_eq_u32_e32 vcc, 0, v146
	s_and_saveexec_b64 s[98:99], vcc
	global_store_dword v204, v205, s[100:101]
	s_mov_b64 exec, s[98:99]
	s_and_b64 vcc, exec, s[10:11]
	s_mov_b64 s[10:11], -1
	s_cbranch_vccnz .LBB0_259
	s_andn2_b64 vcc, exec, s[26:27]
	s_cbranch_vccnz .LBB0_258
	s_barrier
	s_branch .LBB0_258

.LBB0_1010:
	v_lshrrev_b32_e32 v136, 6, v206
	v_and_b32_e32 v147, 63, v206
	v_lshrrev_b32_e32 v146, 2, v136
	v_and_b32_e32 v136, 3, v136
	v_lshlrev_b32_e32 v146, 6, v146
	v_lshrrev_b32_e32 v150, 4, v147
	v_and_b32_e32 v217, 15, v147
	v_xor_b32_e32 v148, 16, v147
	v_xor_b32_e32 v149, 32, v147
	v_lshlrev_b32_e32 v148, 2, v148
	v_lshlrev_b32_e32 v149, 2, v149
	s_lshl_b32 vcc_lo, s24, 8
	v_add_u32_e32 v146, vcc_lo, v146
	s_lshl_b32 vcc_lo, s20, 2
	v_add_u32_e32 v220, vcc_lo, v136
	v_add_u32_e32 v151, v146, v217
	v_lshlrev_b32_e32 v151, 6, v151
	v_lshl_add_u32 v220, v220, 2, v151
	v_lshlrev_b32_e32 v147, 5, v136
	v_lshrrev_b32_e32 v151, 3, v217
	v_lshl_add_u32 v151, v151, 2, v150
	v_lshl_add_u32 v147, v151, 2, v147
	s_lshl_b32 vcc_lo, s20, 8
	v_add_u32_e32 v147, vcc_lo, v147
	v_and_b32_e32 v151, 7, v217
	v_add_u32_e32 v146, v146, v151
	v_lshlrev_b32_e32 v152, 12, v146
	v_lshl_add_u32 v152, v147, 2, v152
	v_add_u32_e32 v153, 0x8000, v152
	v_lshlrev_b32_e32 v210, 11, v146
	v_lshl_add_u32 v210, v147, 1, v210
	v_add_u32_e32 v211, 0x4000, v210
	s_mov_b32 s86, s94
	s_mov_b32 s87, s95
	s_mov_b32 s88, s94
	s_mov_b32 s89, s95
	s_add_u32 s92, s96, 0x9e00000
	s_addc_u32 s93, s97, 0
	s_add_u32 s100, s96, 0x4b00000
	s_addc_u32 s101, s97, 0
	global_load_dwordx4 v[164:167], v152, s[86:87]
	global_load_dwordx4 v[168:171], v153, s[86:87]
	global_load_dwordx4 v[172:175], v152, s[86:87] offset:512
	global_load_dwordx4 v[176:179], v153, s[86:87] offset:512
	s_add_u32 s86, s86, 0x10000
	s_addc_u32 s87, s87, 0
	global_load_dwordx4 v[180:183], v152, s[86:87]
	global_load_dwordx4 v[184:187], v153, s[86:87]
	global_load_dwordx4 v[188:191], v152, s[86:87] offset:512
	global_load_dwordx4 v[192:195], v153, s[86:87] offset:512
	s_add_u32 s86, s86, 0x10000
	s_addc_u32 s87, s87, 0
	global_load_dwordx4 v[196:199], v152, s[86:87]
	global_load_dwordx4 v[200:203], v153, s[86:87]
	global_load_dwordx4 v[212:215], v152, s[86:87] offset:512
	v_mov_b32_e32 v160, v120
	v_mov_b32_e32 v161, v121
	v_mov_b32_e32 v162, v122
	v_mov_b32_e32 v163, v123
	v_mov_b32_dpp v120, v124 row_ror:8 row_mask:0xf bank_mask:0x3
	v_mov_b32_dpp v121, v125 row_ror:8 row_mask:0xf bank_mask:0x3
	v_mov_b32_dpp v122, v126 row_ror:8 row_mask:0xf bank_mask:0x3
	v_mov_b32_dpp v123, v127 row_ror:8 row_mask:0xf bank_mask:0x3
	v_mov_b32_dpp v124, v160 row_ror:8 row_mask:0xf bank_mask:0xc
	v_mov_b32_dpp v125, v161 row_ror:8 row_mask:0xf bank_mask:0xc
	v_mov_b32_dpp v126, v162 row_ror:8 row_mask:0xf bank_mask:0xc
	v_mov_b32_dpp v127, v163 row_ror:8 row_mask:0xf bank_mask:0xc
	s_waitcnt vmcnt(10)
	v_add_f32_e32 v124, v124, v164
	v_add_f32_e32 v125, v125, v165
	v_add_f32_e32 v126, v126, v166
	v_add_f32_e32 v127, v127, v167
	global_store_dwordx4 v152, v[124:127], s[88:89]
	v_cvt_pk_bf16_f32 v164, v124, v125
	v_cvt_pk_bf16_f32 v165, v126, v127
	global_store_dwordx2 v210, v[164:165], s[92:93]
	v_mul_f32_e32 v221, v124, v124
	v_fmac_f32_e32 v221, v125, v125
	v_fmac_f32_e32 v221, v126, v126
	v_fmac_f32_e32 v221, v127, v127
	global_load_dwordx4 v[164:167], v153, s[86:87] offset:512
	s_add_u32 s86, s86, 0x10000
	s_addc_u32 s87, s87, 0
	global_load_dwordx4 v[124:127], v152, s[86:87]
	s_waitcnt vmcnt(13)
	v_add_f32_e32 v120, v120, v168
	v_add_f32_e32 v121, v121, v169
	v_add_f32_e32 v122, v122, v170
	v_add_f32_e32 v123, v123, v171
	global_store_dwordx4 v153, v[120:123], s[88:89]
	v_cvt_pk_bf16_f32 v168, v120, v121
	v_cvt_pk_bf16_f32 v169, v122, v123
	global_store_dwordx2 v211, v[168:169], s[92:93]
	v_mul_f32_e32 v216, v120, v120
	v_fmac_f32_e32 v216, v121, v121
	v_fmac_f32_e32 v216, v122, v122
	v_fmac_f32_e32 v216, v123, v123
	global_load_dwordx4 v[168:171], v153, s[86:87]
	global_load_dwordx4 v[120:123], v152, s[86:87] offset:512
	v_mov_b32_e32 v160, v112
	v_mov_b32_e32 v161, v113
	v_mov_b32_e32 v162, v114
	v_mov_b32_e32 v163, v115
	v_mov_b32_dpp v112, v116 row_ror:8 row_mask:0xf bank_mask:0x3
	v_mov_b32_dpp v113, v117 row_ror:8 row_mask:0xf bank_mask:0x3
	v_mov_b32_dpp v114, v118 row_ror:8 row_mask:0xf bank_mask:0x3
	v_mov_b32_dpp v115, v119 row_ror:8 row_mask:0xf bank_mask:0x3
	v_mov_b32_dpp v116, v160 row_ror:8 row_mask:0xf bank_mask:0xc
	v_mov_b32_dpp v117, v161 row_ror:8 row_mask:0xf bank_mask:0xc
	v_mov_b32_dpp v118, v162 row_ror:8 row_mask:0xf bank_mask:0xc
	v_mov_b32_dpp v119, v163 row_ror:8 row_mask:0xf bank_mask:0xc
	s_waitcnt vmcnt(16)
	v_add_f32_e32 v116, v116, v172
	v_add_f32_e32 v117, v117, v173
	v_add_f32_e32 v118, v118, v174
	v_add_f32_e32 v119, v119, v175
	global_store_dwordx4 v152, v[116:119], s[88:89] offset:512
	v_cvt_pk_bf16_f32 v172, v116, v117
	v_cvt_pk_bf16_f32 v173, v118, v119
	global_store_dwordx2 v210, v[172:173], s[92:93] offset:256
	v_fmac_f32_e32 v221, v116, v116
	v_fmac_f32_e32 v221, v117, v117
	v_fmac_f32_e32 v221, v118, v118
	v_fmac_f32_e32 v221, v119, v119
	global_load_dwordx4 v[172:175], v153, s[86:87] offset:512
	s_add_u32 s86, s86, 0x50000
	s_addc_u32 s87, s87, 0
	global_load_dwordx4 v[116:119], v152, s[86:87]
	s_waitcnt vmcnt(19)
	v_add_f32_e32 v112, v112, v176
	v_add_f32_e32 v113, v113, v177
	v_add_f32_e32 v114, v114, v178
	v_add_f32_e32 v115, v115, v179
	global_store_dwordx4 v153, v[112:115], s[88:89] offset:512
	v_cvt_pk_bf16_f32 v176, v112, v113
	v_cvt_pk_bf16_f32 v177, v114, v115
	global_store_dwordx2 v211, v[176:177], s[92:93] offset:256
	v_fmac_f32_e32 v216, v112, v112
	v_fmac_f32_e32 v216, v113, v113
	v_fmac_f32_e32 v216, v114, v114
	v_fmac_f32_e32 v216, v115, v115
	global_load_dwordx4 v[176:179], v153, s[86:87]
	global_load_dwordx4 v[112:115], v152, s[86:87] offset:512
	s_nop 1
	v_add_f32_dpp v221, v221, v221 row_ror:8 row_mask:0xf bank_mask:0xf
	v_add_f32_dpp v216, v216, v216 row_ror:8 row_mask:0xf bank_mask:0xf
	s_nop 0
	ds_bpermute_b32 v151, v148, v221
	ds_bpermute_b32 v136, v148, v216
	s_waitcnt lgkmcnt(0)
	v_add_f32_e32 v221, v221, v151
	v_add_f32_e32 v216, v216, v136
	s_nop 0
	ds_bpermute_b32 v151, v149, v221
	ds_bpermute_b32 v136, v149, v216
	s_waitcnt lgkmcnt(0)
	v_add_f32_e32 v221, v221, v151
	v_add_f32_e32 v216, v216, v136
	v_cmp_gt_u32_e32 vcc, 8, v217
	s_nop 1
	v_cndmask_b32_e32 v221, v216, v221, vcc
	v_cmp_eq_u32_e32 vcc, 0, v150
	s_and_saveexec_b64 s[98:99], vcc
	global_store_dword v220, v221, s[100:101]
	s_mov_b64 exec, s[98:99]
	s_add_u32 s88, s88, 0x10000
	s_addc_u32 s89, s89, 0
	s_add_u32 s92, s92, 0x8000
	s_addc_u32 s93, s93, 0
	s_add_u32 s100, s100, 0x400
	s_addc_u32 s101, s101, 0
	v_mov_b32_e32 v160, v104
	v_mov_b32_e32 v161, v105
	v_mov_b32_e32 v162, v106
	v_mov_b32_e32 v163, v107
	v_mov_b32_dpp v104, v108 row_ror:8 row_mask:0xf bank_mask:0x3
	v_mov_b32_dpp v105, v109 row_ror:8 row_mask:0xf bank_mask:0x3
	v_mov_b32_dpp v106, v110 row_ror:8 row_mask:0xf bank_mask:0x3
	v_mov_b32_dpp v107, v111 row_ror:8 row_mask:0xf bank_mask:0x3
	v_mov_b32_dpp v108, v160 row_ror:8 row_mask:0xf bank_mask:0xc
	v_mov_b32_dpp v109, v161 row_ror:8 row_mask:0xf bank_mask:0xc
	v_mov_b32_dpp v110, v162 row_ror:8 row_mask:0xf bank_mask:0xc
	v_mov_b32_dpp v111, v163 row_ror:8 row_mask:0xf bank_mask:0xc
	s_waitcnt vmcnt(23)
	v_add_f32_e32 v108, v108, v180
	v_add_f32_e32 v109, v109, v181
	v_add_f32_e32 v110, v110, v182
	v_add_f32_e32 v111, v111, v183
	global_store_dwordx4 v152, v[108:111], s[88:89]
	v_cvt_pk_bf16_f32 v180, v108, v109
	v_cvt_pk_bf16_f32 v181, v110, v111
	global_store_dwordx2 v210, v[180:181], s[92:93]
	v_mul_f32_e32 v221, v108, v108
	v_fmac_f32_e32 v221, v109, v109
	v_fmac_f32_e32 v221, v110, v110
	v_fmac_f32_e32 v221, v111, v111
	global_load_dwordx4 v[180:183], v153, s[86:87] offset:512
	s_add_u32 s86, s86, 0x10000
	s_addc_u32 s87, s87, 0
	global_load_dwordx4 v[108:111], v152, s[86:87]
	s_waitcnt vmcnt(26)
	v_add_f32_e32 v104, v104, v184
	v_add_f32_e32 v105, v105, v185
	v_add_f32_e32 v106, v106, v186
	v_add_f32_e32 v107, v107, v187
	global_store_dwordx4 v153, v[104:107], s[88:89]
	v_cvt_pk_bf16_f32 v184, v104, v105
	v_cvt_pk_bf16_f32 v185, v106, v107
	global_store_dwordx2 v211, v[184:185], s[92:93]
	v_mul_f32_e32 v216, v104, v104
	v_fmac_f32_e32 v216, v105, v105
	v_fmac_f32_e32 v216, v106, v106
	v_fmac_f32_e32 v216, v107, v107
	global_load_dwordx4 v[184:187], v153, s[86:87]
	global_load_dwordx4 v[104:107], v152, s[86:87] offset:512
	v_mov_b32_e32 v160, v96
	v_mov_b32_e32 v161, v97
	v_mov_b32_e32 v162, v98
	v_mov_b32_e32 v163, v99
	v_mov_b32_dpp v96, v100 row_ror:8 row_mask:0xf bank_mask:0x3
	v_mov_b32_dpp v97, v101 row_ror:8 row_mask:0xf bank_mask:0x3
	v_mov_b32_dpp v98, v102 row_ror:8 row_mask:0xf bank_mask:0x3
	v_mov_b32_dpp v99, v103 row_ror:8 row_mask:0xf bank_mask:0x3
	v_mov_b32_dpp v100, v160 row_ror:8 row_mask:0xf bank_mask:0xc
	v_mov_b32_dpp v101, v161 row_ror:8 row_mask:0xf bank_mask:0xc
	v_mov_b32_dpp v102, v162 row_ror:8 row_mask:0xf bank_mask:0xc
	v_mov_b32_dpp v103, v163 row_ror:8 row_mask:0xf bank_mask:0xc
	s_waitcnt vmcnt(29)
	v_add_f32_e32 v100, v100, v188
	v_add_f32_e32 v101, v101, v189
	v_add_f32_e32 v102, v102, v190
	v_add_f32_e32 v103, v103, v191
	global_store_dwordx4 v152, v[100:103], s[88:89] offset:512
	v_cvt_pk_bf16_f32 v188, v100, v101
	v_cvt_pk_bf16_f32 v189, v102, v103
	global_store_dwordx2 v210, v[188:189], s[92:93] offset:256
	v_fmac_f32_e32 v221, v100, v100
	v_fmac_f32_e32 v221, v101, v101
	v_fmac_f32_e32 v221, v102, v102
	v_fmac_f32_e32 v221, v103, v103
	global_load_dwordx4 v[188:191], v153, s[86:87] offset:512
	s_add_u32 s86, s86, 0x10000
	s_addc_u32 s87, s87, 0
	global_load_dwordx4 v[100:103], v152, s[86:87]
	s_waitcnt vmcnt(32)
	v_add_f32_e32 v96, v96, v192
	v_add_f32_e32 v97, v97, v193
	v_add_f32_e32 v98, v98, v194
	v_add_f32_e32 v99, v99, v195
	global_store_dwordx4 v153, v[96:99], s[88:89] offset:512
	v_cvt_pk_bf16_f32 v192, v96, v97
	v_cvt_pk_bf16_f32 v193, v98, v99
	global_store_dwordx2 v211, v[192:193], s[92:93] offset:256
	v_fmac_f32_e32 v216, v96, v96
	v_fmac_f32_e32 v216, v97, v97
	v_fmac_f32_e32 v216, v98, v98
	v_fmac_f32_e32 v216, v99, v99
	global_load_dwordx4 v[192:195], v153, s[86:87]
	global_load_dwordx4 v[96:99], v152, s[86:87] offset:512
	s_nop 1
	v_add_f32_dpp v221, v221, v221 row_ror:8 row_mask:0xf bank_mask:0xf
	v_add_f32_dpp v216, v216, v216 row_ror:8 row_mask:0xf bank_mask:0xf
	s_nop 0
	ds_bpermute_b32 v151, v148, v221
	ds_bpermute_b32 v136, v148, v216
	s_waitcnt lgkmcnt(0)
	v_add_f32_e32 v221, v221, v151
	v_add_f32_e32 v216, v216, v136
	s_nop 0
	ds_bpermute_b32 v151, v149, v221
	ds_bpermute_b32 v136, v149, v216
	s_waitcnt lgkmcnt(0)
	v_add_f32_e32 v221, v221, v151
	v_add_f32_e32 v216, v216, v136
	v_cmp_gt_u32_e32 vcc, 8, v217
	s_nop 1
	v_cndmask_b32_e32 v221, v216, v221, vcc
	v_cmp_eq_u32_e32 vcc, 0, v150
	s_and_saveexec_b64 s[98:99], vcc
	global_store_dword v220, v221, s[100:101]
	s_mov_b64 exec, s[98:99]
	s_add_u32 s88, s88, 0x10000
	s_addc_u32 s89, s89, 0
	s_add_u32 s92, s92, 0x8000
	s_addc_u32 s93, s93, 0
	s_add_u32 s100, s100, 0x400
	s_addc_u32 s101, s101, 0
	v_mov_b32_e32 v160, v88
	v_mov_b32_e32 v161, v89
	v_mov_b32_e32 v162, v90
	v_mov_b32_e32 v163, v91
	v_mov_b32_dpp v88, v92 row_ror:8 row_mask:0xf bank_mask:0x3
	v_mov_b32_dpp v89, v93 row_ror:8 row_mask:0xf bank_mask:0x3
	v_mov_b32_dpp v90, v94 row_ror:8 row_mask:0xf bank_mask:0x3
	v_mov_b32_dpp v91, v95 row_ror:8 row_mask:0xf bank_mask:0x3
	v_mov_b32_dpp v92, v160 row_ror:8 row_mask:0xf bank_mask:0xc
	v_mov_b32_dpp v93, v161 row_ror:8 row_mask:0xf bank_mask:0xc
	v_mov_b32_dpp v94, v162 row_ror:8 row_mask:0xf bank_mask:0xc
	v_mov_b32_dpp v95, v163 row_ror:8 row_mask:0xf bank_mask:0xc
	s_waitcnt vmcnt(36)
	v_add_f32_e32 v92, v92, v196
	v_add_f32_e32 v93, v93, v197
	v_add_f32_e32 v94, v94, v198
	v_add_f32_e32 v95, v95, v199
	global_store_dwordx4 v152, v[92:95], s[88:89]
	v_cvt_pk_bf16_f32 v196, v92, v93
	v_cvt_pk_bf16_f32 v197, v94, v95
	global_store_dwordx2 v210, v[196:197], s[92:93]
	v_mul_f32_e32 v221, v92, v92
	v_fmac_f32_e32 v221, v93, v93
	v_fmac_f32_e32 v221, v94, v94
	v_fmac_f32_e32 v221, v95, v95
	global_load_dwordx4 v[196:199], v153, s[86:87] offset:512
	s_add_u32 s86, s86, 0x10000
	s_addc_u32 s87, s87, 0
	global_load_dwordx4 v[92:95], v152, s[86:87]
	s_waitcnt vmcnt(39)
	v_add_f32_e32 v88, v88, v200
	v_add_f32_e32 v89, v89, v201
	v_add_f32_e32 v90, v90, v202
	v_add_f32_e32 v91, v91, v203
	global_store_dwordx4 v153, v[88:91], s[88:89]
	v_cvt_pk_bf16_f32 v200, v88, v89
	v_cvt_pk_bf16_f32 v201, v90, v91
	global_store_dwordx2 v211, v[200:201], s[92:93]
	v_mul_f32_e32 v216, v88, v88
	v_fmac_f32_e32 v216, v89, v89
	v_fmac_f32_e32 v216, v90, v90
	v_fmac_f32_e32 v216, v91, v91
	global_load_dwordx4 v[200:203], v153, s[86:87]
	global_load_dwordx4 v[88:91], v152, s[86:87] offset:512
	v_mov_b32_e32 v160, v80
	v_mov_b32_e32 v161, v81
	v_mov_b32_e32 v162, v82
	v_mov_b32_e32 v163, v83
	v_mov_b32_dpp v80, v84 row_ror:8 row_mask:0xf bank_mask:0x3
	v_mov_b32_dpp v81, v85 row_ror:8 row_mask:0xf bank_mask:0x3
	v_mov_b32_dpp v82, v86 row_ror:8 row_mask:0xf bank_mask:0x3
	v_mov_b32_dpp v83, v87 row_ror:8 row_mask:0xf bank_mask:0x3
	v_mov_b32_dpp v84, v160 row_ror:8 row_mask:0xf bank_mask:0xc
	v_mov_b32_dpp v85, v161 row_ror:8 row_mask:0xf bank_mask:0xc
	v_mov_b32_dpp v86, v162 row_ror:8 row_mask:0xf bank_mask:0xc
	v_mov_b32_dpp v87, v163 row_ror:8 row_mask:0xf bank_mask:0xc
	s_waitcnt vmcnt(42)
	v_add_f32_e32 v84, v84, v212
	v_add_f32_e32 v85, v85, v213
	v_add_f32_e32 v86, v86, v214
	v_add_f32_e32 v87, v87, v215
	global_store_dwordx4 v152, v[84:87], s[88:89] offset:512
	v_cvt_pk_bf16_f32 v212, v84, v85
	v_cvt_pk_bf16_f32 v213, v86, v87
	global_store_dwordx2 v210, v[212:213], s[92:93] offset:256
	v_fmac_f32_e32 v221, v84, v84
	v_fmac_f32_e32 v221, v85, v85
	v_fmac_f32_e32 v221, v86, v86
	v_fmac_f32_e32 v221, v87, v87
	global_load_dwordx4 v[212:215], v153, s[86:87] offset:512
	s_waitcnt vmcnt(42)
	v_add_f32_e32 v80, v80, v164
	v_add_f32_e32 v81, v81, v165
	v_add_f32_e32 v82, v82, v166
	v_add_f32_e32 v83, v83, v167
	global_store_dwordx4 v153, v[80:83], s[88:89] offset:512
	v_cvt_pk_bf16_f32 v164, v80, v81
	v_cvt_pk_bf16_f32 v165, v82, v83
	global_store_dwordx2 v211, v[164:165], s[92:93] offset:256
	v_fmac_f32_e32 v216, v80, v80
	v_fmac_f32_e32 v216, v81, v81
	v_fmac_f32_e32 v216, v82, v82
	v_fmac_f32_e32 v216, v83, v83
	s_nop 1
	v_add_f32_dpp v221, v221, v221 row_ror:8 row_mask:0xf bank_mask:0xf
	v_add_f32_dpp v216, v216, v216 row_ror:8 row_mask:0xf bank_mask:0xf
	s_nop 0
	ds_bpermute_b32 v151, v148, v221
	ds_bpermute_b32 v136, v148, v216
	s_waitcnt lgkmcnt(0)
	v_add_f32_e32 v221, v221, v151
	v_add_f32_e32 v216, v216, v136
	s_nop 0
	ds_bpermute_b32 v151, v149, v221
	ds_bpermute_b32 v136, v149, v216
	s_waitcnt lgkmcnt(0)
	v_add_f32_e32 v221, v221, v151
	v_add_f32_e32 v216, v216, v136
	v_cmp_gt_u32_e32 vcc, 8, v217
	s_nop 1
	v_cndmask_b32_e32 v221, v216, v221, vcc
	v_cmp_eq_u32_e32 vcc, 0, v150
	s_and_saveexec_b64 s[98:99], vcc
	global_store_dword v220, v221, s[100:101]
	s_mov_b64 exec, s[98:99]
	s_add_u32 s88, s88, 0x10000
	s_addc_u32 s89, s89, 0
	s_add_u32 s92, s92, 0x8000
	s_addc_u32 s93, s93, 0
	s_add_u32 s100, s100, 0x400
	s_addc_u32 s101, s101, 0
	v_mov_b32_e32 v160, v72
	v_mov_b32_e32 v161, v73
	v_mov_b32_e32 v162, v74
	v_mov_b32_e32 v163, v75
	v_mov_b32_dpp v72, v76 row_ror:8 row_mask:0xf bank_mask:0x3
	v_mov_b32_dpp v73, v77 row_ror:8 row_mask:0xf bank_mask:0x3
	v_mov_b32_dpp v74, v78 row_ror:8 row_mask:0xf bank_mask:0x3
	v_mov_b32_dpp v75, v79 row_ror:8 row_mask:0xf bank_mask:0x3
	v_mov_b32_dpp v76, v160 row_ror:8 row_mask:0xf bank_mask:0xc
	v_mov_b32_dpp v77, v161 row_ror:8 row_mask:0xf bank_mask:0xc
	v_mov_b32_dpp v78, v162 row_ror:8 row_mask:0xf bank_mask:0xc
	v_mov_b32_dpp v79, v163 row_ror:8 row_mask:0xf bank_mask:0xc
	s_waitcnt vmcnt(44)
	v_add_f32_e32 v76, v76, v124
	v_add_f32_e32 v77, v77, v125
	v_add_f32_e32 v78, v78, v126
	v_add_f32_e32 v79, v79, v127
	global_store_dwordx4 v152, v[76:79], s[88:89]
	v_cvt_pk_bf16_f32 v124, v76, v77
	v_cvt_pk_bf16_f32 v125, v78, v79
	global_store_dwordx2 v210, v[124:125], s[92:93]
	v_mul_f32_e32 v221, v76, v76
	v_fmac_f32_e32 v221, v77, v77
	v_fmac_f32_e32 v221, v78, v78
	v_fmac_f32_e32 v221, v79, v79
	s_waitcnt vmcnt(43)
	v_add_f32_e32 v72, v72, v168
	v_add_f32_e32 v73, v73, v169
	v_add_f32_e32 v74, v74, v170
	v_add_f32_e32 v75, v75, v171
	global_store_dwordx4 v153, v[72:75], s[88:89]
	v_cvt_pk_bf16_f32 v168, v72, v73
	v_cvt_pk_bf16_f32 v169, v74, v75
	global_store_dwordx2 v211, v[168:169], s[92:93]
	v_mul_f32_e32 v216, v72, v72
	v_fmac_f32_e32 v216, v73, v73
	v_fmac_f32_e32 v216, v74, v74
	v_fmac_f32_e32 v216, v75, v75
	v_mov_b32_e32 v160, v64
	v_mov_b32_e32 v161, v65
	v_mov_b32_e32 v162, v66
	v_mov_b32_e32 v163, v67
	v_mov_b32_dpp v64, v68 row_ror:8 row_mask:0xf bank_mask:0x3
	v_mov_b32_dpp v65, v69 row_ror:8 row_mask:0xf bank_mask:0x3
	v_mov_b32_dpp v66, v70 row_ror:8 row_mask:0xf bank_mask:0x3
	v_mov_b32_dpp v67, v71 row_ror:8 row_mask:0xf bank_mask:0x3
	v_mov_b32_dpp v68, v160 row_ror:8 row_mask:0xf bank_mask:0xc
	v_mov_b32_dpp v69, v161 row_ror:8 row_mask:0xf bank_mask:0xc
	v_mov_b32_dpp v70, v162 row_ror:8 row_mask:0xf bank_mask:0xc
	v_mov_b32_dpp v71, v163 row_ror:8 row_mask:0xf bank_mask:0xc
	s_waitcnt vmcnt(44)
	v_add_f32_e32 v68, v68, v120
	v_add_f32_e32 v69, v69, v121
	v_add_f32_e32 v70, v70, v122
	v_add_f32_e32 v71, v71, v123
	global_store_dwordx4 v152, v[68:71], s[88:89] offset:512
	v_cvt_pk_bf16_f32 v120, v68, v69
	v_cvt_pk_bf16_f32 v121, v70, v71
	global_store_dwordx2 v210, v[120:121], s[92:93] offset:256
	v_fmac_f32_e32 v221, v68, v68
	v_fmac_f32_e32 v221, v69, v69
	v_fmac_f32_e32 v221, v70, v70
	v_fmac_f32_e32 v221, v71, v71
	s_waitcnt vmcnt(43)
	v_add_f32_e32 v64, v64, v172
	v_add_f32_e32 v65, v65, v173
	v_add_f32_e32 v66, v66, v174
	v_add_f32_e32 v67, v67, v175
	global_store_dwordx4 v153, v[64:67], s[88:89] offset:512
	v_cvt_pk_bf16_f32 v172, v64, v65
	v_cvt_pk_bf16_f32 v173, v66, v67
	global_store_dwordx2 v211, v[172:173], s[92:93] offset:256
	v_fmac_f32_e32 v216, v64, v64
	v_fmac_f32_e32 v216, v65, v65
	v_fmac_f32_e32 v216, v66, v66
	v_fmac_f32_e32 v216, v67, v67
	s_nop 1
	v_add_f32_dpp v221, v221, v221 row_ror:8 row_mask:0xf bank_mask:0xf
	v_add_f32_dpp v216, v216, v216 row_ror:8 row_mask:0xf bank_mask:0xf
	s_nop 0
	ds_bpermute_b32 v151, v148, v221
	ds_bpermute_b32 v136, v148, v216
	s_waitcnt lgkmcnt(0)
	v_add_f32_e32 v221, v221, v151
	v_add_f32_e32 v216, v216, v136
	s_nop 0
	ds_bpermute_b32 v151, v149, v221
	ds_bpermute_b32 v136, v149, v216
	s_waitcnt lgkmcnt(0)
	v_add_f32_e32 v221, v221, v151
	v_add_f32_e32 v216, v216, v136
	v_cmp_gt_u32_e32 vcc, 8, v217
	s_nop 1
	v_cndmask_b32_e32 v221, v216, v221, vcc
	v_cmp_eq_u32_e32 vcc, 0, v150
	s_and_saveexec_b64 s[98:99], vcc
	global_store_dword v220, v221, s[100:101]
	s_mov_b64 exec, s[98:99]
	s_add_u32 s88, s88, 0x50000
	s_addc_u32 s89, s89, 0
	s_add_u32 s92, s92, 0x28000
	s_addc_u32 s93, s93, 0
	s_add_u32 s100, s100, 0x1400
	s_addc_u32 s101, s101, 0
	v_mov_b32_e32 v160, v56
	v_mov_b32_e32 v161, v57
	v_mov_b32_e32 v162, v58
	v_mov_b32_e32 v163, v59
	v_mov_b32_dpp v56, v60 row_ror:8 row_mask:0xf bank_mask:0x3
	v_mov_b32_dpp v57, v61 row_ror:8 row_mask:0xf bank_mask:0x3
	v_mov_b32_dpp v58, v62 row_ror:8 row_mask:0xf bank_mask:0x3
	v_mov_b32_dpp v59, v63 row_ror:8 row_mask:0xf bank_mask:0x3
	v_mov_b32_dpp v60, v160 row_ror:8 row_mask:0xf bank_mask:0xc
	v_mov_b32_dpp v61, v161 row_ror:8 row_mask:0xf bank_mask:0xc
	v_mov_b32_dpp v62, v162 row_ror:8 row_mask:0xf bank_mask:0xc
	v_mov_b32_dpp v63, v163 row_ror:8 row_mask:0xf bank_mask:0xc
	s_waitcnt vmcnt(45)
	v_add_f32_e32 v60, v60, v116
	v_add_f32_e32 v61, v61, v117
	v_add_f32_e32 v62, v62, v118
	v_add_f32_e32 v63, v63, v119
	global_store_dwordx4 v152, v[60:63], s[88:89]
	v_cvt_pk_bf16_f32 v116, v60, v61
	v_cvt_pk_bf16_f32 v117, v62, v63
	global_store_dwordx2 v210, v[116:117], s[92:93]
	v_mul_f32_e32 v221, v60, v60
	v_fmac_f32_e32 v221, v61, v61
	v_fmac_f32_e32 v221, v62, v62
	v_fmac_f32_e32 v221, v63, v63
	s_waitcnt vmcnt(44)
	v_add_f32_e32 v56, v56, v176
	v_add_f32_e32 v57, v57, v177
	v_add_f32_e32 v58, v58, v178
	v_add_f32_e32 v59, v59, v179
	global_store_dwordx4 v153, v[56:59], s[88:89]
	v_cvt_pk_bf16_f32 v176, v56, v57
	v_cvt_pk_bf16_f32 v177, v58, v59
	global_store_dwordx2 v211, v[176:177], s[92:93]
	v_mul_f32_e32 v216, v56, v56
	v_fmac_f32_e32 v216, v57, v57
	v_fmac_f32_e32 v216, v58, v58
	v_fmac_f32_e32 v216, v59, v59
	v_mov_b32_e32 v160, v48
	v_mov_b32_e32 v161, v49
	v_mov_b32_e32 v162, v50
	v_mov_b32_e32 v163, v51
	v_mov_b32_dpp v48, v52 row_ror:8 row_mask:0xf bank_mask:0x3
	v_mov_b32_dpp v49, v53 row_ror:8 row_mask:0xf bank_mask:0x3
	v_mov_b32_dpp v50, v54 row_ror:8 row_mask:0xf bank_mask:0x3
	v_mov_b32_dpp v51, v55 row_ror:8 row_mask:0xf bank_mask:0x3
	v_mov_b32_dpp v52, v160 row_ror:8 row_mask:0xf bank_mask:0xc
	v_mov_b32_dpp v53, v161 row_ror:8 row_mask:0xf bank_mask:0xc
	v_mov_b32_dpp v54, v162 row_ror:8 row_mask:0xf bank_mask:0xc
	v_mov_b32_dpp v55, v163 row_ror:8 row_mask:0xf bank_mask:0xc
	s_waitcnt vmcnt(45)
	v_add_f32_e32 v52, v52, v112
	v_add_f32_e32 v53, v53, v113
	v_add_f32_e32 v54, v54, v114
	v_add_f32_e32 v55, v55, v115
	global_store_dwordx4 v152, v[52:55], s[88:89] offset:512
	v_cvt_pk_bf16_f32 v112, v52, v53
	v_cvt_pk_bf16_f32 v113, v54, v55
	global_store_dwordx2 v210, v[112:113], s[92:93] offset:256
	v_fmac_f32_e32 v221, v52, v52
	v_fmac_f32_e32 v221, v53, v53
	v_fmac_f32_e32 v221, v54, v54
	v_fmac_f32_e32 v221, v55, v55
	s_waitcnt vmcnt(43)
	v_add_f32_e32 v48, v48, v180
	v_add_f32_e32 v49, v49, v181
	v_add_f32_e32 v50, v50, v182
	v_add_f32_e32 v51, v51, v183
	global_store_dwordx4 v153, v[48:51], s[88:89] offset:512
	v_cvt_pk_bf16_f32 v180, v48, v49
	v_cvt_pk_bf16_f32 v181, v50, v51
	global_store_dwordx2 v211, v[180:181], s[92:93] offset:256
	v_fmac_f32_e32 v216, v48, v48
	v_fmac_f32_e32 v216, v49, v49
	v_fmac_f32_e32 v216, v50, v50
	v_fmac_f32_e32 v216, v51, v51
	s_nop 1
	v_add_f32_dpp v221, v221, v221 row_ror:8 row_mask:0xf bank_mask:0xf
	v_add_f32_dpp v216, v216, v216 row_ror:8 row_mask:0xf bank_mask:0xf
	s_nop 0
	ds_bpermute_b32 v151, v148, v221
	ds_bpermute_b32 v136, v148, v216
	s_waitcnt lgkmcnt(0)
	v_add_f32_e32 v221, v221, v151
	v_add_f32_e32 v216, v216, v136
	s_nop 0
	ds_bpermute_b32 v151, v149, v221
	ds_bpermute_b32 v136, v149, v216
	s_waitcnt lgkmcnt(0)
	v_add_f32_e32 v221, v221, v151
	v_add_f32_e32 v216, v216, v136
	v_cmp_gt_u32_e32 vcc, 8, v217
	s_nop 1
	v_cndmask_b32_e32 v221, v216, v221, vcc
	v_cmp_eq_u32_e32 vcc, 0, v150
	s_and_saveexec_b64 s[98:99], vcc
	global_store_dword v220, v221, s[100:101]
	s_mov_b64 exec, s[98:99]
	s_add_u32 s88, s88, 0x10000
	s_addc_u32 s89, s89, 0
	s_add_u32 s92, s92, 0x8000
	s_addc_u32 s93, s93, 0
	s_add_u32 s100, s100, 0x400
	s_addc_u32 s101, s101, 0
	v_mov_b32_e32 v160, v40
	v_mov_b32_e32 v161, v41
	v_mov_b32_e32 v162, v42
	v_mov_b32_e32 v163, v43
	v_mov_b32_dpp v40, v44 row_ror:8 row_mask:0xf bank_mask:0x3
	v_mov_b32_dpp v41, v45 row_ror:8 row_mask:0xf bank_mask:0x3
	v_mov_b32_dpp v42, v46 row_ror:8 row_mask:0xf bank_mask:0x3
	v_mov_b32_dpp v43, v47 row_ror:8 row_mask:0xf bank_mask:0x3
	v_mov_b32_dpp v44, v160 row_ror:8 row_mask:0xf bank_mask:0xc
	v_mov_b32_dpp v45, v161 row_ror:8 row_mask:0xf bank_mask:0xc
	v_mov_b32_dpp v46, v162 row_ror:8 row_mask:0xf bank_mask:0xc
	v_mov_b32_dpp v47, v163 row_ror:8 row_mask:0xf bank_mask:0xc
	s_waitcnt vmcnt(45)
	v_add_f32_e32 v44, v44, v108
	v_add_f32_e32 v45, v45, v109
	v_add_f32_e32 v46, v46, v110
	v_add_f32_e32 v47, v47, v111
	global_store_dwordx4 v152, v[44:47], s[88:89]
	v_cvt_pk_bf16_f32 v108, v44, v45
	v_cvt_pk_bf16_f32 v109, v46, v47
	global_store_dwordx2 v210, v[108:109], s[92:93]
	v_mul_f32_e32 v221, v44, v44
	v_fmac_f32_e32 v221, v45, v45
	v_fmac_f32_e32 v221, v46, v46
	v_fmac_f32_e32 v221, v47, v47
	s_waitcnt vmcnt(44)
	v_add_f32_e32 v40, v40, v184
	v_add_f32_e32 v41, v41, v185
	v_add_f32_e32 v42, v42, v186
	v_add_f32_e32 v43, v43, v187
	global_store_dwordx4 v153, v[40:43], s[88:89]
	v_cvt_pk_bf16_f32 v184, v40, v41
	v_cvt_pk_bf16_f32 v185, v42, v43
	global_store_dwordx2 v211, v[184:185], s[92:93]
	v_mul_f32_e32 v216, v40, v40
	v_fmac_f32_e32 v216, v41, v41
	v_fmac_f32_e32 v216, v42, v42
	v_fmac_f32_e32 v216, v43, v43
	v_mov_b32_e32 v160, v32
	v_mov_b32_e32 v161, v33
	v_mov_b32_e32 v162, v34
	v_mov_b32_e32 v163, v35
	v_mov_b32_dpp v32, v36 row_ror:8 row_mask:0xf bank_mask:0x3
	v_mov_b32_dpp v33, v37 row_ror:8 row_mask:0xf bank_mask:0x3
	v_mov_b32_dpp v34, v38 row_ror:8 row_mask:0xf bank_mask:0x3
	v_mov_b32_dpp v35, v39 row_ror:8 row_mask:0xf bank_mask:0x3
	v_mov_b32_dpp v36, v160 row_ror:8 row_mask:0xf bank_mask:0xc
	v_mov_b32_dpp v37, v161 row_ror:8 row_mask:0xf bank_mask:0xc
	v_mov_b32_dpp v38, v162 row_ror:8 row_mask:0xf bank_mask:0xc
	v_mov_b32_dpp v39, v163 row_ror:8 row_mask:0xf bank_mask:0xc
	s_waitcnt vmcnt(45)
	v_add_f32_e32 v36, v36, v104
	v_add_f32_e32 v37, v37, v105
	v_add_f32_e32 v38, v38, v106
	v_add_f32_e32 v39, v39, v107
	global_store_dwordx4 v152, v[36:39], s[88:89] offset:512
	v_cvt_pk_bf16_f32 v104, v36, v37
	v_cvt_pk_bf16_f32 v105, v38, v39
	global_store_dwordx2 v210, v[104:105], s[92:93] offset:256
	v_fmac_f32_e32 v221, v36, v36
	v_fmac_f32_e32 v221, v37, v37
	v_fmac_f32_e32 v221, v38, v38
	v_fmac_f32_e32 v221, v39, v39
	s_waitcnt vmcnt(44)
	v_add_f32_e32 v32, v32, v188
	v_add_f32_e32 v33, v33, v189
	v_add_f32_e32 v34, v34, v190
	v_add_f32_e32 v35, v35, v191
	global_store_dwordx4 v153, v[32:35], s[88:89] offset:512
	v_cvt_pk_bf16_f32 v188, v32, v33
	v_cvt_pk_bf16_f32 v189, v34, v35
	global_store_dwordx2 v211, v[188:189], s[92:93] offset:256
	v_fmac_f32_e32 v216, v32, v32
	v_fmac_f32_e32 v216, v33, v33
	v_fmac_f32_e32 v216, v34, v34
	v_fmac_f32_e32 v216, v35, v35
	s_nop 1
	v_add_f32_dpp v221, v221, v221 row_ror:8 row_mask:0xf bank_mask:0xf
	v_add_f32_dpp v216, v216, v216 row_ror:8 row_mask:0xf bank_mask:0xf
	s_nop 0
	ds_bpermute_b32 v151, v148, v221
	ds_bpermute_b32 v136, v148, v216
	s_waitcnt lgkmcnt(0)
	v_add_f32_e32 v221, v221, v151
	v_add_f32_e32 v216, v216, v136
	s_nop 0
	ds_bpermute_b32 v151, v149, v221
	ds_bpermute_b32 v136, v149, v216
	s_waitcnt lgkmcnt(0)
	v_add_f32_e32 v221, v221, v151
	v_add_f32_e32 v216, v216, v136
	v_cmp_gt_u32_e32 vcc, 8, v217
	s_nop 1
	v_cndmask_b32_e32 v221, v216, v221, vcc
	v_cmp_eq_u32_e32 vcc, 0, v150
	s_and_saveexec_b64 s[98:99], vcc
	global_store_dword v220, v221, s[100:101]
	s_mov_b64 exec, s[98:99]
	s_add_u32 s88, s88, 0x10000
	s_addc_u32 s89, s89, 0
	s_add_u32 s92, s92, 0x8000
	s_addc_u32 s93, s93, 0
	s_add_u32 s100, s100, 0x400
	s_addc_u32 s101, s101, 0
	v_mov_b32_e32 v160, v24
	v_mov_b32_e32 v161, v25
	v_mov_b32_e32 v162, v26
	v_mov_b32_e32 v163, v27
	v_mov_b32_dpp v24, v28 row_ror:8 row_mask:0xf bank_mask:0x3
	v_mov_b32_dpp v25, v29 row_ror:8 row_mask:0xf bank_mask:0x3
	v_mov_b32_dpp v26, v30 row_ror:8 row_mask:0xf bank_mask:0x3
	v_mov_b32_dpp v27, v31 row_ror:8 row_mask:0xf bank_mask:0x3
	v_mov_b32_dpp v28, v160 row_ror:8 row_mask:0xf bank_mask:0xc
	v_mov_b32_dpp v29, v161 row_ror:8 row_mask:0xf bank_mask:0xc
	v_mov_b32_dpp v30, v162 row_ror:8 row_mask:0xf bank_mask:0xc
	v_mov_b32_dpp v31, v163 row_ror:8 row_mask:0xf bank_mask:0xc
	s_waitcnt vmcnt(46)
	v_add_f32_e32 v28, v28, v100
	v_add_f32_e32 v29, v29, v101
	v_add_f32_e32 v30, v30, v102
	v_add_f32_e32 v31, v31, v103
	global_store_dwordx4 v152, v[28:31], s[88:89]
	v_cvt_pk_bf16_f32 v100, v28, v29
	v_cvt_pk_bf16_f32 v101, v30, v31
	global_store_dwordx2 v210, v[100:101], s[92:93]
	v_mul_f32_e32 v221, v28, v28
	v_fmac_f32_e32 v221, v29, v29
	v_fmac_f32_e32 v221, v30, v30
	v_fmac_f32_e32 v221, v31, v31
	s_waitcnt vmcnt(45)
	v_add_f32_e32 v24, v24, v192
	v_add_f32_e32 v25, v25, v193
	v_add_f32_e32 v26, v26, v194
	v_add_f32_e32 v27, v27, v195
	global_store_dwordx4 v153, v[24:27], s[88:89]
	v_cvt_pk_bf16_f32 v192, v24, v25
	v_cvt_pk_bf16_f32 v193, v26, v27
	global_store_dwordx2 v211, v[192:193], s[92:93]
	v_mul_f32_e32 v216, v24, v24
	v_fmac_f32_e32 v216, v25, v25
	v_fmac_f32_e32 v216, v26, v26
	v_fmac_f32_e32 v216, v27, v27
	v_mov_b32_e32 v160, v16
	v_mov_b32_e32 v161, v17
	v_mov_b32_e32 v162, v18
	v_mov_b32_e32 v163, v19
	v_mov_b32_dpp v16, v20 row_ror:8 row_mask:0xf bank_mask:0x3
	v_mov_b32_dpp v17, v21 row_ror:8 row_mask:0xf bank_mask:0x3
	v_mov_b32_dpp v18, v22 row_ror:8 row_mask:0xf bank_mask:0x3
	v_mov_b32_dpp v19, v23 row_ror:8 row_mask:0xf bank_mask:0x3
	v_mov_b32_dpp v20, v160 row_ror:8 row_mask:0xf bank_mask:0xc
	v_mov_b32_dpp v21, v161 row_ror:8 row_mask:0xf bank_mask:0xc
	v_mov_b32_dpp v22, v162 row_ror:8 row_mask:0xf bank_mask:0xc
	v_mov_b32_dpp v23, v163 row_ror:8 row_mask:0xf bank_mask:0xc
	s_waitcnt vmcnt(46)
	v_add_f32_e32 v20, v20, v96
	v_add_f32_e32 v21, v21, v97
	v_add_f32_e32 v22, v22, v98
	v_add_f32_e32 v23, v23, v99
	global_store_dwordx4 v152, v[20:23], s[88:89] offset:512
	v_cvt_pk_bf16_f32 v96, v20, v21
	v_cvt_pk_bf16_f32 v97, v22, v23
	global_store_dwordx2 v210, v[96:97], s[92:93] offset:256
	v_fmac_f32_e32 v221, v20, v20
	v_fmac_f32_e32 v221, v21, v21
	v_fmac_f32_e32 v221, v22, v22
	v_fmac_f32_e32 v221, v23, v23
	s_waitcnt vmcnt(44)
	v_add_f32_e32 v16, v16, v196
	v_add_f32_e32 v17, v17, v197
	v_add_f32_e32 v18, v18, v198
	v_add_f32_e32 v19, v19, v199
	global_store_dwordx4 v153, v[16:19], s[88:89] offset:512
	v_cvt_pk_bf16_f32 v196, v16, v17
	v_cvt_pk_bf16_f32 v197, v18, v19
	global_store_dwordx2 v211, v[196:197], s[92:93] offset:256
	v_fmac_f32_e32 v216, v16, v16
	v_fmac_f32_e32 v216, v17, v17
	v_fmac_f32_e32 v216, v18, v18
	v_fmac_f32_e32 v216, v19, v19
	s_nop 1
	v_add_f32_dpp v221, v221, v221 row_ror:8 row_mask:0xf bank_mask:0xf
	v_add_f32_dpp v216, v216, v216 row_ror:8 row_mask:0xf bank_mask:0xf
	s_nop 0
	ds_bpermute_b32 v151, v148, v221
	ds_bpermute_b32 v136, v148, v216
	s_waitcnt lgkmcnt(0)
	v_add_f32_e32 v221, v221, v151
	v_add_f32_e32 v216, v216, v136
	s_nop 0
	ds_bpermute_b32 v151, v149, v221
	ds_bpermute_b32 v136, v149, v216
	s_waitcnt lgkmcnt(0)
	v_add_f32_e32 v221, v221, v151
	v_add_f32_e32 v216, v216, v136
	v_cmp_gt_u32_e32 vcc, 8, v217
	s_nop 1
	v_cndmask_b32_e32 v221, v216, v221, vcc
	v_cmp_eq_u32_e32 vcc, 0, v150
	s_and_saveexec_b64 s[98:99], vcc
	global_store_dword v220, v221, s[100:101]
	s_mov_b64 exec, s[98:99]
	s_add_u32 s88, s88, 0x10000
	s_addc_u32 s89, s89, 0
	s_add_u32 s92, s92, 0x8000
	s_addc_u32 s93, s93, 0
	s_add_u32 s100, s100, 0x400
	s_addc_u32 s101, s101, 0
	v_mov_b32_e32 v160, v8
	v_mov_b32_e32 v161, v9
	v_mov_b32_e32 v162, v10
	v_mov_b32_e32 v163, v11
	v_mov_b32_dpp v8, v12 row_ror:8 row_mask:0xf bank_mask:0x3
	v_mov_b32_dpp v9, v13 row_ror:8 row_mask:0xf bank_mask:0x3
	v_mov_b32_dpp v10, v14 row_ror:8 row_mask:0xf bank_mask:0x3
	v_mov_b32_dpp v11, v15 row_ror:8 row_mask:0xf bank_mask:0x3
	v_mov_b32_dpp v12, v160 row_ror:8 row_mask:0xf bank_mask:0xc
	v_mov_b32_dpp v13, v161 row_ror:8 row_mask:0xf bank_mask:0xc
	v_mov_b32_dpp v14, v162 row_ror:8 row_mask:0xf bank_mask:0xc
	v_mov_b32_dpp v15, v163 row_ror:8 row_mask:0xf bank_mask:0xc
	s_waitcnt vmcnt(46)
	v_add_f32_e32 v12, v12, v92
	v_add_f32_e32 v13, v13, v93
	v_add_f32_e32 v14, v14, v94
	v_add_f32_e32 v15, v15, v95
	global_store_dwordx4 v152, v[12:15], s[88:89]
	v_cvt_pk_bf16_f32 v92, v12, v13
	v_cvt_pk_bf16_f32 v93, v14, v15
	global_store_dwordx2 v210, v[92:93], s[92:93]
	v_mul_f32_e32 v221, v12, v12
	v_fmac_f32_e32 v221, v13, v13
	v_fmac_f32_e32 v221, v14, v14
	v_fmac_f32_e32 v221, v15, v15
	s_waitcnt vmcnt(45)
	v_add_f32_e32 v8, v8, v200
	v_add_f32_e32 v9, v9, v201
	v_add_f32_e32 v10, v10, v202
	v_add_f32_e32 v11, v11, v203
	global_store_dwordx4 v153, v[8:11], s[88:89]
	v_cvt_pk_bf16_f32 v200, v8, v9
	v_cvt_pk_bf16_f32 v201, v10, v11
	global_store_dwordx2 v211, v[200:201], s[92:93]
	v_mul_f32_e32 v216, v8, v8
	v_fmac_f32_e32 v216, v9, v9
	v_fmac_f32_e32 v216, v10, v10
	v_fmac_f32_e32 v216, v11, v11
	v_mov_b32_e32 v160, v0
	v_mov_b32_e32 v161, v1
	v_mov_b32_e32 v162, v2
	v_mov_b32_e32 v163, v3
	v_mov_b32_dpp v0, v4 row_ror:8 row_mask:0xf bank_mask:0x3
	v_mov_b32_dpp v1, v5 row_ror:8 row_mask:0xf bank_mask:0x3
	v_mov_b32_dpp v2, v6 row_ror:8 row_mask:0xf bank_mask:0x3
	v_mov_b32_dpp v3, v7 row_ror:8 row_mask:0xf bank_mask:0x3
	v_mov_b32_dpp v4, v160 row_ror:8 row_mask:0xf bank_mask:0xc
	v_mov_b32_dpp v5, v161 row_ror:8 row_mask:0xf bank_mask:0xc
	v_mov_b32_dpp v6, v162 row_ror:8 row_mask:0xf bank_mask:0xc
	v_mov_b32_dpp v7, v163 row_ror:8 row_mask:0xf bank_mask:0xc
	s_waitcnt vmcnt(46)
	v_add_f32_e32 v4, v4, v88
	v_add_f32_e32 v5, v5, v89
	v_add_f32_e32 v6, v6, v90
	v_add_f32_e32 v7, v7, v91
	global_store_dwordx4 v152, v[4:7], s[88:89] offset:512
	v_cvt_pk_bf16_f32 v88, v4, v5
	v_cvt_pk_bf16_f32 v89, v6, v7
	global_store_dwordx2 v210, v[88:89], s[92:93] offset:256
	v_fmac_f32_e32 v221, v4, v4
	v_fmac_f32_e32 v221, v5, v5
	v_fmac_f32_e32 v221, v6, v6
	v_fmac_f32_e32 v221, v7, v7
	s_waitcnt vmcnt(45)
	v_add_f32_e32 v0, v0, v212
	v_add_f32_e32 v1, v1, v213
	v_add_f32_e32 v2, v2, v214
	v_add_f32_e32 v3, v3, v215
	global_store_dwordx4 v153, v[0:3], s[88:89] offset:512
	v_cvt_pk_bf16_f32 v212, v0, v1
	v_cvt_pk_bf16_f32 v213, v2, v3
	global_store_dwordx2 v211, v[212:213], s[92:93] offset:256
	v_fmac_f32_e32 v216, v0, v0
	v_fmac_f32_e32 v216, v1, v1
	v_fmac_f32_e32 v216, v2, v2
	v_fmac_f32_e32 v216, v3, v3
	s_nop 1
	v_add_f32_dpp v221, v221, v221 row_ror:8 row_mask:0xf bank_mask:0xf
	v_add_f32_dpp v216, v216, v216 row_ror:8 row_mask:0xf bank_mask:0xf
	s_nop 0
	ds_bpermute_b32 v151, v148, v221
	ds_bpermute_b32 v136, v148, v216
	s_waitcnt lgkmcnt(0)
	v_add_f32_e32 v221, v221, v151
	v_add_f32_e32 v216, v216, v136
	s_nop 0
	ds_bpermute_b32 v151, v149, v221
	ds_bpermute_b32 v136, v149, v216
	s_waitcnt lgkmcnt(0)
	v_add_f32_e32 v221, v221, v151
	v_add_f32_e32 v216, v216, v136
	v_cmp_gt_u32_e32 vcc, 8, v217
	s_nop 1
	v_cndmask_b32_e32 v221, v216, v221, vcc
	v_cmp_eq_u32_e32 vcc, 0, v150
	s_and_saveexec_b64 s[98:99], vcc
	global_store_dword v220, v221, s[100:101]
	s_mov_b64 exec, s[98:99]
	s_and_b64 vcc, exec, s[12:13]
	s_mov_b64 s[12:13], -1
	s_cbranch_vccnz .LBB0_997
	s_andn2_b64 vcc, exec, s[26:27]
	s_cbranch_vccnz .LBB0_996
	s_barrier
	s_branch .LBB0_996

.LBB0_1286:
	v_lshrrev_b32_e32 v132, 6, v206
	v_and_b32_e32 v143, 63, v206
	v_lshrrev_b32_e32 v142, 2, v132
	v_and_b32_e32 v132, 3, v132
	v_lshlrev_b32_e32 v142, 6, v142
	v_lshrrev_b32_e32 v146, 4, v143
	v_and_b32_e32 v213, 15, v143
	v_xor_b32_e32 v144, 16, v143
	v_xor_b32_e32 v145, 32, v143
	v_lshlrev_b32_e32 v144, 2, v144
	v_lshlrev_b32_e32 v145, 2, v145
	s_lshl_b32 vcc_lo, s24, 8
	v_add_u32_e32 v142, vcc_lo, v142
	s_lshl_b32 vcc_lo, s20, 2
	v_add_u32_e32 v216, vcc_lo, v132
	v_add_u32_e32 v147, v142, v213
	v_lshlrev_b32_e32 v147, 6, v147
	v_lshl_add_u32 v216, v216, 2, v147
	v_lshlrev_b32_e32 v143, 5, v132
	v_lshrrev_b32_e32 v147, 3, v213
	v_lshl_add_u32 v147, v147, 2, v146
	v_lshl_add_u32 v143, v147, 2, v143
	s_lshl_b32 vcc_lo, s20, 8
	v_add_u32_e32 v143, vcc_lo, v143
	v_and_b32_e32 v147, 7, v213
	v_add_u32_e32 v142, v142, v147
	v_lshlrev_b32_e32 v148, 12, v142
	v_lshl_add_u32 v148, v143, 2, v148
	v_add_u32_e32 v149, 0x8000, v148
	v_lshlrev_b32_e32 v210, 11, v142
	v_lshl_add_u32 v210, v143, 1, v210
	v_add_u32_e32 v211, 0x4000, v210
	s_mov_b32 s86, s94
	s_mov_b32 s87, s95
	s_mov_b32 s88, s94
	s_mov_b32 s89, s95
	s_add_u32 s92, s96, 0x9e00000
	s_addc_u32 s93, s97, 0
	s_add_u32 s100, s96, 0x5000000
	s_addc_u32 s101, s97, 0
	global_load_dwordx4 v[160:163], v148, s[86:87]
	global_load_dwordx4 v[164:167], v149, s[86:87]
	global_load_dwordx4 v[168:171], v148, s[86:87] offset:512
	global_load_dwordx4 v[172:175], v149, s[86:87] offset:512
	s_add_u32 s86, s86, 0x10000
	s_addc_u32 s87, s87, 0
	global_load_dwordx4 v[176:179], v148, s[86:87]
	global_load_dwordx4 v[180:183], v149, s[86:87]
	global_load_dwordx4 v[184:187], v148, s[86:87] offset:512
	global_load_dwordx4 v[188:191], v149, s[86:87] offset:512
	s_add_u32 s86, s86, 0x10000
	s_addc_u32 s87, s87, 0
	global_load_dwordx4 v[192:195], v148, s[86:87]
	global_load_dwordx4 v[196:199], v149, s[86:87]
	global_load_dwordx4 v[200:203], v148, s[86:87] offset:512
	v_mov_b32_e32 v156, v120
	v_mov_b32_e32 v157, v121
	v_mov_b32_e32 v158, v122
	v_mov_b32_e32 v159, v123
	v_mov_b32_dpp v120, v124 row_ror:8 row_mask:0xf bank_mask:0x3
	v_mov_b32_dpp v121, v125 row_ror:8 row_mask:0xf bank_mask:0x3
	v_mov_b32_dpp v122, v126 row_ror:8 row_mask:0xf bank_mask:0x3
	v_mov_b32_dpp v123, v127 row_ror:8 row_mask:0xf bank_mask:0x3
	v_mov_b32_dpp v124, v156 row_ror:8 row_mask:0xf bank_mask:0xc
	v_mov_b32_dpp v125, v157 row_ror:8 row_mask:0xf bank_mask:0xc
	v_mov_b32_dpp v126, v158 row_ror:8 row_mask:0xf bank_mask:0xc
	v_mov_b32_dpp v127, v159 row_ror:8 row_mask:0xf bank_mask:0xc
	s_waitcnt vmcnt(10)
	v_add_f32_e32 v124, v124, v160
	v_add_f32_e32 v125, v125, v161
	v_add_f32_e32 v126, v126, v162
	v_add_f32_e32 v127, v127, v163
	global_store_dwordx4 v148, v[124:127], s[88:89]
	v_cvt_pk_bf16_f32 v160, v124, v125
	v_cvt_pk_bf16_f32 v161, v126, v127
	global_store_dwordx2 v210, v[160:161], s[92:93]
	v_mul_f32_e32 v217, v124, v124
	v_fmac_f32_e32 v217, v125, v125
	v_fmac_f32_e32 v217, v126, v126
	v_fmac_f32_e32 v217, v127, v127
	global_load_dwordx4 v[160:163], v149, s[86:87] offset:512
	s_add_u32 s86, s86, 0x10000
	s_addc_u32 s87, s87, 0
	global_load_dwordx4 v[124:127], v148, s[86:87]
	s_waitcnt vmcnt(13)
	v_add_f32_e32 v120, v120, v164
	v_add_f32_e32 v121, v121, v165
	v_add_f32_e32 v122, v122, v166
	v_add_f32_e32 v123, v123, v167
	global_store_dwordx4 v149, v[120:123], s[88:89]
	v_cvt_pk_bf16_f32 v164, v120, v121
	v_cvt_pk_bf16_f32 v165, v122, v123
	global_store_dwordx2 v211, v[164:165], s[92:93]
	v_mul_f32_e32 v212, v120, v120
	v_fmac_f32_e32 v212, v121, v121
	v_fmac_f32_e32 v212, v122, v122
	v_fmac_f32_e32 v212, v123, v123
	global_load_dwordx4 v[164:167], v149, s[86:87]
	global_load_dwordx4 v[120:123], v148, s[86:87] offset:512
	v_mov_b32_e32 v156, v112
	v_mov_b32_e32 v157, v113
	v_mov_b32_e32 v158, v114
	v_mov_b32_e32 v159, v115
	v_mov_b32_dpp v112, v116 row_ror:8 row_mask:0xf bank_mask:0x3
	v_mov_b32_dpp v113, v117 row_ror:8 row_mask:0xf bank_mask:0x3
	v_mov_b32_dpp v114, v118 row_ror:8 row_mask:0xf bank_mask:0x3
	v_mov_b32_dpp v115, v119 row_ror:8 row_mask:0xf bank_mask:0x3
	v_mov_b32_dpp v116, v156 row_ror:8 row_mask:0xf bank_mask:0xc
	v_mov_b32_dpp v117, v157 row_ror:8 row_mask:0xf bank_mask:0xc
	v_mov_b32_dpp v118, v158 row_ror:8 row_mask:0xf bank_mask:0xc
	v_mov_b32_dpp v119, v159 row_ror:8 row_mask:0xf bank_mask:0xc
	s_waitcnt vmcnt(16)
	v_add_f32_e32 v116, v116, v168
	v_add_f32_e32 v117, v117, v169
	v_add_f32_e32 v118, v118, v170
	v_add_f32_e32 v119, v119, v171
	global_store_dwordx4 v148, v[116:119], s[88:89] offset:512
	v_cvt_pk_bf16_f32 v168, v116, v117
	v_cvt_pk_bf16_f32 v169, v118, v119
	global_store_dwordx2 v210, v[168:169], s[92:93] offset:256
	v_fmac_f32_e32 v217, v116, v116
	v_fmac_f32_e32 v217, v117, v117
	v_fmac_f32_e32 v217, v118, v118
	v_fmac_f32_e32 v217, v119, v119
	global_load_dwordx4 v[168:171], v149, s[86:87] offset:512
	s_add_u32 s86, s86, 0x50000
	s_addc_u32 s87, s87, 0
	global_load_dwordx4 v[116:119], v148, s[86:87]
	s_waitcnt vmcnt(19)
	v_add_f32_e32 v112, v112, v172
	v_add_f32_e32 v113, v113, v173
	v_add_f32_e32 v114, v114, v174
	v_add_f32_e32 v115, v115, v175
	global_store_dwordx4 v149, v[112:115], s[88:89] offset:512
	v_cvt_pk_bf16_f32 v172, v112, v113
	v_cvt_pk_bf16_f32 v173, v114, v115
	global_store_dwordx2 v211, v[172:173], s[92:93] offset:256
	v_fmac_f32_e32 v212, v112, v112
	v_fmac_f32_e32 v212, v113, v113
	v_fmac_f32_e32 v212, v114, v114
	v_fmac_f32_e32 v212, v115, v115
	global_load_dwordx4 v[172:175], v149, s[86:87]
	global_load_dwordx4 v[112:115], v148, s[86:87] offset:512
	s_nop 1
	v_add_f32_dpp v217, v217, v217 row_ror:8 row_mask:0xf bank_mask:0xf
	v_add_f32_dpp v212, v212, v212 row_ror:8 row_mask:0xf bank_mask:0xf
	s_nop 0
	ds_bpermute_b32 v147, v144, v217
	ds_bpermute_b32 v132, v144, v212
	s_waitcnt lgkmcnt(0)
	v_add_f32_e32 v217, v217, v147
	v_add_f32_e32 v212, v212, v132
	s_nop 0
	ds_bpermute_b32 v147, v145, v217
	ds_bpermute_b32 v132, v145, v212
	s_waitcnt lgkmcnt(0)
	v_add_f32_e32 v217, v217, v147
	v_add_f32_e32 v212, v212, v132
	v_cmp_gt_u32_e32 vcc, 8, v213
	s_nop 1
	v_cndmask_b32_e32 v217, v212, v217, vcc
	v_cmp_eq_u32_e32 vcc, 0, v146
	s_and_saveexec_b64 s[98:99], vcc
	global_store_dword v216, v217, s[100:101]
	s_mov_b64 exec, s[98:99]
	s_add_u32 s88, s88, 0x10000
	s_addc_u32 s89, s89, 0
	s_add_u32 s92, s92, 0x8000
	s_addc_u32 s93, s93, 0
	s_add_u32 s100, s100, 0x400
	s_addc_u32 s101, s101, 0
	v_mov_b32_e32 v156, v104
	v_mov_b32_e32 v157, v105
	v_mov_b32_e32 v158, v106
	v_mov_b32_e32 v159, v107
	v_mov_b32_dpp v104, v108 row_ror:8 row_mask:0xf bank_mask:0x3
	v_mov_b32_dpp v105, v109 row_ror:8 row_mask:0xf bank_mask:0x3
	v_mov_b32_dpp v106, v110 row_ror:8 row_mask:0xf bank_mask:0x3
	v_mov_b32_dpp v107, v111 row_ror:8 row_mask:0xf bank_mask:0x3
	v_mov_b32_dpp v108, v156 row_ror:8 row_mask:0xf bank_mask:0xc
	v_mov_b32_dpp v109, v157 row_ror:8 row_mask:0xf bank_mask:0xc
	v_mov_b32_dpp v110, v158 row_ror:8 row_mask:0xf bank_mask:0xc
	v_mov_b32_dpp v111, v159 row_ror:8 row_mask:0xf bank_mask:0xc
	s_waitcnt vmcnt(23)
	v_add_f32_e32 v108, v108, v176
	v_add_f32_e32 v109, v109, v177
	v_add_f32_e32 v110, v110, v178
	v_add_f32_e32 v111, v111, v179
	global_store_dwordx4 v148, v[108:111], s[88:89]
	v_cvt_pk_bf16_f32 v176, v108, v109
	v_cvt_pk_bf16_f32 v177, v110, v111
	global_store_dwordx2 v210, v[176:177], s[92:93]
	v_mul_f32_e32 v217, v108, v108
	v_fmac_f32_e32 v217, v109, v109
	v_fmac_f32_e32 v217, v110, v110
	v_fmac_f32_e32 v217, v111, v111
	global_load_dwordx4 v[176:179], v149, s[86:87] offset:512
	s_add_u32 s86, s86, 0x10000
	s_addc_u32 s87, s87, 0
	global_load_dwordx4 v[108:111], v148, s[86:87]
	s_waitcnt vmcnt(26)
	v_add_f32_e32 v104, v104, v180
	v_add_f32_e32 v105, v105, v181
	v_add_f32_e32 v106, v106, v182
	v_add_f32_e32 v107, v107, v183
	global_store_dwordx4 v149, v[104:107], s[88:89]
	v_cvt_pk_bf16_f32 v180, v104, v105
	v_cvt_pk_bf16_f32 v181, v106, v107
	global_store_dwordx2 v211, v[180:181], s[92:93]
	v_mul_f32_e32 v212, v104, v104
	v_fmac_f32_e32 v212, v105, v105
	v_fmac_f32_e32 v212, v106, v106
	v_fmac_f32_e32 v212, v107, v107
	global_load_dwordx4 v[180:183], v149, s[86:87]
	global_load_dwordx4 v[104:107], v148, s[86:87] offset:512
	v_mov_b32_e32 v156, v96
	v_mov_b32_e32 v157, v97
	v_mov_b32_e32 v158, v98
	v_mov_b32_e32 v159, v99
	v_mov_b32_dpp v96, v100 row_ror:8 row_mask:0xf bank_mask:0x3
	v_mov_b32_dpp v97, v101 row_ror:8 row_mask:0xf bank_mask:0x3
	v_mov_b32_dpp v98, v102 row_ror:8 row_mask:0xf bank_mask:0x3
	v_mov_b32_dpp v99, v103 row_ror:8 row_mask:0xf bank_mask:0x3
	v_mov_b32_dpp v100, v156 row_ror:8 row_mask:0xf bank_mask:0xc
	v_mov_b32_dpp v101, v157 row_ror:8 row_mask:0xf bank_mask:0xc
	v_mov_b32_dpp v102, v158 row_ror:8 row_mask:0xf bank_mask:0xc
	v_mov_b32_dpp v103, v159 row_ror:8 row_mask:0xf bank_mask:0xc
	s_waitcnt vmcnt(29)
	v_add_f32_e32 v100, v100, v184
	v_add_f32_e32 v101, v101, v185
	v_add_f32_e32 v102, v102, v186
	v_add_f32_e32 v103, v103, v187
	global_store_dwordx4 v148, v[100:103], s[88:89] offset:512
	v_cvt_pk_bf16_f32 v184, v100, v101
	v_cvt_pk_bf16_f32 v185, v102, v103
	global_store_dwordx2 v210, v[184:185], s[92:93] offset:256
	v_fmac_f32_e32 v217, v100, v100
	v_fmac_f32_e32 v217, v101, v101
	v_fmac_f32_e32 v217, v102, v102
	v_fmac_f32_e32 v217, v103, v103
	global_load_dwordx4 v[184:187], v149, s[86:87] offset:512
	s_add_u32 s86, s86, 0x10000
	s_addc_u32 s87, s87, 0
	global_load_dwordx4 v[100:103], v148, s[86:87]
	s_waitcnt vmcnt(32)
	v_add_f32_e32 v96, v96, v188
	v_add_f32_e32 v97, v97, v189
	v_add_f32_e32 v98, v98, v190
	v_add_f32_e32 v99, v99, v191
	global_store_dwordx4 v149, v[96:99], s[88:89] offset:512
	v_cvt_pk_bf16_f32 v188, v96, v97
	v_cvt_pk_bf16_f32 v189, v98, v99
	global_store_dwordx2 v211, v[188:189], s[92:93] offset:256
	v_fmac_f32_e32 v212, v96, v96
	v_fmac_f32_e32 v212, v97, v97
	v_fmac_f32_e32 v212, v98, v98
	v_fmac_f32_e32 v212, v99, v99
	global_load_dwordx4 v[188:191], v149, s[86:87]
	global_load_dwordx4 v[96:99], v148, s[86:87] offset:512
	s_nop 1
	v_add_f32_dpp v217, v217, v217 row_ror:8 row_mask:0xf bank_mask:0xf
	v_add_f32_dpp v212, v212, v212 row_ror:8 row_mask:0xf bank_mask:0xf
	s_nop 0
	ds_bpermute_b32 v147, v144, v217
	ds_bpermute_b32 v132, v144, v212
	s_waitcnt lgkmcnt(0)
	v_add_f32_e32 v217, v217, v147
	v_add_f32_e32 v212, v212, v132
	s_nop 0
	ds_bpermute_b32 v147, v145, v217
	ds_bpermute_b32 v132, v145, v212
	s_waitcnt lgkmcnt(0)
	v_add_f32_e32 v217, v217, v147
	v_add_f32_e32 v212, v212, v132
	v_cmp_gt_u32_e32 vcc, 8, v213
	s_nop 1
	v_cndmask_b32_e32 v217, v212, v217, vcc
	v_cmp_eq_u32_e32 vcc, 0, v146
	s_and_saveexec_b64 s[98:99], vcc
	global_store_dword v216, v217, s[100:101]
	s_mov_b64 exec, s[98:99]
	s_add_u32 s88, s88, 0x10000
	s_addc_u32 s89, s89, 0
	s_add_u32 s92, s92, 0x8000
	s_addc_u32 s93, s93, 0
	s_add_u32 s100, s100, 0x400
	s_addc_u32 s101, s101, 0
	v_mov_b32_e32 v156, v88
	v_mov_b32_e32 v157, v89
	v_mov_b32_e32 v158, v90
	v_mov_b32_e32 v159, v91
	v_mov_b32_dpp v88, v92 row_ror:8 row_mask:0xf bank_mask:0x3
	v_mov_b32_dpp v89, v93 row_ror:8 row_mask:0xf bank_mask:0x3
	v_mov_b32_dpp v90, v94 row_ror:8 row_mask:0xf bank_mask:0x3
	v_mov_b32_dpp v91, v95 row_ror:8 row_mask:0xf bank_mask:0x3
	v_mov_b32_dpp v92, v156 row_ror:8 row_mask:0xf bank_mask:0xc
	v_mov_b32_dpp v93, v157 row_ror:8 row_mask:0xf bank_mask:0xc
	v_mov_b32_dpp v94, v158 row_ror:8 row_mask:0xf bank_mask:0xc
	v_mov_b32_dpp v95, v159 row_ror:8 row_mask:0xf bank_mask:0xc
	s_waitcnt vmcnt(36)
	v_add_f32_e32 v92, v92, v192
	v_add_f32_e32 v93, v93, v193
	v_add_f32_e32 v94, v94, v194
	v_add_f32_e32 v95, v95, v195
	global_store_dwordx4 v148, v[92:95], s[88:89]
	v_cvt_pk_bf16_f32 v192, v92, v93
	v_cvt_pk_bf16_f32 v193, v94, v95
	global_store_dwordx2 v210, v[192:193], s[92:93]
	v_mul_f32_e32 v217, v92, v92
	v_fmac_f32_e32 v217, v93, v93
	v_fmac_f32_e32 v217, v94, v94
	v_fmac_f32_e32 v217, v95, v95
	global_load_dwordx4 v[192:195], v149, s[86:87] offset:512
	s_add_u32 s86, s86, 0x10000
	s_addc_u32 s87, s87, 0
	global_load_dwordx4 v[92:95], v148, s[86:87]
	s_waitcnt vmcnt(39)
	v_add_f32_e32 v88, v88, v196
	v_add_f32_e32 v89, v89, v197
	v_add_f32_e32 v90, v90, v198
	v_add_f32_e32 v91, v91, v199
	global_store_dwordx4 v149, v[88:91], s[88:89]
	v_cvt_pk_bf16_f32 v196, v88, v89
	v_cvt_pk_bf16_f32 v197, v90, v91
	global_store_dwordx2 v211, v[196:197], s[92:93]
	v_mul_f32_e32 v212, v88, v88
	v_fmac_f32_e32 v212, v89, v89
	v_fmac_f32_e32 v212, v90, v90
	v_fmac_f32_e32 v212, v91, v91
	global_load_dwordx4 v[196:199], v149, s[86:87]
	global_load_dwordx4 v[88:91], v148, s[86:87] offset:512
	v_mov_b32_e32 v156, v80
	v_mov_b32_e32 v157, v81
	v_mov_b32_e32 v158, v82
	v_mov_b32_e32 v159, v83
	v_mov_b32_dpp v80, v84 row_ror:8 row_mask:0xf bank_mask:0x3
	v_mov_b32_dpp v81, v85 row_ror:8 row_mask:0xf bank_mask:0x3
	v_mov_b32_dpp v82, v86 row_ror:8 row_mask:0xf bank_mask:0x3
	v_mov_b32_dpp v83, v87 row_ror:8 row_mask:0xf bank_mask:0x3
	v_mov_b32_dpp v84, v156 row_ror:8 row_mask:0xf bank_mask:0xc
	v_mov_b32_dpp v85, v157 row_ror:8 row_mask:0xf bank_mask:0xc
	v_mov_b32_dpp v86, v158 row_ror:8 row_mask:0xf bank_mask:0xc
	v_mov_b32_dpp v87, v159 row_ror:8 row_mask:0xf bank_mask:0xc
	s_waitcnt vmcnt(42)
	v_add_f32_e32 v84, v84, v200
	v_add_f32_e32 v85, v85, v201
	v_add_f32_e32 v86, v86, v202
	v_add_f32_e32 v87, v87, v203
	global_store_dwordx4 v148, v[84:87], s[88:89] offset:512
	v_cvt_pk_bf16_f32 v200, v84, v85
	v_cvt_pk_bf16_f32 v201, v86, v87
	global_store_dwordx2 v210, v[200:201], s[92:93] offset:256
	v_fmac_f32_e32 v217, v84, v84
	v_fmac_f32_e32 v217, v85, v85
	v_fmac_f32_e32 v217, v86, v86
	v_fmac_f32_e32 v217, v87, v87
	global_load_dwordx4 v[200:203], v149, s[86:87] offset:512
	s_waitcnt vmcnt(42)
	v_add_f32_e32 v80, v80, v160
	v_add_f32_e32 v81, v81, v161
	v_add_f32_e32 v82, v82, v162
	v_add_f32_e32 v83, v83, v163
	global_store_dwordx4 v149, v[80:83], s[88:89] offset:512
	v_cvt_pk_bf16_f32 v160, v80, v81
	v_cvt_pk_bf16_f32 v161, v82, v83
	global_store_dwordx2 v211, v[160:161], s[92:93] offset:256
	v_fmac_f32_e32 v212, v80, v80
	v_fmac_f32_e32 v212, v81, v81
	v_fmac_f32_e32 v212, v82, v82
	v_fmac_f32_e32 v212, v83, v83
	s_nop 1
	v_add_f32_dpp v217, v217, v217 row_ror:8 row_mask:0xf bank_mask:0xf
	v_add_f32_dpp v212, v212, v212 row_ror:8 row_mask:0xf bank_mask:0xf
	s_nop 0
	ds_bpermute_b32 v147, v144, v217
	ds_bpermute_b32 v132, v144, v212
	s_waitcnt lgkmcnt(0)
	v_add_f32_e32 v217, v217, v147
	v_add_f32_e32 v212, v212, v132
	s_nop 0
	ds_bpermute_b32 v147, v145, v217
	ds_bpermute_b32 v132, v145, v212
	s_waitcnt lgkmcnt(0)
	v_add_f32_e32 v217, v217, v147
	v_add_f32_e32 v212, v212, v132
	v_cmp_gt_u32_e32 vcc, 8, v213
	s_nop 1
	v_cndmask_b32_e32 v217, v212, v217, vcc
	v_cmp_eq_u32_e32 vcc, 0, v146
	s_and_saveexec_b64 s[98:99], vcc
	global_store_dword v216, v217, s[100:101]
	s_mov_b64 exec, s[98:99]
	s_add_u32 s88, s88, 0x10000
	s_addc_u32 s89, s89, 0
	s_add_u32 s92, s92, 0x8000
	s_addc_u32 s93, s93, 0
	s_add_u32 s100, s100, 0x400
	s_addc_u32 s101, s101, 0
	v_mov_b32_e32 v156, v72
	v_mov_b32_e32 v157, v73
	v_mov_b32_e32 v158, v74
	v_mov_b32_e32 v159, v75
	v_mov_b32_dpp v72, v76 row_ror:8 row_mask:0xf bank_mask:0x3
	v_mov_b32_dpp v73, v77 row_ror:8 row_mask:0xf bank_mask:0x3
	v_mov_b32_dpp v74, v78 row_ror:8 row_mask:0xf bank_mask:0x3
	v_mov_b32_dpp v75, v79 row_ror:8 row_mask:0xf bank_mask:0x3
	v_mov_b32_dpp v76, v156 row_ror:8 row_mask:0xf bank_mask:0xc
	v_mov_b32_dpp v77, v157 row_ror:8 row_mask:0xf bank_mask:0xc
	v_mov_b32_dpp v78, v158 row_ror:8 row_mask:0xf bank_mask:0xc
	v_mov_b32_dpp v79, v159 row_ror:8 row_mask:0xf bank_mask:0xc
	s_waitcnt vmcnt(44)
	v_add_f32_e32 v76, v76, v124
	v_add_f32_e32 v77, v77, v125
	v_add_f32_e32 v78, v78, v126
	v_add_f32_e32 v79, v79, v127
	global_store_dwordx4 v148, v[76:79], s[88:89]
	v_cvt_pk_bf16_f32 v124, v76, v77
	v_cvt_pk_bf16_f32 v125, v78, v79
	global_store_dwordx2 v210, v[124:125], s[92:93]
	v_mul_f32_e32 v217, v76, v76
	v_fmac_f32_e32 v217, v77, v77
	v_fmac_f32_e32 v217, v78, v78
	v_fmac_f32_e32 v217, v79, v79
	s_waitcnt vmcnt(43)
	v_add_f32_e32 v72, v72, v164
	v_add_f32_e32 v73, v73, v165
	v_add_f32_e32 v74, v74, v166
	v_add_f32_e32 v75, v75, v167
	global_store_dwordx4 v149, v[72:75], s[88:89]
	v_cvt_pk_bf16_f32 v164, v72, v73
	v_cvt_pk_bf16_f32 v165, v74, v75
	global_store_dwordx2 v211, v[164:165], s[92:93]
	v_mul_f32_e32 v212, v72, v72
	v_fmac_f32_e32 v212, v73, v73
	v_fmac_f32_e32 v212, v74, v74
	v_fmac_f32_e32 v212, v75, v75
	v_mov_b32_e32 v156, v64
	v_mov_b32_e32 v157, v65
	v_mov_b32_e32 v158, v66
	v_mov_b32_e32 v159, v67
	v_mov_b32_dpp v64, v68 row_ror:8 row_mask:0xf bank_mask:0x3
	v_mov_b32_dpp v65, v69 row_ror:8 row_mask:0xf bank_mask:0x3
	v_mov_b32_dpp v66, v70 row_ror:8 row_mask:0xf bank_mask:0x3
	v_mov_b32_dpp v67, v71 row_ror:8 row_mask:0xf bank_mask:0x3
	v_mov_b32_dpp v68, v156 row_ror:8 row_mask:0xf bank_mask:0xc
	v_mov_b32_dpp v69, v157 row_ror:8 row_mask:0xf bank_mask:0xc
	v_mov_b32_dpp v70, v158 row_ror:8 row_mask:0xf bank_mask:0xc
	v_mov_b32_dpp v71, v159 row_ror:8 row_mask:0xf bank_mask:0xc
	s_waitcnt vmcnt(44)
	v_add_f32_e32 v68, v68, v120
	v_add_f32_e32 v69, v69, v121
	v_add_f32_e32 v70, v70, v122
	v_add_f32_e32 v71, v71, v123
	global_store_dwordx4 v148, v[68:71], s[88:89] offset:512
	v_cvt_pk_bf16_f32 v120, v68, v69
	v_cvt_pk_bf16_f32 v121, v70, v71
	global_store_dwordx2 v210, v[120:121], s[92:93] offset:256
	v_fmac_f32_e32 v217, v68, v68
	v_fmac_f32_e32 v217, v69, v69
	v_fmac_f32_e32 v217, v70, v70
	v_fmac_f32_e32 v217, v71, v71
	s_waitcnt vmcnt(43)
	v_add_f32_e32 v64, v64, v168
	v_add_f32_e32 v65, v65, v169
	v_add_f32_e32 v66, v66, v170
	v_add_f32_e32 v67, v67, v171
	global_store_dwordx4 v149, v[64:67], s[88:89] offset:512
	v_cvt_pk_bf16_f32 v168, v64, v65
	v_cvt_pk_bf16_f32 v169, v66, v67
	global_store_dwordx2 v211, v[168:169], s[92:93] offset:256
	v_fmac_f32_e32 v212, v64, v64
	v_fmac_f32_e32 v212, v65, v65
	v_fmac_f32_e32 v212, v66, v66
	v_fmac_f32_e32 v212, v67, v67
	s_nop 1
	v_add_f32_dpp v217, v217, v217 row_ror:8 row_mask:0xf bank_mask:0xf
	v_add_f32_dpp v212, v212, v212 row_ror:8 row_mask:0xf bank_mask:0xf
	s_nop 0
	ds_bpermute_b32 v147, v144, v217
	ds_bpermute_b32 v132, v144, v212
	s_waitcnt lgkmcnt(0)
	v_add_f32_e32 v217, v217, v147
	v_add_f32_e32 v212, v212, v132
	s_nop 0
	ds_bpermute_b32 v147, v145, v217
	ds_bpermute_b32 v132, v145, v212
	s_waitcnt lgkmcnt(0)
	v_add_f32_e32 v217, v217, v147
	v_add_f32_e32 v212, v212, v132
	v_cmp_gt_u32_e32 vcc, 8, v213
	s_nop 1
	v_cndmask_b32_e32 v217, v212, v217, vcc
	v_cmp_eq_u32_e32 vcc, 0, v146
	s_and_saveexec_b64 s[98:99], vcc
	global_store_dword v216, v217, s[100:101]
	s_mov_b64 exec, s[98:99]
	s_add_u32 s88, s88, 0x50000
	s_addc_u32 s89, s89, 0
	s_add_u32 s92, s92, 0x28000
	s_addc_u32 s93, s93, 0
	s_add_u32 s100, s100, 0x1400
	s_addc_u32 s101, s101, 0
	v_mov_b32_e32 v156, v56
	v_mov_b32_e32 v157, v57
	v_mov_b32_e32 v158, v58
	v_mov_b32_e32 v159, v59
	v_mov_b32_dpp v56, v60 row_ror:8 row_mask:0xf bank_mask:0x3
	v_mov_b32_dpp v57, v61 row_ror:8 row_mask:0xf bank_mask:0x3
	v_mov_b32_dpp v58, v62 row_ror:8 row_mask:0xf bank_mask:0x3
	v_mov_b32_dpp v59, v63 row_ror:8 row_mask:0xf bank_mask:0x3
	v_mov_b32_dpp v60, v156 row_ror:8 row_mask:0xf bank_mask:0xc
	v_mov_b32_dpp v61, v157 row_ror:8 row_mask:0xf bank_mask:0xc
	v_mov_b32_dpp v62, v158 row_ror:8 row_mask:0xf bank_mask:0xc
	v_mov_b32_dpp v63, v159 row_ror:8 row_mask:0xf bank_mask:0xc
	s_waitcnt vmcnt(45)
	v_add_f32_e32 v60, v60, v116
	v_add_f32_e32 v61, v61, v117
	v_add_f32_e32 v62, v62, v118
	v_add_f32_e32 v63, v63, v119
	global_store_dwordx4 v148, v[60:63], s[88:89]
	v_cvt_pk_bf16_f32 v116, v60, v61
	v_cvt_pk_bf16_f32 v117, v62, v63
	global_store_dwordx2 v210, v[116:117], s[92:93]
	v_mul_f32_e32 v217, v60, v60
	v_fmac_f32_e32 v217, v61, v61
	v_fmac_f32_e32 v217, v62, v62
	v_fmac_f32_e32 v217, v63, v63
	s_waitcnt vmcnt(44)
	v_add_f32_e32 v56, v56, v172
	v_add_f32_e32 v57, v57, v173
	v_add_f32_e32 v58, v58, v174
	v_add_f32_e32 v59, v59, v175
	global_store_dwordx4 v149, v[56:59], s[88:89]
	v_cvt_pk_bf16_f32 v172, v56, v57
	v_cvt_pk_bf16_f32 v173, v58, v59
	global_store_dwordx2 v211, v[172:173], s[92:93]
	v_mul_f32_e32 v212, v56, v56
	v_fmac_f32_e32 v212, v57, v57
	v_fmac_f32_e32 v212, v58, v58
	v_fmac_f32_e32 v212, v59, v59
	v_mov_b32_e32 v156, v48
	v_mov_b32_e32 v157, v49
	v_mov_b32_e32 v158, v50
	v_mov_b32_e32 v159, v51
	v_mov_b32_dpp v48, v52 row_ror:8 row_mask:0xf bank_mask:0x3
	v_mov_b32_dpp v49, v53 row_ror:8 row_mask:0xf bank_mask:0x3
	v_mov_b32_dpp v50, v54 row_ror:8 row_mask:0xf bank_mask:0x3
	v_mov_b32_dpp v51, v55 row_ror:8 row_mask:0xf bank_mask:0x3
	v_mov_b32_dpp v52, v156 row_ror:8 row_mask:0xf bank_mask:0xc
	v_mov_b32_dpp v53, v157 row_ror:8 row_mask:0xf bank_mask:0xc
	v_mov_b32_dpp v54, v158 row_ror:8 row_mask:0xf bank_mask:0xc
	v_mov_b32_dpp v55, v159 row_ror:8 row_mask:0xf bank_mask:0xc
	s_waitcnt vmcnt(45)
	v_add_f32_e32 v52, v52, v112
	v_add_f32_e32 v53, v53, v113
	v_add_f32_e32 v54, v54, v114
	v_add_f32_e32 v55, v55, v115
	global_store_dwordx4 v148, v[52:55], s[88:89] offset:512
	v_cvt_pk_bf16_f32 v112, v52, v53
	v_cvt_pk_bf16_f32 v113, v54, v55
	global_store_dwordx2 v210, v[112:113], s[92:93] offset:256
	v_fmac_f32_e32 v217, v52, v52
	v_fmac_f32_e32 v217, v53, v53
	v_fmac_f32_e32 v217, v54, v54
	v_fmac_f32_e32 v217, v55, v55
	s_waitcnt vmcnt(43)
	v_add_f32_e32 v48, v48, v176
	v_add_f32_e32 v49, v49, v177
	v_add_f32_e32 v50, v50, v178
	v_add_f32_e32 v51, v51, v179
	global_store_dwordx4 v149, v[48:51], s[88:89] offset:512
	v_cvt_pk_bf16_f32 v176, v48, v49
	v_cvt_pk_bf16_f32 v177, v50, v51
	global_store_dwordx2 v211, v[176:177], s[92:93] offset:256
	v_fmac_f32_e32 v212, v48, v48
	v_fmac_f32_e32 v212, v49, v49
	v_fmac_f32_e32 v212, v50, v50
	v_fmac_f32_e32 v212, v51, v51
	s_nop 1
	v_add_f32_dpp v217, v217, v217 row_ror:8 row_mask:0xf bank_mask:0xf
	v_add_f32_dpp v212, v212, v212 row_ror:8 row_mask:0xf bank_mask:0xf
	s_nop 0
	ds_bpermute_b32 v147, v144, v217
	ds_bpermute_b32 v132, v144, v212
	s_waitcnt lgkmcnt(0)
	v_add_f32_e32 v217, v217, v147
	v_add_f32_e32 v212, v212, v132
	s_nop 0
	ds_bpermute_b32 v147, v145, v217
	ds_bpermute_b32 v132, v145, v212
	s_waitcnt lgkmcnt(0)
	v_add_f32_e32 v217, v217, v147
	v_add_f32_e32 v212, v212, v132
	v_cmp_gt_u32_e32 vcc, 8, v213
	s_nop 1
	v_cndmask_b32_e32 v217, v212, v217, vcc
	v_cmp_eq_u32_e32 vcc, 0, v146
	s_and_saveexec_b64 s[98:99], vcc
	global_store_dword v216, v217, s[100:101]
	s_mov_b64 exec, s[98:99]
	s_add_u32 s88, s88, 0x10000
	s_addc_u32 s89, s89, 0
	s_add_u32 s92, s92, 0x8000
	s_addc_u32 s93, s93, 0
	s_add_u32 s100, s100, 0x400
	s_addc_u32 s101, s101, 0
	v_mov_b32_e32 v156, v40
	v_mov_b32_e32 v157, v41
	v_mov_b32_e32 v158, v42
	v_mov_b32_e32 v159, v43
	v_mov_b32_dpp v40, v44 row_ror:8 row_mask:0xf bank_mask:0x3
	v_mov_b32_dpp v41, v45 row_ror:8 row_mask:0xf bank_mask:0x3
	v_mov_b32_dpp v42, v46 row_ror:8 row_mask:0xf bank_mask:0x3
	v_mov_b32_dpp v43, v47 row_ror:8 row_mask:0xf bank_mask:0x3
	v_mov_b32_dpp v44, v156 row_ror:8 row_mask:0xf bank_mask:0xc
	v_mov_b32_dpp v45, v157 row_ror:8 row_mask:0xf bank_mask:0xc
	v_mov_b32_dpp v46, v158 row_ror:8 row_mask:0xf bank_mask:0xc
	v_mov_b32_dpp v47, v159 row_ror:8 row_mask:0xf bank_mask:0xc
	s_waitcnt vmcnt(45)
	v_add_f32_e32 v44, v44, v108
	v_add_f32_e32 v45, v45, v109
	v_add_f32_e32 v46, v46, v110
	v_add_f32_e32 v47, v47, v111
	global_store_dwordx4 v148, v[44:47], s[88:89]
	v_cvt_pk_bf16_f32 v108, v44, v45
	v_cvt_pk_bf16_f32 v109, v46, v47
	global_store_dwordx2 v210, v[108:109], s[92:93]
	v_mul_f32_e32 v217, v44, v44
	v_fmac_f32_e32 v217, v45, v45
	v_fmac_f32_e32 v217, v46, v46
	v_fmac_f32_e32 v217, v47, v47
	s_waitcnt vmcnt(44)
	v_add_f32_e32 v40, v40, v180
	v_add_f32_e32 v41, v41, v181
	v_add_f32_e32 v42, v42, v182
	v_add_f32_e32 v43, v43, v183
	global_store_dwordx4 v149, v[40:43], s[88:89]
	v_cvt_pk_bf16_f32 v180, v40, v41
	v_cvt_pk_bf16_f32 v181, v42, v43
	global_store_dwordx2 v211, v[180:181], s[92:93]
	v_mul_f32_e32 v212, v40, v40
	v_fmac_f32_e32 v212, v41, v41
	v_fmac_f32_e32 v212, v42, v42
	v_fmac_f32_e32 v212, v43, v43
	v_mov_b32_e32 v156, v32
	v_mov_b32_e32 v157, v33
	v_mov_b32_e32 v158, v34
	v_mov_b32_e32 v159, v35
	v_mov_b32_dpp v32, v36 row_ror:8 row_mask:0xf bank_mask:0x3
	v_mov_b32_dpp v33, v37 row_ror:8 row_mask:0xf bank_mask:0x3
	v_mov_b32_dpp v34, v38 row_ror:8 row_mask:0xf bank_mask:0x3
	v_mov_b32_dpp v35, v39 row_ror:8 row_mask:0xf bank_mask:0x3
	v_mov_b32_dpp v36, v156 row_ror:8 row_mask:0xf bank_mask:0xc
	v_mov_b32_dpp v37, v157 row_ror:8 row_mask:0xf bank_mask:0xc
	v_mov_b32_dpp v38, v158 row_ror:8 row_mask:0xf bank_mask:0xc
	v_mov_b32_dpp v39, v159 row_ror:8 row_mask:0xf bank_mask:0xc
	s_waitcnt vmcnt(45)
	v_add_f32_e32 v36, v36, v104
	v_add_f32_e32 v37, v37, v105
	v_add_f32_e32 v38, v38, v106
	v_add_f32_e32 v39, v39, v107
	global_store_dwordx4 v148, v[36:39], s[88:89] offset:512
	v_cvt_pk_bf16_f32 v104, v36, v37
	v_cvt_pk_bf16_f32 v105, v38, v39
	global_store_dwordx2 v210, v[104:105], s[92:93] offset:256
	v_fmac_f32_e32 v217, v36, v36
	v_fmac_f32_e32 v217, v37, v37
	v_fmac_f32_e32 v217, v38, v38
	v_fmac_f32_e32 v217, v39, v39
	s_waitcnt vmcnt(44)
	v_add_f32_e32 v32, v32, v184
	v_add_f32_e32 v33, v33, v185
	v_add_f32_e32 v34, v34, v186
	v_add_f32_e32 v35, v35, v187
	global_store_dwordx4 v149, v[32:35], s[88:89] offset:512
	v_cvt_pk_bf16_f32 v184, v32, v33
	v_cvt_pk_bf16_f32 v185, v34, v35
	global_store_dwordx2 v211, v[184:185], s[92:93] offset:256
	v_fmac_f32_e32 v212, v32, v32
	v_fmac_f32_e32 v212, v33, v33
	v_fmac_f32_e32 v212, v34, v34
	v_fmac_f32_e32 v212, v35, v35
	s_nop 1
	v_add_f32_dpp v217, v217, v217 row_ror:8 row_mask:0xf bank_mask:0xf
	v_add_f32_dpp v212, v212, v212 row_ror:8 row_mask:0xf bank_mask:0xf
	s_nop 0
	ds_bpermute_b32 v147, v144, v217
	ds_bpermute_b32 v132, v144, v212
	s_waitcnt lgkmcnt(0)
	v_add_f32_e32 v217, v217, v147
	v_add_f32_e32 v212, v212, v132
	s_nop 0
	ds_bpermute_b32 v147, v145, v217
	ds_bpermute_b32 v132, v145, v212
	s_waitcnt lgkmcnt(0)
	v_add_f32_e32 v217, v217, v147
	v_add_f32_e32 v212, v212, v132
	v_cmp_gt_u32_e32 vcc, 8, v213
	s_nop 1
	v_cndmask_b32_e32 v217, v212, v217, vcc
	v_cmp_eq_u32_e32 vcc, 0, v146
	s_and_saveexec_b64 s[98:99], vcc
	global_store_dword v216, v217, s[100:101]
	s_mov_b64 exec, s[98:99]
	s_add_u32 s88, s88, 0x10000
	s_addc_u32 s89, s89, 0
	s_add_u32 s92, s92, 0x8000
	s_addc_u32 s93, s93, 0
	s_add_u32 s100, s100, 0x400
	s_addc_u32 s101, s101, 0
	v_mov_b32_e32 v156, v24
	v_mov_b32_e32 v157, v25
	v_mov_b32_e32 v158, v26
	v_mov_b32_e32 v159, v27
	v_mov_b32_dpp v24, v28 row_ror:8 row_mask:0xf bank_mask:0x3
	v_mov_b32_dpp v25, v29 row_ror:8 row_mask:0xf bank_mask:0x3
	v_mov_b32_dpp v26, v30 row_ror:8 row_mask:0xf bank_mask:0x3
	v_mov_b32_dpp v27, v31 row_ror:8 row_mask:0xf bank_mask:0x3
	v_mov_b32_dpp v28, v156 row_ror:8 row_mask:0xf bank_mask:0xc
	v_mov_b32_dpp v29, v157 row_ror:8 row_mask:0xf bank_mask:0xc
	v_mov_b32_dpp v30, v158 row_ror:8 row_mask:0xf bank_mask:0xc
	v_mov_b32_dpp v31, v159 row_ror:8 row_mask:0xf bank_mask:0xc
	s_waitcnt vmcnt(46)
	v_add_f32_e32 v28, v28, v100
	v_add_f32_e32 v29, v29, v101
	v_add_f32_e32 v30, v30, v102
	v_add_f32_e32 v31, v31, v103
	global_store_dwordx4 v148, v[28:31], s[88:89]
	v_cvt_pk_bf16_f32 v100, v28, v29
	v_cvt_pk_bf16_f32 v101, v30, v31
	global_store_dwordx2 v210, v[100:101], s[92:93]
	v_mul_f32_e32 v217, v28, v28
	v_fmac_f32_e32 v217, v29, v29
	v_fmac_f32_e32 v217, v30, v30
	v_fmac_f32_e32 v217, v31, v31
	s_waitcnt vmcnt(45)
	v_add_f32_e32 v24, v24, v188
	v_add_f32_e32 v25, v25, v189
	v_add_f32_e32 v26, v26, v190
	v_add_f32_e32 v27, v27, v191
	global_store_dwordx4 v149, v[24:27], s[88:89]
	v_cvt_pk_bf16_f32 v188, v24, v25
	v_cvt_pk_bf16_f32 v189, v26, v27
	global_store_dwordx2 v211, v[188:189], s[92:93]
	v_mul_f32_e32 v212, v24, v24
	v_fmac_f32_e32 v212, v25, v25
	v_fmac_f32_e32 v212, v26, v26
	v_fmac_f32_e32 v212, v27, v27
	v_mov_b32_e32 v156, v16
	v_mov_b32_e32 v157, v17
	v_mov_b32_e32 v158, v18
	v_mov_b32_e32 v159, v19
	v_mov_b32_dpp v16, v20 row_ror:8 row_mask:0xf bank_mask:0x3
	v_mov_b32_dpp v17, v21 row_ror:8 row_mask:0xf bank_mask:0x3
	v_mov_b32_dpp v18, v22 row_ror:8 row_mask:0xf bank_mask:0x3
	v_mov_b32_dpp v19, v23 row_ror:8 row_mask:0xf bank_mask:0x3
	v_mov_b32_dpp v20, v156 row_ror:8 row_mask:0xf bank_mask:0xc
	v_mov_b32_dpp v21, v157 row_ror:8 row_mask:0xf bank_mask:0xc
	v_mov_b32_dpp v22, v158 row_ror:8 row_mask:0xf bank_mask:0xc
	v_mov_b32_dpp v23, v159 row_ror:8 row_mask:0xf bank_mask:0xc
	s_waitcnt vmcnt(46)
	v_add_f32_e32 v20, v20, v96
	v_add_f32_e32 v21, v21, v97
	v_add_f32_e32 v22, v22, v98
	v_add_f32_e32 v23, v23, v99
	global_store_dwordx4 v148, v[20:23], s[88:89] offset:512
	v_cvt_pk_bf16_f32 v96, v20, v21
	v_cvt_pk_bf16_f32 v97, v22, v23
	global_store_dwordx2 v210, v[96:97], s[92:93] offset:256
	v_fmac_f32_e32 v217, v20, v20
	v_fmac_f32_e32 v217, v21, v21
	v_fmac_f32_e32 v217, v22, v22
	v_fmac_f32_e32 v217, v23, v23
	s_waitcnt vmcnt(44)
	v_add_f32_e32 v16, v16, v192
	v_add_f32_e32 v17, v17, v193
	v_add_f32_e32 v18, v18, v194
	v_add_f32_e32 v19, v19, v195
	global_store_dwordx4 v149, v[16:19], s[88:89] offset:512
	v_cvt_pk_bf16_f32 v192, v16, v17
	v_cvt_pk_bf16_f32 v193, v18, v19
	global_store_dwordx2 v211, v[192:193], s[92:93] offset:256
	v_fmac_f32_e32 v212, v16, v16
	v_fmac_f32_e32 v212, v17, v17
	v_fmac_f32_e32 v212, v18, v18
	v_fmac_f32_e32 v212, v19, v19
	s_nop 1
	v_add_f32_dpp v217, v217, v217 row_ror:8 row_mask:0xf bank_mask:0xf
	v_add_f32_dpp v212, v212, v212 row_ror:8 row_mask:0xf bank_mask:0xf
	s_nop 0
	ds_bpermute_b32 v147, v144, v217
	ds_bpermute_b32 v132, v144, v212
	s_waitcnt lgkmcnt(0)
	v_add_f32_e32 v217, v217, v147
	v_add_f32_e32 v212, v212, v132
	s_nop 0
	ds_bpermute_b32 v147, v145, v217
	ds_bpermute_b32 v132, v145, v212
	s_waitcnt lgkmcnt(0)
	v_add_f32_e32 v217, v217, v147
	v_add_f32_e32 v212, v212, v132
	v_cmp_gt_u32_e32 vcc, 8, v213
	s_nop 1
	v_cndmask_b32_e32 v217, v212, v217, vcc
	v_cmp_eq_u32_e32 vcc, 0, v146
	s_and_saveexec_b64 s[98:99], vcc
	global_store_dword v216, v217, s[100:101]
	s_mov_b64 exec, s[98:99]
	s_add_u32 s88, s88, 0x10000
	s_addc_u32 s89, s89, 0
	s_add_u32 s92, s92, 0x8000
	s_addc_u32 s93, s93, 0
	s_add_u32 s100, s100, 0x400
	s_addc_u32 s101, s101, 0
	v_mov_b32_e32 v156, v8
	v_mov_b32_e32 v157, v9
	v_mov_b32_e32 v158, v10
	v_mov_b32_e32 v159, v11
	v_mov_b32_dpp v8, v12 row_ror:8 row_mask:0xf bank_mask:0x3
	v_mov_b32_dpp v9, v13 row_ror:8 row_mask:0xf bank_mask:0x3
	v_mov_b32_dpp v10, v14 row_ror:8 row_mask:0xf bank_mask:0x3
	v_mov_b32_dpp v11, v15 row_ror:8 row_mask:0xf bank_mask:0x3
	v_mov_b32_dpp v12, v156 row_ror:8 row_mask:0xf bank_mask:0xc
	v_mov_b32_dpp v13, v157 row_ror:8 row_mask:0xf bank_mask:0xc
	v_mov_b32_dpp v14, v158 row_ror:8 row_mask:0xf bank_mask:0xc
	v_mov_b32_dpp v15, v159 row_ror:8 row_mask:0xf bank_mask:0xc
	s_waitcnt vmcnt(46)
	v_add_f32_e32 v12, v12, v92
	v_add_f32_e32 v13, v13, v93
	v_add_f32_e32 v14, v14, v94
	v_add_f32_e32 v15, v15, v95
	global_store_dwordx4 v148, v[12:15], s[88:89]
	v_cvt_pk_bf16_f32 v92, v12, v13
	v_cvt_pk_bf16_f32 v93, v14, v15
	global_store_dwordx2 v210, v[92:93], s[92:93]
	v_mul_f32_e32 v217, v12, v12
	v_fmac_f32_e32 v217, v13, v13
	v_fmac_f32_e32 v217, v14, v14
	v_fmac_f32_e32 v217, v15, v15
	s_waitcnt vmcnt(45)
	v_add_f32_e32 v8, v8, v196
	v_add_f32_e32 v9, v9, v197
	v_add_f32_e32 v10, v10, v198
	v_add_f32_e32 v11, v11, v199
	global_store_dwordx4 v149, v[8:11], s[88:89]
	v_cvt_pk_bf16_f32 v196, v8, v9
	v_cvt_pk_bf16_f32 v197, v10, v11
	global_store_dwordx2 v211, v[196:197], s[92:93]
	v_mul_f32_e32 v212, v8, v8
	v_fmac_f32_e32 v212, v9, v9
	v_fmac_f32_e32 v212, v10, v10
	v_fmac_f32_e32 v212, v11, v11
	v_mov_b32_e32 v156, v0
	v_mov_b32_e32 v157, v1
	v_mov_b32_e32 v158, v2
	v_mov_b32_e32 v159, v3
	v_mov_b32_dpp v0, v4 row_ror:8 row_mask:0xf bank_mask:0x3
	v_mov_b32_dpp v1, v5 row_ror:8 row_mask:0xf bank_mask:0x3
	v_mov_b32_dpp v2, v6 row_ror:8 row_mask:0xf bank_mask:0x3
	v_mov_b32_dpp v3, v7 row_ror:8 row_mask:0xf bank_mask:0x3
	v_mov_b32_dpp v4, v156 row_ror:8 row_mask:0xf bank_mask:0xc
	v_mov_b32_dpp v5, v157 row_ror:8 row_mask:0xf bank_mask:0xc
	v_mov_b32_dpp v6, v158 row_ror:8 row_mask:0xf bank_mask:0xc
	v_mov_b32_dpp v7, v159 row_ror:8 row_mask:0xf bank_mask:0xc
	s_waitcnt vmcnt(46)
	v_add_f32_e32 v4, v4, v88
	v_add_f32_e32 v5, v5, v89
	v_add_f32_e32 v6, v6, v90
	v_add_f32_e32 v7, v7, v91
	global_store_dwordx4 v148, v[4:7], s[88:89] offset:512
	v_cvt_pk_bf16_f32 v88, v4, v5
	v_cvt_pk_bf16_f32 v89, v6, v7
	global_store_dwordx2 v210, v[88:89], s[92:93] offset:256
	v_fmac_f32_e32 v217, v4, v4
	v_fmac_f32_e32 v217, v5, v5
	v_fmac_f32_e32 v217, v6, v6
	v_fmac_f32_e32 v217, v7, v7
	s_waitcnt vmcnt(45)
	v_add_f32_e32 v0, v0, v200
	v_add_f32_e32 v1, v1, v201
	v_add_f32_e32 v2, v2, v202
	v_add_f32_e32 v3, v3, v203
	global_store_dwordx4 v149, v[0:3], s[88:89] offset:512
	v_cvt_pk_bf16_f32 v200, v0, v1
	v_cvt_pk_bf16_f32 v201, v2, v3
	global_store_dwordx2 v211, v[200:201], s[92:93] offset:256
	v_fmac_f32_e32 v212, v0, v0
	v_fmac_f32_e32 v212, v1, v1
	v_fmac_f32_e32 v212, v2, v2
	v_fmac_f32_e32 v212, v3, v3
	s_nop 1
	v_add_f32_dpp v217, v217, v217 row_ror:8 row_mask:0xf bank_mask:0xf
	v_add_f32_dpp v212, v212, v212 row_ror:8 row_mask:0xf bank_mask:0xf
	s_nop 0
	ds_bpermute_b32 v147, v144, v217
	ds_bpermute_b32 v132, v144, v212
	s_waitcnt lgkmcnt(0)
	v_add_f32_e32 v217, v217, v147
	v_add_f32_e32 v212, v212, v132
	s_nop 0
	ds_bpermute_b32 v147, v145, v217
	ds_bpermute_b32 v132, v145, v212
	s_waitcnt lgkmcnt(0)
	v_add_f32_e32 v217, v217, v147
	v_add_f32_e32 v212, v212, v132
	v_cmp_gt_u32_e32 vcc, 8, v213
	s_nop 1
	v_cndmask_b32_e32 v217, v212, v217, vcc
	v_cmp_eq_u32_e32 vcc, 0, v146
	s_and_saveexec_b64 s[98:99], vcc
	global_store_dword v216, v217, s[100:101]
	s_mov_b64 exec, s[98:99]
	s_andn2_b64 vcc, exec, s[12:13]
	s_mov_b64 s[12:13], -1
	s_cbranch_vccnz .LBB0_1275
	s_andn2_b64 vcc, exec, s[26:27]
	s_cbranch_vccnz .LBB0_1274
	s_barrier
	s_branch .LBB0_1274

.LBB0_1492:
	v_lshrrev_b32_e32 v132, 6, v206
	v_and_b32_e32 v143, 63, v206
	v_lshrrev_b32_e32 v142, 2, v132
	v_and_b32_e32 v132, 3, v132
	v_lshlrev_b32_e32 v142, 6, v142
	v_lshrrev_b32_e32 v146, 4, v143
	v_and_b32_e32 v213, 15, v143
	v_xor_b32_e32 v144, 16, v143
	v_xor_b32_e32 v145, 32, v143
	v_lshlrev_b32_e32 v144, 2, v144
	v_lshlrev_b32_e32 v145, 2, v145
	s_lshl_b32 vcc_lo, s12, 8
	v_add_u32_e32 v142, vcc_lo, v142
	s_lshl_b32 vcc_lo, s49, 2
	v_add_u32_e32 v216, vcc_lo, v132
	v_add_u32_e32 v147, v142, v213
	v_lshlrev_b32_e32 v147, 6, v147
	v_lshl_add_u32 v216, v216, 2, v147
	v_lshlrev_b32_e32 v143, 5, v132
	v_lshrrev_b32_e32 v147, 3, v213
	v_lshl_add_u32 v147, v147, 2, v146
	v_lshl_add_u32 v143, v147, 2, v143
	s_lshl_b32 vcc_lo, s49, 8
	v_add_u32_e32 v143, vcc_lo, v143
	v_and_b32_e32 v147, 7, v213
	v_add_u32_e32 v142, v142, v147
	v_lshlrev_b32_e32 v148, 12, v142
	v_lshl_add_u32 v148, v143, 2, v148
	v_add_u32_e32 v149, 0x8000, v148
	v_lshlrev_b32_e32 v210, 11, v142
	v_lshl_add_u32 v210, v143, 1, v210
	v_add_u32_e32 v211, 0x4000, v210
	s_mov_b32 s86, s94
	s_mov_b32 s87, s95
	s_mov_b32 s88, s94
	s_mov_b32 s89, s95
	s_add_u32 s100, s96, 0x5500000
	s_addc_u32 s101, s97, 0
	global_load_dwordx4 v[160:163], v148, s[86:87]
	global_load_dwordx4 v[164:167], v149, s[86:87]
	global_load_dwordx4 v[168:171], v148, s[86:87] offset:512
	global_load_dwordx4 v[172:175], v149, s[86:87] offset:512
	s_add_u32 s86, s86, 0x10000
	s_addc_u32 s87, s87, 0
	global_load_dwordx4 v[176:179], v148, s[86:87]
	global_load_dwordx4 v[180:183], v149, s[86:87]
	global_load_dwordx4 v[184:187], v148, s[86:87] offset:512
	global_load_dwordx4 v[188:191], v149, s[86:87] offset:512
	s_add_u32 s86, s86, 0x10000
	s_addc_u32 s87, s87, 0
	global_load_dwordx4 v[192:195], v148, s[86:87]
	global_load_dwordx4 v[196:199], v149, s[86:87]
	global_load_dwordx4 v[200:203], v148, s[86:87] offset:512
	v_mov_b32_e32 v156, v120
	v_mov_b32_e32 v157, v121
	v_mov_b32_e32 v158, v122
	v_mov_b32_e32 v159, v123
	v_mov_b32_dpp v120, v124 row_ror:8 row_mask:0xf bank_mask:0x3
	v_mov_b32_dpp v121, v125 row_ror:8 row_mask:0xf bank_mask:0x3
	v_mov_b32_dpp v122, v126 row_ror:8 row_mask:0xf bank_mask:0x3
	v_mov_b32_dpp v123, v127 row_ror:8 row_mask:0xf bank_mask:0x3
	v_mov_b32_dpp v124, v156 row_ror:8 row_mask:0xf bank_mask:0xc
	v_mov_b32_dpp v125, v157 row_ror:8 row_mask:0xf bank_mask:0xc
	v_mov_b32_dpp v126, v158 row_ror:8 row_mask:0xf bank_mask:0xc
	v_mov_b32_dpp v127, v159 row_ror:8 row_mask:0xf bank_mask:0xc
	s_waitcnt vmcnt(10)
	v_fma_f32 v124, v124, 0.5, v160
	v_fma_f32 v125, v125, 0.5, v161
	v_fma_f32 v126, v126, 0.5, v162
	v_fma_f32 v127, v127, 0.5, v163
	global_store_dwordx4 v148, v[124:127], s[88:89]
	v_mul_f32_e32 v217, v124, v124
	v_fmac_f32_e32 v217, v125, v125
	v_fmac_f32_e32 v217, v126, v126
	v_fmac_f32_e32 v217, v127, v127
	global_load_dwordx4 v[160:163], v149, s[86:87] offset:512
	s_add_u32 s86, s86, 0x10000
	s_addc_u32 s87, s87, 0
	global_load_dwordx4 v[124:127], v148, s[86:87]
	s_waitcnt vmcnt(12)
	v_fma_f32 v120, v120, 0.5, v164
	v_fma_f32 v121, v121, 0.5, v165
	v_fma_f32 v122, v122, 0.5, v166
	v_fma_f32 v123, v123, 0.5, v167
	global_store_dwordx4 v149, v[120:123], s[88:89]
	v_mul_f32_e32 v212, v120, v120
	v_fmac_f32_e32 v212, v121, v121
	v_fmac_f32_e32 v212, v122, v122
	v_fmac_f32_e32 v212, v123, v123
	global_load_dwordx4 v[164:167], v149, s[86:87]
	global_load_dwordx4 v[120:123], v148, s[86:87] offset:512
	v_mov_b32_e32 v156, v112
	v_mov_b32_e32 v157, v113
	v_mov_b32_e32 v158, v114
	v_mov_b32_e32 v159, v115
	v_mov_b32_dpp v112, v116 row_ror:8 row_mask:0xf bank_mask:0x3
	v_mov_b32_dpp v113, v117 row_ror:8 row_mask:0xf bank_mask:0x3
	v_mov_b32_dpp v114, v118 row_ror:8 row_mask:0xf bank_mask:0x3
	v_mov_b32_dpp v115, v119 row_ror:8 row_mask:0xf bank_mask:0x3
	v_mov_b32_dpp v116, v156 row_ror:8 row_mask:0xf bank_mask:0xc
	v_mov_b32_dpp v117, v157 row_ror:8 row_mask:0xf bank_mask:0xc
	v_mov_b32_dpp v118, v158 row_ror:8 row_mask:0xf bank_mask:0xc
	v_mov_b32_dpp v119, v159 row_ror:8 row_mask:0xf bank_mask:0xc
	s_waitcnt vmcnt(14)
	v_fma_f32 v116, v116, 0.5, v168
	v_fma_f32 v117, v117, 0.5, v169
	v_fma_f32 v118, v118, 0.5, v170
	v_fma_f32 v119, v119, 0.5, v171
	global_store_dwordx4 v148, v[116:119], s[88:89] offset:512
	v_fmac_f32_e32 v217, v116, v116
	v_fmac_f32_e32 v217, v117, v117
	v_fmac_f32_e32 v217, v118, v118
	v_fmac_f32_e32 v217, v119, v119
	global_load_dwordx4 v[168:171], v149, s[86:87] offset:512
	s_add_u32 s86, s86, 0x50000
	s_addc_u32 s87, s87, 0
	global_load_dwordx4 v[116:119], v148, s[86:87]
	s_waitcnt vmcnt(16)
	v_fma_f32 v112, v112, 0.5, v172
	v_fma_f32 v113, v113, 0.5, v173
	v_fma_f32 v114, v114, 0.5, v174
	v_fma_f32 v115, v115, 0.5, v175
	global_store_dwordx4 v149, v[112:115], s[88:89] offset:512
	v_fmac_f32_e32 v212, v112, v112
	v_fmac_f32_e32 v212, v113, v113
	v_fmac_f32_e32 v212, v114, v114
	v_fmac_f32_e32 v212, v115, v115
	global_load_dwordx4 v[172:175], v149, s[86:87]
	global_load_dwordx4 v[112:115], v148, s[86:87] offset:512
	s_nop 1
	v_add_f32_dpp v217, v217, v217 row_ror:8 row_mask:0xf bank_mask:0xf
	v_add_f32_dpp v212, v212, v212 row_ror:8 row_mask:0xf bank_mask:0xf
	s_nop 0
	ds_bpermute_b32 v147, v144, v217
	ds_bpermute_b32 v132, v144, v212
	s_waitcnt lgkmcnt(0)
	v_add_f32_e32 v217, v217, v147
	v_add_f32_e32 v212, v212, v132
	s_nop 0
	ds_bpermute_b32 v147, v145, v217
	ds_bpermute_b32 v132, v145, v212
	s_waitcnt lgkmcnt(0)
	v_add_f32_e32 v217, v217, v147
	v_add_f32_e32 v212, v212, v132
	v_cmp_gt_u32_e32 vcc, 8, v213
	s_nop 1
	v_cndmask_b32_e32 v217, v212, v217, vcc
	v_cmp_eq_u32_e32 vcc, 0, v146
	s_and_saveexec_b64 s[98:99], vcc
	global_store_dword v216, v217, s[100:101]
	s_mov_b64 exec, s[98:99]
	s_add_u32 s88, s88, 0x10000
	s_addc_u32 s89, s89, 0
	s_add_u32 s100, s100, 0x400
	s_addc_u32 s101, s101, 0
	v_mov_b32_e32 v156, v104
	v_mov_b32_e32 v157, v105
	v_mov_b32_e32 v158, v106
	v_mov_b32_e32 v159, v107
	v_mov_b32_dpp v104, v108 row_ror:8 row_mask:0xf bank_mask:0x3
	v_mov_b32_dpp v105, v109 row_ror:8 row_mask:0xf bank_mask:0x3
	v_mov_b32_dpp v106, v110 row_ror:8 row_mask:0xf bank_mask:0x3
	v_mov_b32_dpp v107, v111 row_ror:8 row_mask:0xf bank_mask:0x3
	v_mov_b32_dpp v108, v156 row_ror:8 row_mask:0xf bank_mask:0xc
	v_mov_b32_dpp v109, v157 row_ror:8 row_mask:0xf bank_mask:0xc
	v_mov_b32_dpp v110, v158 row_ror:8 row_mask:0xf bank_mask:0xc
	v_mov_b32_dpp v111, v159 row_ror:8 row_mask:0xf bank_mask:0xc
	s_waitcnt vmcnt(19)
	v_fma_f32 v108, v108, 0.5, v176
	v_fma_f32 v109, v109, 0.5, v177
	v_fma_f32 v110, v110, 0.5, v178
	v_fma_f32 v111, v111, 0.5, v179
	global_store_dwordx4 v148, v[108:111], s[88:89]
	v_mul_f32_e32 v217, v108, v108
	v_fmac_f32_e32 v217, v109, v109
	v_fmac_f32_e32 v217, v110, v110
	v_fmac_f32_e32 v217, v111, v111
	global_load_dwordx4 v[176:179], v149, s[86:87] offset:512
	s_add_u32 s86, s86, 0x10000
	s_addc_u32 s87, s87, 0
	global_load_dwordx4 v[108:111], v148, s[86:87]
	s_waitcnt vmcnt(21)
	v_fma_f32 v104, v104, 0.5, v180
	v_fma_f32 v105, v105, 0.5, v181
	v_fma_f32 v106, v106, 0.5, v182
	v_fma_f32 v107, v107, 0.5, v183
	global_store_dwordx4 v149, v[104:107], s[88:89]
	v_mul_f32_e32 v212, v104, v104
	v_fmac_f32_e32 v212, v105, v105
	v_fmac_f32_e32 v212, v106, v106
	v_fmac_f32_e32 v212, v107, v107
	global_load_dwordx4 v[180:183], v149, s[86:87]
	global_load_dwordx4 v[104:107], v148, s[86:87] offset:512
	v_mov_b32_e32 v156, v96
	v_mov_b32_e32 v157, v97
	v_mov_b32_e32 v158, v98
	v_mov_b32_e32 v159, v99
	v_mov_b32_dpp v96, v100 row_ror:8 row_mask:0xf bank_mask:0x3
	v_mov_b32_dpp v97, v101 row_ror:8 row_mask:0xf bank_mask:0x3
	v_mov_b32_dpp v98, v102 row_ror:8 row_mask:0xf bank_mask:0x3
	v_mov_b32_dpp v99, v103 row_ror:8 row_mask:0xf bank_mask:0x3
	v_mov_b32_dpp v100, v156 row_ror:8 row_mask:0xf bank_mask:0xc
	v_mov_b32_dpp v101, v157 row_ror:8 row_mask:0xf bank_mask:0xc
	v_mov_b32_dpp v102, v158 row_ror:8 row_mask:0xf bank_mask:0xc
	v_mov_b32_dpp v103, v159 row_ror:8 row_mask:0xf bank_mask:0xc
	s_waitcnt vmcnt(23)
	v_fma_f32 v100, v100, 0.5, v184
	v_fma_f32 v101, v101, 0.5, v185
	v_fma_f32 v102, v102, 0.5, v186
	v_fma_f32 v103, v103, 0.5, v187
	global_store_dwordx4 v148, v[100:103], s[88:89] offset:512
	v_fmac_f32_e32 v217, v100, v100
	v_fmac_f32_e32 v217, v101, v101
	v_fmac_f32_e32 v217, v102, v102
	v_fmac_f32_e32 v217, v103, v103
	global_load_dwordx4 v[184:187], v149, s[86:87] offset:512
	s_add_u32 s86, s86, 0x10000
	s_addc_u32 s87, s87, 0
	global_load_dwordx4 v[100:103], v148, s[86:87]
	s_waitcnt vmcnt(25)
	v_fma_f32 v96, v96, 0.5, v188
	v_fma_f32 v97, v97, 0.5, v189
	v_fma_f32 v98, v98, 0.5, v190
	v_fma_f32 v99, v99, 0.5, v191
	global_store_dwordx4 v149, v[96:99], s[88:89] offset:512
	v_fmac_f32_e32 v212, v96, v96
	v_fmac_f32_e32 v212, v97, v97
	v_fmac_f32_e32 v212, v98, v98
	v_fmac_f32_e32 v212, v99, v99
	global_load_dwordx4 v[188:191], v149, s[86:87]
	global_load_dwordx4 v[96:99], v148, s[86:87] offset:512
	s_nop 1
	v_add_f32_dpp v217, v217, v217 row_ror:8 row_mask:0xf bank_mask:0xf
	v_add_f32_dpp v212, v212, v212 row_ror:8 row_mask:0xf bank_mask:0xf
	s_nop 0
	ds_bpermute_b32 v147, v144, v217
	ds_bpermute_b32 v132, v144, v212
	s_waitcnt lgkmcnt(0)
	v_add_f32_e32 v217, v217, v147
	v_add_f32_e32 v212, v212, v132
	s_nop 0
	ds_bpermute_b32 v147, v145, v217
	ds_bpermute_b32 v132, v145, v212
	s_waitcnt lgkmcnt(0)
	v_add_f32_e32 v217, v217, v147
	v_add_f32_e32 v212, v212, v132
	v_cmp_gt_u32_e32 vcc, 8, v213
	s_nop 1
	v_cndmask_b32_e32 v217, v212, v217, vcc
	v_cmp_eq_u32_e32 vcc, 0, v146
	s_and_saveexec_b64 s[98:99], vcc
	global_store_dword v216, v217, s[100:101]
	s_mov_b64 exec, s[98:99]
	s_add_u32 s88, s88, 0x10000
	s_addc_u32 s89, s89, 0
	s_add_u32 s100, s100, 0x400
	s_addc_u32 s101, s101, 0
	v_mov_b32_e32 v156, v88
	v_mov_b32_e32 v157, v89
	v_mov_b32_e32 v158, v90
	v_mov_b32_e32 v159, v91
	v_mov_b32_dpp v88, v92 row_ror:8 row_mask:0xf bank_mask:0x3
	v_mov_b32_dpp v89, v93 row_ror:8 row_mask:0xf bank_mask:0x3
	v_mov_b32_dpp v90, v94 row_ror:8 row_mask:0xf bank_mask:0x3
	v_mov_b32_dpp v91, v95 row_ror:8 row_mask:0xf bank_mask:0x3
	v_mov_b32_dpp v92, v156 row_ror:8 row_mask:0xf bank_mask:0xc
	v_mov_b32_dpp v93, v157 row_ror:8 row_mask:0xf bank_mask:0xc
	v_mov_b32_dpp v94, v158 row_ror:8 row_mask:0xf bank_mask:0xc
	v_mov_b32_dpp v95, v159 row_ror:8 row_mask:0xf bank_mask:0xc
	s_waitcnt vmcnt(28)
	v_fma_f32 v92, v92, 0.5, v192
	v_fma_f32 v93, v93, 0.5, v193
	v_fma_f32 v94, v94, 0.5, v194
	v_fma_f32 v95, v95, 0.5, v195
	global_store_dwordx4 v148, v[92:95], s[88:89]
	v_mul_f32_e32 v217, v92, v92
	v_fmac_f32_e32 v217, v93, v93
	v_fmac_f32_e32 v217, v94, v94
	v_fmac_f32_e32 v217, v95, v95
	global_load_dwordx4 v[192:195], v149, s[86:87] offset:512
	s_add_u32 s86, s86, 0x10000
	s_addc_u32 s87, s87, 0
	global_load_dwordx4 v[92:95], v148, s[86:87]
	s_waitcnt vmcnt(30)
	v_fma_f32 v88, v88, 0.5, v196
	v_fma_f32 v89, v89, 0.5, v197
	v_fma_f32 v90, v90, 0.5, v198
	v_fma_f32 v91, v91, 0.5, v199
	global_store_dwordx4 v149, v[88:91], s[88:89]
	v_mul_f32_e32 v212, v88, v88
	v_fmac_f32_e32 v212, v89, v89
	v_fmac_f32_e32 v212, v90, v90
	v_fmac_f32_e32 v212, v91, v91
	global_load_dwordx4 v[196:199], v149, s[86:87]
	global_load_dwordx4 v[88:91], v148, s[86:87] offset:512
	v_mov_b32_e32 v156, v80
	v_mov_b32_e32 v157, v81
	v_mov_b32_e32 v158, v82
	v_mov_b32_e32 v159, v83
	v_mov_b32_dpp v80, v84 row_ror:8 row_mask:0xf bank_mask:0x3
	v_mov_b32_dpp v81, v85 row_ror:8 row_mask:0xf bank_mask:0x3
	v_mov_b32_dpp v82, v86 row_ror:8 row_mask:0xf bank_mask:0x3
	v_mov_b32_dpp v83, v87 row_ror:8 row_mask:0xf bank_mask:0x3
	v_mov_b32_dpp v84, v156 row_ror:8 row_mask:0xf bank_mask:0xc
	v_mov_b32_dpp v85, v157 row_ror:8 row_mask:0xf bank_mask:0xc
	v_mov_b32_dpp v86, v158 row_ror:8 row_mask:0xf bank_mask:0xc
	v_mov_b32_dpp v87, v159 row_ror:8 row_mask:0xf bank_mask:0xc
	s_waitcnt vmcnt(32)
	v_fma_f32 v84, v84, 0.5, v200
	v_fma_f32 v85, v85, 0.5, v201
	v_fma_f32 v86, v86, 0.5, v202
	v_fma_f32 v87, v87, 0.5, v203
	global_store_dwordx4 v148, v[84:87], s[88:89] offset:512
	v_fmac_f32_e32 v217, v84, v84
	v_fmac_f32_e32 v217, v85, v85
	v_fmac_f32_e32 v217, v86, v86
	v_fmac_f32_e32 v217, v87, v87
	global_load_dwordx4 v[200:203], v149, s[86:87] offset:512
	s_waitcnt vmcnt(32)
	v_fma_f32 v80, v80, 0.5, v160
	v_fma_f32 v81, v81, 0.5, v161
	v_fma_f32 v82, v82, 0.5, v162
	v_fma_f32 v83, v83, 0.5, v163
	global_store_dwordx4 v149, v[80:83], s[88:89] offset:512
	v_fmac_f32_e32 v212, v80, v80
	v_fmac_f32_e32 v212, v81, v81
	v_fmac_f32_e32 v212, v82, v82
	v_fmac_f32_e32 v212, v83, v83
	s_nop 1
	v_add_f32_dpp v217, v217, v217 row_ror:8 row_mask:0xf bank_mask:0xf
	v_add_f32_dpp v212, v212, v212 row_ror:8 row_mask:0xf bank_mask:0xf
	s_nop 0
	ds_bpermute_b32 v147, v144, v217
	ds_bpermute_b32 v132, v144, v212
	s_waitcnt lgkmcnt(0)
	v_add_f32_e32 v217, v217, v147
	v_add_f32_e32 v212, v212, v132
	s_nop 0
	ds_bpermute_b32 v147, v145, v217
	ds_bpermute_b32 v132, v145, v212
	s_waitcnt lgkmcnt(0)
	v_add_f32_e32 v217, v217, v147
	v_add_f32_e32 v212, v212, v132
	v_cmp_gt_u32_e32 vcc, 8, v213
	s_nop 1
	v_cndmask_b32_e32 v217, v212, v217, vcc
	v_cmp_eq_u32_e32 vcc, 0, v146
	s_and_saveexec_b64 s[98:99], vcc
	global_store_dword v216, v217, s[100:101]
	s_mov_b64 exec, s[98:99]
	s_add_u32 s88, s88, 0x10000
	s_addc_u32 s89, s89, 0
	s_add_u32 s100, s100, 0x400
	s_addc_u32 s101, s101, 0
	v_mov_b32_e32 v156, v72
	v_mov_b32_e32 v157, v73
	v_mov_b32_e32 v158, v74
	v_mov_b32_e32 v159, v75
	v_mov_b32_dpp v72, v76 row_ror:8 row_mask:0xf bank_mask:0x3
	v_mov_b32_dpp v73, v77 row_ror:8 row_mask:0xf bank_mask:0x3
	v_mov_b32_dpp v74, v78 row_ror:8 row_mask:0xf bank_mask:0x3
	v_mov_b32_dpp v75, v79 row_ror:8 row_mask:0xf bank_mask:0x3
	v_mov_b32_dpp v76, v156 row_ror:8 row_mask:0xf bank_mask:0xc
	v_mov_b32_dpp v77, v157 row_ror:8 row_mask:0xf bank_mask:0xc
	v_mov_b32_dpp v78, v158 row_ror:8 row_mask:0xf bank_mask:0xc
	v_mov_b32_dpp v79, v159 row_ror:8 row_mask:0xf bank_mask:0xc
	s_waitcnt vmcnt(33)
	v_fma_f32 v76, v76, 0.5, v124
	v_fma_f32 v77, v77, 0.5, v125
	v_fma_f32 v78, v78, 0.5, v126
	v_fma_f32 v79, v79, 0.5, v127
	global_store_dwordx4 v148, v[76:79], s[88:89]
	v_mul_f32_e32 v217, v76, v76
	v_fmac_f32_e32 v217, v77, v77
	v_fmac_f32_e32 v217, v78, v78
	v_fmac_f32_e32 v217, v79, v79
	s_waitcnt vmcnt(32)
	v_fma_f32 v72, v72, 0.5, v164
	v_fma_f32 v73, v73, 0.5, v165
	v_fma_f32 v74, v74, 0.5, v166
	v_fma_f32 v75, v75, 0.5, v167
	global_store_dwordx4 v149, v[72:75], s[88:89]
	v_mul_f32_e32 v212, v72, v72
	v_fmac_f32_e32 v212, v73, v73
	v_fmac_f32_e32 v212, v74, v74
	v_fmac_f32_e32 v212, v75, v75
	v_mov_b32_e32 v156, v64
	v_mov_b32_e32 v157, v65
	v_mov_b32_e32 v158, v66
	v_mov_b32_e32 v159, v67
	v_mov_b32_dpp v64, v68 row_ror:8 row_mask:0xf bank_mask:0x3
	v_mov_b32_dpp v65, v69 row_ror:8 row_mask:0xf bank_mask:0x3
	v_mov_b32_dpp v66, v70 row_ror:8 row_mask:0xf bank_mask:0x3
	v_mov_b32_dpp v67, v71 row_ror:8 row_mask:0xf bank_mask:0x3
	v_mov_b32_dpp v68, v156 row_ror:8 row_mask:0xf bank_mask:0xc
	v_mov_b32_dpp v69, v157 row_ror:8 row_mask:0xf bank_mask:0xc
	v_mov_b32_dpp v70, v158 row_ror:8 row_mask:0xf bank_mask:0xc
	v_mov_b32_dpp v71, v159 row_ror:8 row_mask:0xf bank_mask:0xc
	s_waitcnt vmcnt(32)
	v_fma_f32 v68, v68, 0.5, v120
	v_fma_f32 v69, v69, 0.5, v121
	v_fma_f32 v70, v70, 0.5, v122
	v_fma_f32 v71, v71, 0.5, v123
	global_store_dwordx4 v148, v[68:71], s[88:89] offset:512
	v_fmac_f32_e32 v217, v68, v68
	v_fmac_f32_e32 v217, v69, v69
	v_fmac_f32_e32 v217, v70, v70
	v_fmac_f32_e32 v217, v71, v71
	s_waitcnt vmcnt(31)
	v_fma_f32 v64, v64, 0.5, v168
	v_fma_f32 v65, v65, 0.5, v169
	v_fma_f32 v66, v66, 0.5, v170
	v_fma_f32 v67, v67, 0.5, v171
	global_store_dwordx4 v149, v[64:67], s[88:89] offset:512
	v_fmac_f32_e32 v212, v64, v64
	v_fmac_f32_e32 v212, v65, v65
	v_fmac_f32_e32 v212, v66, v66
	v_fmac_f32_e32 v212, v67, v67
	s_nop 1
	v_add_f32_dpp v217, v217, v217 row_ror:8 row_mask:0xf bank_mask:0xf
	v_add_f32_dpp v212, v212, v212 row_ror:8 row_mask:0xf bank_mask:0xf
	s_nop 0
	ds_bpermute_b32 v147, v144, v217
	ds_bpermute_b32 v132, v144, v212
	s_waitcnt lgkmcnt(0)
	v_add_f32_e32 v217, v217, v147
	v_add_f32_e32 v212, v212, v132
	s_nop 0
	ds_bpermute_b32 v147, v145, v217
	ds_bpermute_b32 v132, v145, v212
	s_waitcnt lgkmcnt(0)
	v_add_f32_e32 v217, v217, v147
	v_add_f32_e32 v212, v212, v132
	v_cmp_gt_u32_e32 vcc, 8, v213
	s_nop 1
	v_cndmask_b32_e32 v217, v212, v217, vcc
	v_cmp_eq_u32_e32 vcc, 0, v146
	s_and_saveexec_b64 s[98:99], vcc
	global_store_dword v216, v217, s[100:101]
	s_mov_b64 exec, s[98:99]
	s_add_u32 s88, s88, 0x50000
	s_addc_u32 s89, s89, 0
	s_add_u32 s100, s100, 0x1400
	s_addc_u32 s101, s101, 0
	v_mov_b32_e32 v156, v56
	v_mov_b32_e32 v157, v57
	v_mov_b32_e32 v158, v58
	v_mov_b32_e32 v159, v59
	v_mov_b32_dpp v56, v60 row_ror:8 row_mask:0xf bank_mask:0x3
	v_mov_b32_dpp v57, v61 row_ror:8 row_mask:0xf bank_mask:0x3
	v_mov_b32_dpp v58, v62 row_ror:8 row_mask:0xf bank_mask:0x3
	v_mov_b32_dpp v59, v63 row_ror:8 row_mask:0xf bank_mask:0x3
	v_mov_b32_dpp v60, v156 row_ror:8 row_mask:0xf bank_mask:0xc
	v_mov_b32_dpp v61, v157 row_ror:8 row_mask:0xf bank_mask:0xc
	v_mov_b32_dpp v62, v158 row_ror:8 row_mask:0xf bank_mask:0xc
	v_mov_b32_dpp v63, v159 row_ror:8 row_mask:0xf bank_mask:0xc
	s_waitcnt vmcnt(32)
	v_fma_f32 v60, v60, 0.5, v116
	v_fma_f32 v61, v61, 0.5, v117
	v_fma_f32 v62, v62, 0.5, v118
	v_fma_f32 v63, v63, 0.5, v119
	global_store_dwordx4 v148, v[60:63], s[88:89]
	v_mul_f32_e32 v217, v60, v60
	v_fmac_f32_e32 v217, v61, v61
	v_fmac_f32_e32 v217, v62, v62
	v_fmac_f32_e32 v217, v63, v63
	s_waitcnt vmcnt(31)
	v_fma_f32 v56, v56, 0.5, v172
	v_fma_f32 v57, v57, 0.5, v173
	v_fma_f32 v58, v58, 0.5, v174
	v_fma_f32 v59, v59, 0.5, v175
	global_store_dwordx4 v149, v[56:59], s[88:89]
	v_mul_f32_e32 v212, v56, v56
	v_fmac_f32_e32 v212, v57, v57
	v_fmac_f32_e32 v212, v58, v58
	v_fmac_f32_e32 v212, v59, v59
	v_mov_b32_e32 v156, v48
	v_mov_b32_e32 v157, v49
	v_mov_b32_e32 v158, v50
	v_mov_b32_e32 v159, v51
	v_mov_b32_dpp v48, v52 row_ror:8 row_mask:0xf bank_mask:0x3
	v_mov_b32_dpp v49, v53 row_ror:8 row_mask:0xf bank_mask:0x3
	v_mov_b32_dpp v50, v54 row_ror:8 row_mask:0xf bank_mask:0x3
	v_mov_b32_dpp v51, v55 row_ror:8 row_mask:0xf bank_mask:0x3
	v_mov_b32_dpp v52, v156 row_ror:8 row_mask:0xf bank_mask:0xc
	v_mov_b32_dpp v53, v157 row_ror:8 row_mask:0xf bank_mask:0xc
	v_mov_b32_dpp v54, v158 row_ror:8 row_mask:0xf bank_mask:0xc
	v_mov_b32_dpp v55, v159 row_ror:8 row_mask:0xf bank_mask:0xc
	s_waitcnt vmcnt(31)
	v_fma_f32 v52, v52, 0.5, v112
	v_fma_f32 v53, v53, 0.5, v113
	v_fma_f32 v54, v54, 0.5, v114
	v_fma_f32 v55, v55, 0.5, v115
	global_store_dwordx4 v148, v[52:55], s[88:89] offset:512
	v_fmac_f32_e32 v217, v52, v52
	v_fmac_f32_e32 v217, v53, v53
	v_fmac_f32_e32 v217, v54, v54
	v_fmac_f32_e32 v217, v55, v55
	s_waitcnt vmcnt(29)
	v_fma_f32 v48, v48, 0.5, v176
	v_fma_f32 v49, v49, 0.5, v177
	v_fma_f32 v50, v50, 0.5, v178
	v_fma_f32 v51, v51, 0.5, v179
	global_store_dwordx4 v149, v[48:51], s[88:89] offset:512
	v_fmac_f32_e32 v212, v48, v48
	v_fmac_f32_e32 v212, v49, v49
	v_fmac_f32_e32 v212, v50, v50
	v_fmac_f32_e32 v212, v51, v51
	s_nop 1
	v_add_f32_dpp v217, v217, v217 row_ror:8 row_mask:0xf bank_mask:0xf
	v_add_f32_dpp v212, v212, v212 row_ror:8 row_mask:0xf bank_mask:0xf
	s_nop 0
	ds_bpermute_b32 v147, v144, v217
	ds_bpermute_b32 v132, v144, v212
	s_waitcnt lgkmcnt(0)
	v_add_f32_e32 v217, v217, v147
	v_add_f32_e32 v212, v212, v132
	s_nop 0
	ds_bpermute_b32 v147, v145, v217
	ds_bpermute_b32 v132, v145, v212
	s_waitcnt lgkmcnt(0)
	v_add_f32_e32 v217, v217, v147
	v_add_f32_e32 v212, v212, v132
	v_cmp_gt_u32_e32 vcc, 8, v213
	s_nop 1
	v_cndmask_b32_e32 v217, v212, v217, vcc
	v_cmp_eq_u32_e32 vcc, 0, v146
	s_and_saveexec_b64 s[98:99], vcc
	global_store_dword v216, v217, s[100:101]
	s_mov_b64 exec, s[98:99]
	s_add_u32 s88, s88, 0x10000
	s_addc_u32 s89, s89, 0
	s_add_u32 s100, s100, 0x400
	s_addc_u32 s101, s101, 0
	v_mov_b32_e32 v156, v40
	v_mov_b32_e32 v157, v41
	v_mov_b32_e32 v158, v42
	v_mov_b32_e32 v159, v43
	v_mov_b32_dpp v40, v44 row_ror:8 row_mask:0xf bank_mask:0x3
	v_mov_b32_dpp v41, v45 row_ror:8 row_mask:0xf bank_mask:0x3
	v_mov_b32_dpp v42, v46 row_ror:8 row_mask:0xf bank_mask:0x3
	v_mov_b32_dpp v43, v47 row_ror:8 row_mask:0xf bank_mask:0x3
	v_mov_b32_dpp v44, v156 row_ror:8 row_mask:0xf bank_mask:0xc
	v_mov_b32_dpp v45, v157 row_ror:8 row_mask:0xf bank_mask:0xc
	v_mov_b32_dpp v46, v158 row_ror:8 row_mask:0xf bank_mask:0xc
	v_mov_b32_dpp v47, v159 row_ror:8 row_mask:0xf bank_mask:0xc
	s_waitcnt vmcnt(30)
	v_fma_f32 v44, v44, 0.5, v108
	v_fma_f32 v45, v45, 0.5, v109
	v_fma_f32 v46, v46, 0.5, v110
	v_fma_f32 v47, v47, 0.5, v111
	global_store_dwordx4 v148, v[44:47], s[88:89]
	v_mul_f32_e32 v217, v44, v44
	v_fmac_f32_e32 v217, v45, v45
	v_fmac_f32_e32 v217, v46, v46
	v_fmac_f32_e32 v217, v47, v47
	s_waitcnt vmcnt(29)
	v_fma_f32 v40, v40, 0.5, v180
	v_fma_f32 v41, v41, 0.5, v181
	v_fma_f32 v42, v42, 0.5, v182
	v_fma_f32 v43, v43, 0.5, v183
	global_store_dwordx4 v149, v[40:43], s[88:89]
	v_mul_f32_e32 v212, v40, v40
	v_fmac_f32_e32 v212, v41, v41
	v_fmac_f32_e32 v212, v42, v42
	v_fmac_f32_e32 v212, v43, v43
	v_mov_b32_e32 v156, v32
	v_mov_b32_e32 v157, v33
	v_mov_b32_e32 v158, v34
	v_mov_b32_e32 v159, v35
	v_mov_b32_dpp v32, v36 row_ror:8 row_mask:0xf bank_mask:0x3
	v_mov_b32_dpp v33, v37 row_ror:8 row_mask:0xf bank_mask:0x3
	v_mov_b32_dpp v34, v38 row_ror:8 row_mask:0xf bank_mask:0x3
	v_mov_b32_dpp v35, v39 row_ror:8 row_mask:0xf bank_mask:0x3
	v_mov_b32_dpp v36, v156 row_ror:8 row_mask:0xf bank_mask:0xc
	v_mov_b32_dpp v37, v157 row_ror:8 row_mask:0xf bank_mask:0xc
	v_mov_b32_dpp v38, v158 row_ror:8 row_mask:0xf bank_mask:0xc
	v_mov_b32_dpp v39, v159 row_ror:8 row_mask:0xf bank_mask:0xc
	s_waitcnt vmcnt(29)
	v_fma_f32 v36, v36, 0.5, v104
	v_fma_f32 v37, v37, 0.5, v105
	v_fma_f32 v38, v38, 0.5, v106
	v_fma_f32 v39, v39, 0.5, v107
	global_store_dwordx4 v148, v[36:39], s[88:89] offset:512
	v_fmac_f32_e32 v217, v36, v36
	v_fmac_f32_e32 v217, v37, v37
	v_fmac_f32_e32 v217, v38, v38
	v_fmac_f32_e32 v217, v39, v39
	s_waitcnt vmcnt(28)
	v_fma_f32 v32, v32, 0.5, v184
	v_fma_f32 v33, v33, 0.5, v185
	v_fma_f32 v34, v34, 0.5, v186
	v_fma_f32 v35, v35, 0.5, v187
	global_store_dwordx4 v149, v[32:35], s[88:89] offset:512
	v_fmac_f32_e32 v212, v32, v32
	v_fmac_f32_e32 v212, v33, v33
	v_fmac_f32_e32 v212, v34, v34
	v_fmac_f32_e32 v212, v35, v35
	s_nop 1
	v_add_f32_dpp v217, v217, v217 row_ror:8 row_mask:0xf bank_mask:0xf
	v_add_f32_dpp v212, v212, v212 row_ror:8 row_mask:0xf bank_mask:0xf
	s_nop 0
	ds_bpermute_b32 v147, v144, v217
	ds_bpermute_b32 v132, v144, v212
	s_waitcnt lgkmcnt(0)
	v_add_f32_e32 v217, v217, v147
	v_add_f32_e32 v212, v212, v132
	s_nop 0
	ds_bpermute_b32 v147, v145, v217
	ds_bpermute_b32 v132, v145, v212
	s_waitcnt lgkmcnt(0)
	v_add_f32_e32 v217, v217, v147
	v_add_f32_e32 v212, v212, v132
	v_cmp_gt_u32_e32 vcc, 8, v213
	s_nop 1
	v_cndmask_b32_e32 v217, v212, v217, vcc
	v_cmp_eq_u32_e32 vcc, 0, v146
	s_and_saveexec_b64 s[98:99], vcc
	global_store_dword v216, v217, s[100:101]
	s_mov_b64 exec, s[98:99]
	s_add_u32 s88, s88, 0x10000
	s_addc_u32 s89, s89, 0
	s_add_u32 s100, s100, 0x400
	s_addc_u32 s101, s101, 0
	v_mov_b32_e32 v156, v24
	v_mov_b32_e32 v157, v25
	v_mov_b32_e32 v158, v26
	v_mov_b32_e32 v159, v27
	v_mov_b32_dpp v24, v28 row_ror:8 row_mask:0xf bank_mask:0x3
	v_mov_b32_dpp v25, v29 row_ror:8 row_mask:0xf bank_mask:0x3
	v_mov_b32_dpp v26, v30 row_ror:8 row_mask:0xf bank_mask:0x3
	v_mov_b32_dpp v27, v31 row_ror:8 row_mask:0xf bank_mask:0x3
	v_mov_b32_dpp v28, v156 row_ror:8 row_mask:0xf bank_mask:0xc
	v_mov_b32_dpp v29, v157 row_ror:8 row_mask:0xf bank_mask:0xc
	v_mov_b32_dpp v30, v158 row_ror:8 row_mask:0xf bank_mask:0xc
	v_mov_b32_dpp v31, v159 row_ror:8 row_mask:0xf bank_mask:0xc
	s_waitcnt vmcnt(29)
	v_fma_f32 v28, v28, 0.5, v100
	v_fma_f32 v29, v29, 0.5, v101
	v_fma_f32 v30, v30, 0.5, v102
	v_fma_f32 v31, v31, 0.5, v103
	global_store_dwordx4 v148, v[28:31], s[88:89]
	v_mul_f32_e32 v217, v28, v28
	v_fmac_f32_e32 v217, v29, v29
	v_fmac_f32_e32 v217, v30, v30
	v_fmac_f32_e32 v217, v31, v31
	s_waitcnt vmcnt(28)
	v_fma_f32 v24, v24, 0.5, v188
	v_fma_f32 v25, v25, 0.5, v189
	v_fma_f32 v26, v26, 0.5, v190
	v_fma_f32 v27, v27, 0.5, v191
	global_store_dwordx4 v149, v[24:27], s[88:89]
	v_mul_f32_e32 v212, v24, v24
	v_fmac_f32_e32 v212, v25, v25
	v_fmac_f32_e32 v212, v26, v26
	v_fmac_f32_e32 v212, v27, v27
	v_mov_b32_e32 v156, v16
	v_mov_b32_e32 v157, v17
	v_mov_b32_e32 v158, v18
	v_mov_b32_e32 v159, v19
	v_mov_b32_dpp v16, v20 row_ror:8 row_mask:0xf bank_mask:0x3
	v_mov_b32_dpp v17, v21 row_ror:8 row_mask:0xf bank_mask:0x3
	v_mov_b32_dpp v18, v22 row_ror:8 row_mask:0xf bank_mask:0x3
	v_mov_b32_dpp v19, v23 row_ror:8 row_mask:0xf bank_mask:0x3
	v_mov_b32_dpp v20, v156 row_ror:8 row_mask:0xf bank_mask:0xc
	v_mov_b32_dpp v21, v157 row_ror:8 row_mask:0xf bank_mask:0xc
	v_mov_b32_dpp v22, v158 row_ror:8 row_mask:0xf bank_mask:0xc
	v_mov_b32_dpp v23, v159 row_ror:8 row_mask:0xf bank_mask:0xc
	s_waitcnt vmcnt(28)
	v_fma_f32 v20, v20, 0.5, v96
	v_fma_f32 v21, v21, 0.5, v97
	v_fma_f32 v22, v22, 0.5, v98
	v_fma_f32 v23, v23, 0.5, v99
	global_store_dwordx4 v148, v[20:23], s[88:89] offset:512
	v_fmac_f32_e32 v217, v20, v20
	v_fmac_f32_e32 v217, v21, v21
	v_fmac_f32_e32 v217, v22, v22
	v_fmac_f32_e32 v217, v23, v23
	s_waitcnt vmcnt(26)
	v_fma_f32 v16, v16, 0.5, v192
	v_fma_f32 v17, v17, 0.5, v193
	v_fma_f32 v18, v18, 0.5, v194
	v_fma_f32 v19, v19, 0.5, v195
	global_store_dwordx4 v149, v[16:19], s[88:89] offset:512
	v_fmac_f32_e32 v212, v16, v16
	v_fmac_f32_e32 v212, v17, v17
	v_fmac_f32_e32 v212, v18, v18
	v_fmac_f32_e32 v212, v19, v19
	s_nop 1
	v_add_f32_dpp v217, v217, v217 row_ror:8 row_mask:0xf bank_mask:0xf
	v_add_f32_dpp v212, v212, v212 row_ror:8 row_mask:0xf bank_mask:0xf
	s_nop 0
	ds_bpermute_b32 v147, v144, v217
	ds_bpermute_b32 v132, v144, v212
	s_waitcnt lgkmcnt(0)
	v_add_f32_e32 v217, v217, v147
	v_add_f32_e32 v212, v212, v132
	s_nop 0
	ds_bpermute_b32 v147, v145, v217
	ds_bpermute_b32 v132, v145, v212
	s_waitcnt lgkmcnt(0)
	v_add_f32_e32 v217, v217, v147
	v_add_f32_e32 v212, v212, v132
	v_cmp_gt_u32_e32 vcc, 8, v213
	s_nop 1
	v_cndmask_b32_e32 v217, v212, v217, vcc
	v_cmp_eq_u32_e32 vcc, 0, v146
	s_and_saveexec_b64 s[98:99], vcc
	global_store_dword v216, v217, s[100:101]
	s_mov_b64 exec, s[98:99]
	s_add_u32 s88, s88, 0x10000
	s_addc_u32 s89, s89, 0
	s_add_u32 s100, s100, 0x400
	s_addc_u32 s101, s101, 0
	v_mov_b32_e32 v156, v8
	v_mov_b32_e32 v157, v9
	v_mov_b32_e32 v158, v10
	v_mov_b32_e32 v159, v11
	v_mov_b32_dpp v8, v12 row_ror:8 row_mask:0xf bank_mask:0x3
	v_mov_b32_dpp v9, v13 row_ror:8 row_mask:0xf bank_mask:0x3
	v_mov_b32_dpp v10, v14 row_ror:8 row_mask:0xf bank_mask:0x3
	v_mov_b32_dpp v11, v15 row_ror:8 row_mask:0xf bank_mask:0x3
	v_mov_b32_dpp v12, v156 row_ror:8 row_mask:0xf bank_mask:0xc
	v_mov_b32_dpp v13, v157 row_ror:8 row_mask:0xf bank_mask:0xc
	v_mov_b32_dpp v14, v158 row_ror:8 row_mask:0xf bank_mask:0xc
	v_mov_b32_dpp v15, v159 row_ror:8 row_mask:0xf bank_mask:0xc
	s_waitcnt vmcnt(27)
	v_fma_f32 v12, v12, 0.5, v92
	v_fma_f32 v13, v13, 0.5, v93
	v_fma_f32 v14, v14, 0.5, v94
	v_fma_f32 v15, v15, 0.5, v95
	global_store_dwordx4 v148, v[12:15], s[88:89]
	v_mul_f32_e32 v217, v12, v12
	v_fmac_f32_e32 v217, v13, v13
	v_fmac_f32_e32 v217, v14, v14
	v_fmac_f32_e32 v217, v15, v15
	s_waitcnt vmcnt(26)
	v_fma_f32 v8, v8, 0.5, v196
	v_fma_f32 v9, v9, 0.5, v197
	v_fma_f32 v10, v10, 0.5, v198
	v_fma_f32 v11, v11, 0.5, v199
	global_store_dwordx4 v149, v[8:11], s[88:89]
	v_mul_f32_e32 v212, v8, v8
	v_fmac_f32_e32 v212, v9, v9
	v_fmac_f32_e32 v212, v10, v10
	v_fmac_f32_e32 v212, v11, v11
	v_mov_b32_e32 v156, v0
	v_mov_b32_e32 v157, v1
	v_mov_b32_e32 v158, v2
	v_mov_b32_e32 v159, v3
	v_mov_b32_dpp v0, v4 row_ror:8 row_mask:0xf bank_mask:0x3
	v_mov_b32_dpp v1, v5 row_ror:8 row_mask:0xf bank_mask:0x3
	v_mov_b32_dpp v2, v6 row_ror:8 row_mask:0xf bank_mask:0x3
	v_mov_b32_dpp v3, v7 row_ror:8 row_mask:0xf bank_mask:0x3
	v_mov_b32_dpp v4, v156 row_ror:8 row_mask:0xf bank_mask:0xc
	v_mov_b32_dpp v5, v157 row_ror:8 row_mask:0xf bank_mask:0xc
	v_mov_b32_dpp v6, v158 row_ror:8 row_mask:0xf bank_mask:0xc
	v_mov_b32_dpp v7, v159 row_ror:8 row_mask:0xf bank_mask:0xc
	s_waitcnt vmcnt(26)
	v_fma_f32 v4, v4, 0.5, v88
	v_fma_f32 v5, v5, 0.5, v89
	v_fma_f32 v6, v6, 0.5, v90
	v_fma_f32 v7, v7, 0.5, v91
	global_store_dwordx4 v148, v[4:7], s[88:89] offset:512
	v_fmac_f32_e32 v217, v4, v4
	v_fmac_f32_e32 v217, v5, v5
	v_fmac_f32_e32 v217, v6, v6
	v_fmac_f32_e32 v217, v7, v7
	s_waitcnt vmcnt(25)
	v_fma_f32 v0, v0, 0.5, v200
	v_fma_f32 v1, v1, 0.5, v201
	v_fma_f32 v2, v2, 0.5, v202
	v_fma_f32 v3, v3, 0.5, v203
	global_store_dwordx4 v149, v[0:3], s[88:89] offset:512
	v_fmac_f32_e32 v212, v0, v0
	v_fmac_f32_e32 v212, v1, v1
	v_fmac_f32_e32 v212, v2, v2
	v_fmac_f32_e32 v212, v3, v3
	s_nop 1
	v_add_f32_dpp v217, v217, v217 row_ror:8 row_mask:0xf bank_mask:0xf
	v_add_f32_dpp v212, v212, v212 row_ror:8 row_mask:0xf bank_mask:0xf
	s_nop 0
	ds_bpermute_b32 v147, v144, v217
	ds_bpermute_b32 v132, v144, v212
	s_waitcnt lgkmcnt(0)
	v_add_f32_e32 v217, v217, v147
	v_add_f32_e32 v212, v212, v132
	s_nop 0
	ds_bpermute_b32 v147, v145, v217
	ds_bpermute_b32 v132, v145, v212
	s_waitcnt lgkmcnt(0)
	v_add_f32_e32 v217, v217, v147
	v_add_f32_e32 v212, v212, v132
	v_cmp_gt_u32_e32 vcc, 8, v213
	s_nop 1
	v_cndmask_b32_e32 v217, v212, v217, vcc
	v_cmp_eq_u32_e32 vcc, 0, v146
	s_and_saveexec_b64 s[98:99], vcc
	global_store_dword v216, v217, s[100:101]
	s_mov_b64 exec, s[98:99]
	s_and_b64 vcc, exec, s[8:9]
	s_mov_b64 s[8:9], -1
	s_cbranch_vccnz .LBB0_1477
	s_andn2_b64 vcc, exec, s[14:15]
	s_cbranch_vccnz .LBB0_1476
	s_barrier
	s_branch .LBB0_1476
